# scan compute loop: one 8-deep chain per dot product (no merge adds), merged LDS waits
# speedup vs baseline: 1.0983x; 1.0010x over previous
.Lscan_chunk:
	s_and_b32 s10, s13, 1
	s_mul_i32 s16, s10, 0xe200
	v_add_u32_e32 v225, s16, v222
	v_add_u32_e32 v224, s16, v223
	v_mov_b32_e32 v134, s16
	v_mad_u32_u24 v135, v136, s10, v137
	s_waitcnt lgkmcnt(0)
	s_barrier
	ds_read_b128 v[20:23], v225 offset:0
	ds_read_b128 v[24:27], v225 offset:16
	ds_read_b128 v[28:31], v225 offset:32768
	ds_read_b128 v[32:35], v225 offset:32784
	ds_read_b64 v[60:61], v224 offset:40960
	ds_read_b128 v[36:39], v225 offset:24576
	ds_read_b128 v[40:43], v225 offset:24592
	ds_read_b64 v[62:63], v134 offset:57344
	ds_read_b128 v[44:47], v225 offset:16384
	ds_read_b128 v[48:51], v225 offset:16400
	ds_read_b128 v[52:55], v225 offset:8192
	ds_read_b128 v[56:59], v225 offset:8208
	s_waitcnt lgkmcnt(8)
	v_pk_mul_f32 v[108:109], v[2:3], v[20:21] op_sel_hi:[1,0]
	v_pk_mul_f32 v[112:113], v[2:3], v[28:29] op_sel_hi:[1,0]
	v_pk_fma_f32 v[108:109], v[4:5], v[20:21], v[108:109] op_sel:[0,1,0]
	v_pk_fma_f32 v[112:113], v[4:5], v[28:29], v[112:113] op_sel:[0,1,0]
	ds_read_b128 v[64:67], v225 offset:256
	v_pk_fma_f32 v[108:109], v[6:7], v[22:23], v[108:109] op_sel_hi:[1,0,1]
	v_pk_fma_f32 v[112:113], v[6:7], v[30:31], v[112:113] op_sel_hi:[1,0,1]
	v_pk_fma_f32 v[108:109], v[8:9], v[22:23], v[108:109] op_sel:[0,1,0]
	v_pk_fma_f32 v[112:113], v[8:9], v[30:31], v[112:113] op_sel:[0,1,0]
	ds_read_b128 v[68:71], v225 offset:272
	v_pk_fma_f32 v[108:109], v[10:11], v[24:25], v[108:109] op_sel_hi:[1,0,1]
	v_pk_fma_f32 v[112:113], v[10:11], v[32:33], v[112:113] op_sel_hi:[1,0,1]
	v_pk_fma_f32 v[108:109], v[12:13], v[24:25], v[108:109] op_sel:[0,1,0]
	v_pk_fma_f32 v[112:113], v[12:13], v[32:33], v[112:113] op_sel:[0,1,0]
	ds_read_b128 v[72:75], v225 offset:33024
	v_pk_fma_f32 v[108:109], v[14:15], v[26:27], v[108:109] op_sel_hi:[1,0,1]
	v_pk_fma_f32 v[112:113], v[14:15], v[34:35], v[112:113] op_sel_hi:[1,0,1]
	v_pk_fma_f32 v[108:109], v[16:17], v[26:27], v[108:109] op_sel:[0,1,0]
	v_pk_fma_f32 v[112:113], v[16:17], v[34:35], v[112:113] op_sel:[0,1,0]
	ds_read_b128 v[76:79], v225 offset:33040
	s_waitcnt lgkmcnt(9)
	v_pk_mul_f32 v[116:117], v[60:61], v[36:37] op_sel_hi:[1,0]
	v_pk_mul_f32 v[118:119], v[60:61], v[36:37] op_sel:[0,1]
	v_pk_mul_f32 v[120:121], v[60:61], v[38:39] op_sel_hi:[1,0]
	v_pk_mul_f32 v[122:123], v[60:61], v[38:39] op_sel:[0,1]
	ds_read_b64 v[104:105], v224 offset:41216
	ds_read_b128 v[80:83], v225 offset:24832
	v_add_f32_dpp v108, v108, v108 quad_perm:[1,0,3,2] row_mask:0xf bank_mask:0xf bound_ctrl:1
	v_add_f32_dpp v109, v109, v109 quad_perm:[1,0,3,2] row_mask:0xf bank_mask:0xf bound_ctrl:1
	v_add_f32_dpp v112, v112, v112 quad_perm:[1,0,3,2] row_mask:0xf bank_mask:0xf bound_ctrl:1
	v_add_f32_dpp v113, v113, v113 quad_perm:[1,0,3,2] row_mask:0xf bank_mask:0xf bound_ctrl:1
	v_pk_mul_f32 v[124:125], v[60:61], v[40:41] op_sel_hi:[1,0]
	v_pk_mul_f32 v[126:127], v[60:61], v[40:41] op_sel:[0,1]
	v_pk_mul_f32 v[128:129], v[60:61], v[42:43] op_sel_hi:[1,0]
	v_pk_mul_f32 v[130:131], v[60:61], v[42:43] op_sel:[0,1]
	ds_read_b128 v[84:87], v225 offset:24848
	ds_read_b64 v[106:107], v134 offset:57352
	v_add_f32_dpp v108, v108, v108 quad_perm:[2,3,0,1] row_mask:0xf bank_mask:0xf bound_ctrl:1
	v_add_f32_dpp v109, v109, v109 quad_perm:[2,3,0,1] row_mask:0xf bank_mask:0xf bound_ctrl:1
	v_add_f32_dpp v112, v112, v112 quad_perm:[2,3,0,1] row_mask:0xf bank_mask:0xf bound_ctrl:1
	v_add_f32_dpp v113, v113, v113 quad_perm:[2,3,0,1] row_mask:0xf bank_mask:0xf bound_ctrl:1
	ds_read_b128 v[88:91], v225 offset:16640
	v_add_f32_dpp v108, v108, v108 row_half_mirror row_mask:0xf bank_mask:0xf bound_ctrl:1
	v_add_f32_dpp v109, v109, v109 row_half_mirror row_mask:0xf bank_mask:0xf bound_ctrl:1
	v_add_f32_dpp v112, v112, v112 row_half_mirror row_mask:0xf bank_mask:0xf bound_ctrl:1
	v_add_f32_dpp v113, v113, v113 row_half_mirror row_mask:0xf bank_mask:0xf bound_ctrl:1
	ds_read_b128 v[92:95], v225 offset:16656
	s_waitcnt lgkmcnt(10)
	v_pk_fma_f32 v[116:117], v[108:109], v[44:45], v[116:117] op_sel_hi:[1,0,1] neg_lo:[1,0,0] neg_hi:[1,0,0]
	v_pk_fma_f32 v[118:119], v[108:109], v[44:45], v[118:119] op_sel:[0,1,0] neg_lo:[1,0,0] neg_hi:[1,0,0]
	v_pk_fma_f32 v[120:121], v[108:109], v[46:47], v[120:121] op_sel_hi:[1,0,1] neg_lo:[1,0,0] neg_hi:[1,0,0]
	v_pk_fma_f32 v[122:123], v[108:109], v[46:47], v[122:123] op_sel:[0,1,0] neg_lo:[1,0,0] neg_hi:[1,0,0]
	v_pk_fma_f32 v[124:125], v[108:109], v[48:49], v[124:125] op_sel_hi:[1,0,1] neg_lo:[1,0,0] neg_hi:[1,0,0]
	v_pk_fma_f32 v[126:127], v[108:109], v[48:49], v[126:127] op_sel:[0,1,0] neg_lo:[1,0,0] neg_hi:[1,0,0]
	v_pk_fma_f32 v[128:129], v[108:109], v[50:51], v[128:129] op_sel_hi:[1,0,1] neg_lo:[1,0,0] neg_hi:[1,0,0]
	v_pk_fma_f32 v[130:131], v[108:109], v[50:51], v[130:131] op_sel:[0,1,0] neg_lo:[1,0,0] neg_hi:[1,0,0]
	ds_read_b128 v[96:99], v225 offset:8448
	v_pk_fma_f32 v[132:133], v[108:109], v[62:63], v[112:113] op_sel_hi:[1,0,1] neg_lo:[1,0,0] neg_hi:[1,0,0]
	ds_read_b128 v[100:103], v225 offset:8464
	v_pk_fma_f32 v[2:3], v[2:3], v[52:53], v[116:117] op_sel_hi:[1,0,1]
	v_pk_fma_f32 v[4:5], v[4:5], v[52:53], v[118:119] op_sel:[0,1,0]
	v_pk_fma_f32 v[6:7], v[6:7], v[54:55], v[120:121] op_sel_hi:[1,0,1]
	v_pk_fma_f32 v[8:9], v[8:9], v[54:55], v[122:123] op_sel:[0,1,0]
	v_pk_fma_f32 v[132:133], v[60:61], v[62:63], v[132:133] op_sel:[0,1,0]
	v_pk_fma_f32 v[10:11], v[10:11], v[56:57], v[124:125] op_sel_hi:[1,0,1]
	v_pk_fma_f32 v[12:13], v[12:13], v[56:57], v[126:127] op_sel:[0,1,0]
	v_pk_fma_f32 v[14:15], v[14:15], v[58:59], v[128:129] op_sel_hi:[1,0,1]
	v_pk_fma_f32 v[16:17], v[16:17], v[58:59], v[130:131] op_sel:[0,1,0]
	ds_write_b64 v135, v[132:133] offset:49152
	s_waitcnt lgkmcnt(9)
	v_pk_mul_f32 v[108:109], v[2:3], v[64:65] op_sel_hi:[1,0]
	v_pk_mul_f32 v[112:113], v[2:3], v[72:73] op_sel_hi:[1,0]
	v_pk_fma_f32 v[108:109], v[4:5], v[64:65], v[108:109] op_sel:[0,1,0]
	v_pk_fma_f32 v[112:113], v[4:5], v[72:73], v[112:113] op_sel:[0,1,0]
	ds_read_b128 v[20:23], v225 offset:512
	v_pk_fma_f32 v[108:109], v[6:7], v[66:67], v[108:109] op_sel_hi:[1,0,1]
	v_pk_fma_f32 v[112:113], v[6:7], v[74:75], v[112:113] op_sel_hi:[1,0,1]
	v_pk_fma_f32 v[108:109], v[8:9], v[66:67], v[108:109] op_sel:[0,1,0]
	v_pk_fma_f32 v[112:113], v[8:9], v[74:75], v[112:113] op_sel:[0,1,0]
	ds_read_b128 v[24:27], v225 offset:528
	v_pk_fma_f32 v[108:109], v[10:11], v[68:69], v[108:109] op_sel_hi:[1,0,1]
	v_pk_fma_f32 v[112:113], v[10:11], v[76:77], v[112:113] op_sel_hi:[1,0,1]
	v_pk_fma_f32 v[108:109], v[12:13], v[68:69], v[108:109] op_sel:[0,1,0]
	v_pk_fma_f32 v[112:113], v[12:13], v[76:77], v[112:113] op_sel:[0,1,0]
	ds_read_b128 v[28:31], v225 offset:33280
	v_pk_fma_f32 v[108:109], v[14:15], v[70:71], v[108:109] op_sel_hi:[1,0,1]
	v_pk_fma_f32 v[112:113], v[14:15], v[78:79], v[112:113] op_sel_hi:[1,0,1]
	v_pk_fma_f32 v[108:109], v[16:17], v[70:71], v[108:109] op_sel:[0,1,0]
	v_pk_fma_f32 v[112:113], v[16:17], v[78:79], v[112:113] op_sel:[0,1,0]
	ds_read_b128 v[32:35], v225 offset:33296
	s_waitcnt lgkmcnt(10)
	v_pk_mul_f32 v[116:117], v[104:105], v[80:81] op_sel_hi:[1,0]
	v_pk_mul_f32 v[118:119], v[104:105], v[80:81] op_sel:[0,1]
	v_pk_mul_f32 v[120:121], v[104:105], v[82:83] op_sel_hi:[1,0]
	v_pk_mul_f32 v[122:123], v[104:105], v[82:83] op_sel:[0,1]
	ds_read_b64 v[60:61], v224 offset:41472
	ds_read_b128 v[36:39], v225 offset:25088
	v_add_f32_dpp v108, v108, v108 quad_perm:[1,0,3,2] row_mask:0xf bank_mask:0xf bound_ctrl:1
	v_add_f32_dpp v109, v109, v109 quad_perm:[1,0,3,2] row_mask:0xf bank_mask:0xf bound_ctrl:1
	v_add_f32_dpp v112, v112, v112 quad_perm:[1,0,3,2] row_mask:0xf bank_mask:0xf bound_ctrl:1
	v_add_f32_dpp v113, v113, v113 quad_perm:[1,0,3,2] row_mask:0xf bank_mask:0xf bound_ctrl:1
	v_pk_mul_f32 v[124:125], v[104:105], v[84:85] op_sel_hi:[1,0]
	v_pk_mul_f32 v[126:127], v[104:105], v[84:85] op_sel:[0,1]
	v_pk_mul_f32 v[128:129], v[104:105], v[86:87] op_sel_hi:[1,0]
	v_pk_mul_f32 v[130:131], v[104:105], v[86:87] op_sel:[0,1]
	ds_read_b128 v[40:43], v225 offset:25104
	ds_read_b64 v[62:63], v134 offset:57360
	v_add_f32_dpp v108, v108, v108 quad_perm:[2,3,0,1] row_mask:0xf bank_mask:0xf bound_ctrl:1
	v_add_f32_dpp v109, v109, v109 quad_perm:[2,3,0,1] row_mask:0xf bank_mask:0xf bound_ctrl:1
	v_add_f32_dpp v112, v112, v112 quad_perm:[2,3,0,1] row_mask:0xf bank_mask:0xf bound_ctrl:1
	v_add_f32_dpp v113, v113, v113 quad_perm:[2,3,0,1] row_mask:0xf bank_mask:0xf bound_ctrl:1
	ds_read_b128 v[44:47], v225 offset:16896
	v_add_f32_dpp v108, v108, v108 row_half_mirror row_mask:0xf bank_mask:0xf bound_ctrl:1
	v_add_f32_dpp v109, v109, v109 row_half_mirror row_mask:0xf bank_mask:0xf bound_ctrl:1
	v_add_f32_dpp v112, v112, v112 row_half_mirror row_mask:0xf bank_mask:0xf bound_ctrl:1
	v_add_f32_dpp v113, v113, v113 row_half_mirror row_mask:0xf bank_mask:0xf bound_ctrl:1
	ds_read_b128 v[48:51], v225 offset:16912
	s_waitcnt lgkmcnt(11)
	v_pk_fma_f32 v[116:117], v[108:109], v[88:89], v[116:117] op_sel_hi:[1,0,1] neg_lo:[1,0,0] neg_hi:[1,0,0]
	v_pk_fma_f32 v[118:119], v[108:109], v[88:89], v[118:119] op_sel:[0,1,0] neg_lo:[1,0,0] neg_hi:[1,0,0]
	v_pk_fma_f32 v[120:121], v[108:109], v[90:91], v[120:121] op_sel_hi:[1,0,1] neg_lo:[1,0,0] neg_hi:[1,0,0]
	v_pk_fma_f32 v[122:123], v[108:109], v[90:91], v[122:123] op_sel:[0,1,0] neg_lo:[1,0,0] neg_hi:[1,0,0]
	v_pk_fma_f32 v[124:125], v[108:109], v[92:93], v[124:125] op_sel_hi:[1,0,1] neg_lo:[1,0,0] neg_hi:[1,0,0]
	v_pk_fma_f32 v[126:127], v[108:109], v[92:93], v[126:127] op_sel:[0,1,0] neg_lo:[1,0,0] neg_hi:[1,0,0]
	v_pk_fma_f32 v[128:129], v[108:109], v[94:95], v[128:129] op_sel_hi:[1,0,1] neg_lo:[1,0,0] neg_hi:[1,0,0]
	v_pk_fma_f32 v[130:131], v[108:109], v[94:95], v[130:131] op_sel:[0,1,0] neg_lo:[1,0,0] neg_hi:[1,0,0]
	ds_read_b128 v[52:55], v225 offset:8704
	v_pk_fma_f32 v[132:133], v[108:109], v[106:107], v[112:113] op_sel_hi:[1,0,1] neg_lo:[1,0,0] neg_hi:[1,0,0]
	ds_read_b128 v[56:59], v225 offset:8720
	v_pk_fma_f32 v[2:3], v[2:3], v[96:97], v[116:117] op_sel_hi:[1,0,1]
	v_pk_fma_f32 v[4:5], v[4:5], v[96:97], v[118:119] op_sel:[0,1,0]
	v_pk_fma_f32 v[6:7], v[6:7], v[98:99], v[120:121] op_sel_hi:[1,0,1]
	v_pk_fma_f32 v[8:9], v[8:9], v[98:99], v[122:123] op_sel:[0,1,0]
	v_pk_fma_f32 v[132:133], v[104:105], v[106:107], v[132:133] op_sel:[0,1,0]
	v_pk_fma_f32 v[10:11], v[10:11], v[100:101], v[124:125] op_sel_hi:[1,0,1]
	v_pk_fma_f32 v[12:13], v[12:13], v[100:101], v[126:127] op_sel:[0,1,0]
	v_pk_fma_f32 v[14:15], v[14:15], v[102:103], v[128:129] op_sel_hi:[1,0,1]
	v_pk_fma_f32 v[16:17], v[16:17], v[102:103], v[130:131] op_sel:[0,1,0]
	ds_write_b64 v135, v[132:133] offset:49408
	s_waitcnt lgkmcnt(9)
	v_pk_mul_f32 v[108:109], v[2:3], v[20:21] op_sel_hi:[1,0]
	v_pk_mul_f32 v[112:113], v[2:3], v[28:29] op_sel_hi:[1,0]
	v_pk_fma_f32 v[108:109], v[4:5], v[20:21], v[108:109] op_sel:[0,1,0]
	v_pk_fma_f32 v[112:113], v[4:5], v[28:29], v[112:113] op_sel:[0,1,0]
	ds_read_b128 v[64:67], v225 offset:768
	v_pk_fma_f32 v[108:109], v[6:7], v[22:23], v[108:109] op_sel_hi:[1,0,1]
	v_pk_fma_f32 v[112:113], v[6:7], v[30:31], v[112:113] op_sel_hi:[1,0,1]
	v_pk_fma_f32 v[108:109], v[8:9], v[22:23], v[108:109] op_sel:[0,1,0]
	v_pk_fma_f32 v[112:113], v[8:9], v[30:31], v[112:113] op_sel:[0,1,0]
	ds_read_b128 v[68:71], v225 offset:784
	v_pk_fma_f32 v[108:109], v[10:11], v[24:25], v[108:109] op_sel_hi:[1,0,1]
	v_pk_fma_f32 v[112:113], v[10:11], v[32:33], v[112:113] op_sel_hi:[1,0,1]
	v_pk_fma_f32 v[108:109], v[12:13], v[24:25], v[108:109] op_sel:[0,1,0]
	v_pk_fma_f32 v[112:113], v[12:13], v[32:33], v[112:113] op_sel:[0,1,0]
	ds_read_b128 v[72:75], v225 offset:33536
	v_pk_fma_f32 v[108:109], v[14:15], v[26:27], v[108:109] op_sel_hi:[1,0,1]
	v_pk_fma_f32 v[112:113], v[14:15], v[34:35], v[112:113] op_sel_hi:[1,0,1]
	v_pk_fma_f32 v[108:109], v[16:17], v[26:27], v[108:109] op_sel:[0,1,0]
	v_pk_fma_f32 v[112:113], v[16:17], v[34:35], v[112:113] op_sel:[0,1,0]
	ds_read_b128 v[76:79], v225 offset:33552
	s_waitcnt lgkmcnt(10)
	v_pk_mul_f32 v[116:117], v[60:61], v[36:37] op_sel_hi:[1,0]
	v_pk_mul_f32 v[118:119], v[60:61], v[36:37] op_sel:[0,1]
	v_pk_mul_f32 v[120:121], v[60:61], v[38:39] op_sel_hi:[1,0]
	v_pk_mul_f32 v[122:123], v[60:61], v[38:39] op_sel:[0,1]
	ds_read_b64 v[104:105], v224 offset:41728
	ds_read_b128 v[80:83], v225 offset:25344
	v_add_f32_dpp v108, v108, v108 quad_perm:[1,0,3,2] row_mask:0xf bank_mask:0xf bound_ctrl:1
	v_add_f32_dpp v109, v109, v109 quad_perm:[1,0,3,2] row_mask:0xf bank_mask:0xf bound_ctrl:1
	v_add_f32_dpp v112, v112, v112 quad_perm:[1,0,3,2] row_mask:0xf bank_mask:0xf bound_ctrl:1
	v_add_f32_dpp v113, v113, v113 quad_perm:[1,0,3,2] row_mask:0xf bank_mask:0xf bound_ctrl:1
	v_pk_mul_f32 v[124:125], v[60:61], v[40:41] op_sel_hi:[1,0]
	v_pk_mul_f32 v[126:127], v[60:61], v[40:41] op_sel:[0,1]
	v_pk_mul_f32 v[128:129], v[60:61], v[42:43] op_sel_hi:[1,0]
	v_pk_mul_f32 v[130:131], v[60:61], v[42:43] op_sel:[0,1]
	ds_read_b128 v[84:87], v225 offset:25360
	ds_read_b64 v[106:107], v134 offset:57368
	v_add_f32_dpp v108, v108, v108 quad_perm:[2,3,0,1] row_mask:0xf bank_mask:0xf bound_ctrl:1
	v_add_f32_dpp v109, v109, v109 quad_perm:[2,3,0,1] row_mask:0xf bank_mask:0xf bound_ctrl:1
	v_add_f32_dpp v112, v112, v112 quad_perm:[2,3,0,1] row_mask:0xf bank_mask:0xf bound_ctrl:1
	v_add_f32_dpp v113, v113, v113 quad_perm:[2,3,0,1] row_mask:0xf bank_mask:0xf bound_ctrl:1
	ds_read_b128 v[88:91], v225 offset:17152
	v_add_f32_dpp v108, v108, v108 row_half_mirror row_mask:0xf bank_mask:0xf bound_ctrl:1
	v_add_f32_dpp v109, v109, v109 row_half_mirror row_mask:0xf bank_mask:0xf bound_ctrl:1
	v_add_f32_dpp v112, v112, v112 row_half_mirror row_mask:0xf bank_mask:0xf bound_ctrl:1
	v_add_f32_dpp v113, v113, v113 row_half_mirror row_mask:0xf bank_mask:0xf bound_ctrl:1
	ds_read_b128 v[92:95], v225 offset:17168
	s_waitcnt lgkmcnt(11)
	v_pk_fma_f32 v[116:117], v[108:109], v[44:45], v[116:117] op_sel_hi:[1,0,1] neg_lo:[1,0,0] neg_hi:[1,0,0]
	v_pk_fma_f32 v[118:119], v[108:109], v[44:45], v[118:119] op_sel:[0,1,0] neg_lo:[1,0,0] neg_hi:[1,0,0]
	v_pk_fma_f32 v[120:121], v[108:109], v[46:47], v[120:121] op_sel_hi:[1,0,1] neg_lo:[1,0,0] neg_hi:[1,0,0]
	v_pk_fma_f32 v[122:123], v[108:109], v[46:47], v[122:123] op_sel:[0,1,0] neg_lo:[1,0,0] neg_hi:[1,0,0]
	v_pk_fma_f32 v[124:125], v[108:109], v[48:49], v[124:125] op_sel_hi:[1,0,1] neg_lo:[1,0,0] neg_hi:[1,0,0]
	v_pk_fma_f32 v[126:127], v[108:109], v[48:49], v[126:127] op_sel:[0,1,0] neg_lo:[1,0,0] neg_hi:[1,0,0]
	v_pk_fma_f32 v[128:129], v[108:109], v[50:51], v[128:129] op_sel_hi:[1,0,1] neg_lo:[1,0,0] neg_hi:[1,0,0]
	v_pk_fma_f32 v[130:131], v[108:109], v[50:51], v[130:131] op_sel:[0,1,0] neg_lo:[1,0,0] neg_hi:[1,0,0]
	ds_read_b128 v[96:99], v225 offset:8960
	v_pk_fma_f32 v[132:133], v[108:109], v[62:63], v[112:113] op_sel_hi:[1,0,1] neg_lo:[1,0,0] neg_hi:[1,0,0]
	ds_read_b128 v[100:103], v225 offset:8976
	v_pk_fma_f32 v[2:3], v[2:3], v[52:53], v[116:117] op_sel_hi:[1,0,1]
	v_pk_fma_f32 v[4:5], v[4:5], v[52:53], v[118:119] op_sel:[0,1,0]
	v_pk_fma_f32 v[6:7], v[6:7], v[54:55], v[120:121] op_sel_hi:[1,0,1]
	v_pk_fma_f32 v[8:9], v[8:9], v[54:55], v[122:123] op_sel:[0,1,0]
	v_pk_fma_f32 v[132:133], v[60:61], v[62:63], v[132:133] op_sel:[0,1,0]
	v_pk_fma_f32 v[10:11], v[10:11], v[56:57], v[124:125] op_sel_hi:[1,0,1]
	v_pk_fma_f32 v[12:13], v[12:13], v[56:57], v[126:127] op_sel:[0,1,0]
	v_pk_fma_f32 v[14:15], v[14:15], v[58:59], v[128:129] op_sel_hi:[1,0,1]
	v_pk_fma_f32 v[16:17], v[16:17], v[58:59], v[130:131] op_sel:[0,1,0]
	ds_write_b64 v135, v[132:133] offset:49664
	s_waitcnt lgkmcnt(9)
	v_pk_mul_f32 v[108:109], v[2:3], v[64:65] op_sel_hi:[1,0]
	v_pk_mul_f32 v[112:113], v[2:3], v[72:73] op_sel_hi:[1,0]
	v_pk_fma_f32 v[108:109], v[4:5], v[64:65], v[108:109] op_sel:[0,1,0]
	v_pk_fma_f32 v[112:113], v[4:5], v[72:73], v[112:113] op_sel:[0,1,0]
	ds_read_b128 v[20:23], v225 offset:1024
	v_pk_fma_f32 v[108:109], v[6:7], v[66:67], v[108:109] op_sel_hi:[1,0,1]
	v_pk_fma_f32 v[112:113], v[6:7], v[74:75], v[112:113] op_sel_hi:[1,0,1]
	v_pk_fma_f32 v[108:109], v[8:9], v[66:67], v[108:109] op_sel:[0,1,0]
	v_pk_fma_f32 v[112:113], v[8:9], v[74:75], v[112:113] op_sel:[0,1,0]
	ds_read_b128 v[24:27], v225 offset:1040
	v_pk_fma_f32 v[108:109], v[10:11], v[68:69], v[108:109] op_sel_hi:[1,0,1]
	v_pk_fma_f32 v[112:113], v[10:11], v[76:77], v[112:113] op_sel_hi:[1,0,1]
	v_pk_fma_f32 v[108:109], v[12:13], v[68:69], v[108:109] op_sel:[0,1,0]
	v_pk_fma_f32 v[112:113], v[12:13], v[76:77], v[112:113] op_sel:[0,1,0]
	ds_read_b128 v[28:31], v225 offset:33792
	v_pk_fma_f32 v[108:109], v[14:15], v[70:71], v[108:109] op_sel_hi:[1,0,1]
	v_pk_fma_f32 v[112:113], v[14:15], v[78:79], v[112:113] op_sel_hi:[1,0,1]
	v_pk_fma_f32 v[108:109], v[16:17], v[70:71], v[108:109] op_sel:[0,1,0]
	v_pk_fma_f32 v[112:113], v[16:17], v[78:79], v[112:113] op_sel:[0,1,0]
	ds_read_b128 v[32:35], v225 offset:33808
	s_waitcnt lgkmcnt(10)
	v_pk_mul_f32 v[116:117], v[104:105], v[80:81] op_sel_hi:[1,0]
	v_pk_mul_f32 v[118:119], v[104:105], v[80:81] op_sel:[0,1]
	v_pk_mul_f32 v[120:121], v[104:105], v[82:83] op_sel_hi:[1,0]
	v_pk_mul_f32 v[122:123], v[104:105], v[82:83] op_sel:[0,1]
	ds_read_b64 v[60:61], v224 offset:41984
	ds_read_b128 v[36:39], v225 offset:25600
	v_add_f32_dpp v108, v108, v108 quad_perm:[1,0,3,2] row_mask:0xf bank_mask:0xf bound_ctrl:1
	v_add_f32_dpp v109, v109, v109 quad_perm:[1,0,3,2] row_mask:0xf bank_mask:0xf bound_ctrl:1
	v_add_f32_dpp v112, v112, v112 quad_perm:[1,0,3,2] row_mask:0xf bank_mask:0xf bound_ctrl:1
	v_add_f32_dpp v113, v113, v113 quad_perm:[1,0,3,2] row_mask:0xf bank_mask:0xf bound_ctrl:1
	v_pk_mul_f32 v[124:125], v[104:105], v[84:85] op_sel_hi:[1,0]
	v_pk_mul_f32 v[126:127], v[104:105], v[84:85] op_sel:[0,1]
	v_pk_mul_f32 v[128:129], v[104:105], v[86:87] op_sel_hi:[1,0]
	v_pk_mul_f32 v[130:131], v[104:105], v[86:87] op_sel:[0,1]
	ds_read_b128 v[40:43], v225 offset:25616
	ds_read_b64 v[62:63], v134 offset:57376
	v_add_f32_dpp v108, v108, v108 quad_perm:[2,3,0,1] row_mask:0xf bank_mask:0xf bound_ctrl:1
	v_add_f32_dpp v109, v109, v109 quad_perm:[2,3,0,1] row_mask:0xf bank_mask:0xf bound_ctrl:1
	v_add_f32_dpp v112, v112, v112 quad_perm:[2,3,0,1] row_mask:0xf bank_mask:0xf bound_ctrl:1
	v_add_f32_dpp v113, v113, v113 quad_perm:[2,3,0,1] row_mask:0xf bank_mask:0xf bound_ctrl:1
	ds_read_b128 v[44:47], v225 offset:17408
	v_add_f32_dpp v108, v108, v108 row_half_mirror row_mask:0xf bank_mask:0xf bound_ctrl:1
	v_add_f32_dpp v109, v109, v109 row_half_mirror row_mask:0xf bank_mask:0xf bound_ctrl:1
	v_add_f32_dpp v112, v112, v112 row_half_mirror row_mask:0xf bank_mask:0xf bound_ctrl:1
	v_add_f32_dpp v113, v113, v113 row_half_mirror row_mask:0xf bank_mask:0xf bound_ctrl:1
	ds_read_b128 v[48:51], v225 offset:17424
	s_waitcnt lgkmcnt(11)
	v_pk_fma_f32 v[116:117], v[108:109], v[88:89], v[116:117] op_sel_hi:[1,0,1] neg_lo:[1,0,0] neg_hi:[1,0,0]
	v_pk_fma_f32 v[118:119], v[108:109], v[88:89], v[118:119] op_sel:[0,1,0] neg_lo:[1,0,0] neg_hi:[1,0,0]
	v_pk_fma_f32 v[120:121], v[108:109], v[90:91], v[120:121] op_sel_hi:[1,0,1] neg_lo:[1,0,0] neg_hi:[1,0,0]
	v_pk_fma_f32 v[122:123], v[108:109], v[90:91], v[122:123] op_sel:[0,1,0] neg_lo:[1,0,0] neg_hi:[1,0,0]
	v_pk_fma_f32 v[124:125], v[108:109], v[92:93], v[124:125] op_sel_hi:[1,0,1] neg_lo:[1,0,0] neg_hi:[1,0,0]
	v_pk_fma_f32 v[126:127], v[108:109], v[92:93], v[126:127] op_sel:[0,1,0] neg_lo:[1,0,0] neg_hi:[1,0,0]
	v_pk_fma_f32 v[128:129], v[108:109], v[94:95], v[128:129] op_sel_hi:[1,0,1] neg_lo:[1,0,0] neg_hi:[1,0,0]
	v_pk_fma_f32 v[130:131], v[108:109], v[94:95], v[130:131] op_sel:[0,1,0] neg_lo:[1,0,0] neg_hi:[1,0,0]
	ds_read_b128 v[52:55], v225 offset:9216
	v_pk_fma_f32 v[132:133], v[108:109], v[106:107], v[112:113] op_sel_hi:[1,0,1] neg_lo:[1,0,0] neg_hi:[1,0,0]
	ds_read_b128 v[56:59], v225 offset:9232
	v_pk_fma_f32 v[2:3], v[2:3], v[96:97], v[116:117] op_sel_hi:[1,0,1]
	v_pk_fma_f32 v[4:5], v[4:5], v[96:97], v[118:119] op_sel:[0,1,0]
	v_pk_fma_f32 v[6:7], v[6:7], v[98:99], v[120:121] op_sel_hi:[1,0,1]
	v_pk_fma_f32 v[8:9], v[8:9], v[98:99], v[122:123] op_sel:[0,1,0]
	v_pk_fma_f32 v[132:133], v[104:105], v[106:107], v[132:133] op_sel:[0,1,0]
	v_pk_fma_f32 v[10:11], v[10:11], v[100:101], v[124:125] op_sel_hi:[1,0,1]
	v_pk_fma_f32 v[12:13], v[12:13], v[100:101], v[126:127] op_sel:[0,1,0]
	v_pk_fma_f32 v[14:15], v[14:15], v[102:103], v[128:129] op_sel_hi:[1,0,1]
	v_pk_fma_f32 v[16:17], v[16:17], v[102:103], v[130:131] op_sel:[0,1,0]
	ds_write_b64 v135, v[132:133] offset:49920
	s_waitcnt lgkmcnt(9)
	v_pk_mul_f32 v[108:109], v[2:3], v[20:21] op_sel_hi:[1,0]
	v_pk_mul_f32 v[112:113], v[2:3], v[28:29] op_sel_hi:[1,0]
	v_pk_fma_f32 v[108:109], v[4:5], v[20:21], v[108:109] op_sel:[0,1,0]
	v_pk_fma_f32 v[112:113], v[4:5], v[28:29], v[112:113] op_sel:[0,1,0]
	ds_read_b128 v[64:67], v225 offset:1280
	v_pk_fma_f32 v[108:109], v[6:7], v[22:23], v[108:109] op_sel_hi:[1,0,1]
	v_pk_fma_f32 v[112:113], v[6:7], v[30:31], v[112:113] op_sel_hi:[1,0,1]
	v_pk_fma_f32 v[108:109], v[8:9], v[22:23], v[108:109] op_sel:[0,1,0]
	v_pk_fma_f32 v[112:113], v[8:9], v[30:31], v[112:113] op_sel:[0,1,0]
	ds_read_b128 v[68:71], v225 offset:1296
	v_pk_fma_f32 v[108:109], v[10:11], v[24:25], v[108:109] op_sel_hi:[1,0,1]
	v_pk_fma_f32 v[112:113], v[10:11], v[32:33], v[112:113] op_sel_hi:[1,0,1]
	v_pk_fma_f32 v[108:109], v[12:13], v[24:25], v[108:109] op_sel:[0,1,0]
	v_pk_fma_f32 v[112:113], v[12:13], v[32:33], v[112:113] op_sel:[0,1,0]
	ds_read_b128 v[72:75], v225 offset:34048
	v_pk_fma_f32 v[108:109], v[14:15], v[26:27], v[108:109] op_sel_hi:[1,0,1]
	v_pk_fma_f32 v[112:113], v[14:15], v[34:35], v[112:113] op_sel_hi:[1,0,1]
	v_pk_fma_f32 v[108:109], v[16:17], v[26:27], v[108:109] op_sel:[0,1,0]
	v_pk_fma_f32 v[112:113], v[16:17], v[34:35], v[112:113] op_sel:[0,1,0]
	ds_read_b128 v[76:79], v225 offset:34064
	s_waitcnt lgkmcnt(10)
	v_pk_mul_f32 v[116:117], v[60:61], v[36:37] op_sel_hi:[1,0]
	v_pk_mul_f32 v[118:119], v[60:61], v[36:37] op_sel:[0,1]
	v_pk_mul_f32 v[120:121], v[60:61], v[38:39] op_sel_hi:[1,0]
	v_pk_mul_f32 v[122:123], v[60:61], v[38:39] op_sel:[0,1]
	ds_read_b64 v[104:105], v224 offset:42240
	ds_read_b128 v[80:83], v225 offset:25856
	v_add_f32_dpp v108, v108, v108 quad_perm:[1,0,3,2] row_mask:0xf bank_mask:0xf bound_ctrl:1
	v_add_f32_dpp v109, v109, v109 quad_perm:[1,0,3,2] row_mask:0xf bank_mask:0xf bound_ctrl:1
	v_add_f32_dpp v112, v112, v112 quad_perm:[1,0,3,2] row_mask:0xf bank_mask:0xf bound_ctrl:1
	v_add_f32_dpp v113, v113, v113 quad_perm:[1,0,3,2] row_mask:0xf bank_mask:0xf bound_ctrl:1
	v_pk_mul_f32 v[124:125], v[60:61], v[40:41] op_sel_hi:[1,0]
	v_pk_mul_f32 v[126:127], v[60:61], v[40:41] op_sel:[0,1]
	v_pk_mul_f32 v[128:129], v[60:61], v[42:43] op_sel_hi:[1,0]
	v_pk_mul_f32 v[130:131], v[60:61], v[42:43] op_sel:[0,1]
	ds_read_b128 v[84:87], v225 offset:25872
	ds_read_b64 v[106:107], v134 offset:57384
	v_add_f32_dpp v108, v108, v108 quad_perm:[2,3,0,1] row_mask:0xf bank_mask:0xf bound_ctrl:1
	v_add_f32_dpp v109, v109, v109 quad_perm:[2,3,0,1] row_mask:0xf bank_mask:0xf bound_ctrl:1
	v_add_f32_dpp v112, v112, v112 quad_perm:[2,3,0,1] row_mask:0xf bank_mask:0xf bound_ctrl:1
	v_add_f32_dpp v113, v113, v113 quad_perm:[2,3,0,1] row_mask:0xf bank_mask:0xf bound_ctrl:1
	ds_read_b128 v[88:91], v225 offset:17664
	v_add_f32_dpp v108, v108, v108 row_half_mirror row_mask:0xf bank_mask:0xf bound_ctrl:1
	v_add_f32_dpp v109, v109, v109 row_half_mirror row_mask:0xf bank_mask:0xf bound_ctrl:1
	v_add_f32_dpp v112, v112, v112 row_half_mirror row_mask:0xf bank_mask:0xf bound_ctrl:1
	v_add_f32_dpp v113, v113, v113 row_half_mirror row_mask:0xf bank_mask:0xf bound_ctrl:1
	ds_read_b128 v[92:95], v225 offset:17680
	s_waitcnt lgkmcnt(11)
	v_pk_fma_f32 v[116:117], v[108:109], v[44:45], v[116:117] op_sel_hi:[1,0,1] neg_lo:[1,0,0] neg_hi:[1,0,0]
	v_pk_fma_f32 v[118:119], v[108:109], v[44:45], v[118:119] op_sel:[0,1,0] neg_lo:[1,0,0] neg_hi:[1,0,0]
	v_pk_fma_f32 v[120:121], v[108:109], v[46:47], v[120:121] op_sel_hi:[1,0,1] neg_lo:[1,0,0] neg_hi:[1,0,0]
	v_pk_fma_f32 v[122:123], v[108:109], v[46:47], v[122:123] op_sel:[0,1,0] neg_lo:[1,0,0] neg_hi:[1,0,0]
	v_pk_fma_f32 v[124:125], v[108:109], v[48:49], v[124:125] op_sel_hi:[1,0,1] neg_lo:[1,0,0] neg_hi:[1,0,0]
	v_pk_fma_f32 v[126:127], v[108:109], v[48:49], v[126:127] op_sel:[0,1,0] neg_lo:[1,0,0] neg_hi:[1,0,0]
	v_pk_fma_f32 v[128:129], v[108:109], v[50:51], v[128:129] op_sel_hi:[1,0,1] neg_lo:[1,0,0] neg_hi:[1,0,0]
	v_pk_fma_f32 v[130:131], v[108:109], v[50:51], v[130:131] op_sel:[0,1,0] neg_lo:[1,0,0] neg_hi:[1,0,0]
	ds_read_b128 v[96:99], v225 offset:9472
	v_pk_fma_f32 v[132:133], v[108:109], v[62:63], v[112:113] op_sel_hi:[1,0,1] neg_lo:[1,0,0] neg_hi:[1,0,0]
	ds_read_b128 v[100:103], v225 offset:9488
	v_pk_fma_f32 v[2:3], v[2:3], v[52:53], v[116:117] op_sel_hi:[1,0,1]
	v_pk_fma_f32 v[4:5], v[4:5], v[52:53], v[118:119] op_sel:[0,1,0]
	v_pk_fma_f32 v[6:7], v[6:7], v[54:55], v[120:121] op_sel_hi:[1,0,1]
	v_pk_fma_f32 v[8:9], v[8:9], v[54:55], v[122:123] op_sel:[0,1,0]
	v_pk_fma_f32 v[132:133], v[60:61], v[62:63], v[132:133] op_sel:[0,1,0]
	v_pk_fma_f32 v[10:11], v[10:11], v[56:57], v[124:125] op_sel_hi:[1,0,1]
	v_pk_fma_f32 v[12:13], v[12:13], v[56:57], v[126:127] op_sel:[0,1,0]
	v_pk_fma_f32 v[14:15], v[14:15], v[58:59], v[128:129] op_sel_hi:[1,0,1]
	v_pk_fma_f32 v[16:17], v[16:17], v[58:59], v[130:131] op_sel:[0,1,0]
	ds_write_b64 v135, v[132:133] offset:50176
	s_waitcnt lgkmcnt(9)
	v_pk_mul_f32 v[108:109], v[2:3], v[64:65] op_sel_hi:[1,0]
	v_pk_mul_f32 v[112:113], v[2:3], v[72:73] op_sel_hi:[1,0]
	v_pk_fma_f32 v[108:109], v[4:5], v[64:65], v[108:109] op_sel:[0,1,0]
	v_pk_fma_f32 v[112:113], v[4:5], v[72:73], v[112:113] op_sel:[0,1,0]
	ds_read_b128 v[20:23], v225 offset:1536
	v_pk_fma_f32 v[108:109], v[6:7], v[66:67], v[108:109] op_sel_hi:[1,0,1]
	v_pk_fma_f32 v[112:113], v[6:7], v[74:75], v[112:113] op_sel_hi:[1,0,1]
	v_pk_fma_f32 v[108:109], v[8:9], v[66:67], v[108:109] op_sel:[0,1,0]
	v_pk_fma_f32 v[112:113], v[8:9], v[74:75], v[112:113] op_sel:[0,1,0]
	ds_read_b128 v[24:27], v225 offset:1552
	v_pk_fma_f32 v[108:109], v[10:11], v[68:69], v[108:109] op_sel_hi:[1,0,1]
	v_pk_fma_f32 v[112:113], v[10:11], v[76:77], v[112:113] op_sel_hi:[1,0,1]
	v_pk_fma_f32 v[108:109], v[12:13], v[68:69], v[108:109] op_sel:[0,1,0]
	v_pk_fma_f32 v[112:113], v[12:13], v[76:77], v[112:113] op_sel:[0,1,0]
	ds_read_b128 v[28:31], v225 offset:34304
	v_pk_fma_f32 v[108:109], v[14:15], v[70:71], v[108:109] op_sel_hi:[1,0,1]
	v_pk_fma_f32 v[112:113], v[14:15], v[78:79], v[112:113] op_sel_hi:[1,0,1]
	v_pk_fma_f32 v[108:109], v[16:17], v[70:71], v[108:109] op_sel:[0,1,0]
	v_pk_fma_f32 v[112:113], v[16:17], v[78:79], v[112:113] op_sel:[0,1,0]
	ds_read_b128 v[32:35], v225 offset:34320
	s_waitcnt lgkmcnt(10)
	v_pk_mul_f32 v[116:117], v[104:105], v[80:81] op_sel_hi:[1,0]
	v_pk_mul_f32 v[118:119], v[104:105], v[80:81] op_sel:[0,1]
	v_pk_mul_f32 v[120:121], v[104:105], v[82:83] op_sel_hi:[1,0]
	v_pk_mul_f32 v[122:123], v[104:105], v[82:83] op_sel:[0,1]
	ds_read_b64 v[60:61], v224 offset:42496
	ds_read_b128 v[36:39], v225 offset:26112
	v_add_f32_dpp v108, v108, v108 quad_perm:[1,0,3,2] row_mask:0xf bank_mask:0xf bound_ctrl:1
	v_add_f32_dpp v109, v109, v109 quad_perm:[1,0,3,2] row_mask:0xf bank_mask:0xf bound_ctrl:1
	v_add_f32_dpp v112, v112, v112 quad_perm:[1,0,3,2] row_mask:0xf bank_mask:0xf bound_ctrl:1
	v_add_f32_dpp v113, v113, v113 quad_perm:[1,0,3,2] row_mask:0xf bank_mask:0xf bound_ctrl:1
	v_pk_mul_f32 v[124:125], v[104:105], v[84:85] op_sel_hi:[1,0]
	v_pk_mul_f32 v[126:127], v[104:105], v[84:85] op_sel:[0,1]
	v_pk_mul_f32 v[128:129], v[104:105], v[86:87] op_sel_hi:[1,0]
	v_pk_mul_f32 v[130:131], v[104:105], v[86:87] op_sel:[0,1]
	ds_read_b128 v[40:43], v225 offset:26128
	ds_read_b64 v[62:63], v134 offset:57392
	v_add_f32_dpp v108, v108, v108 quad_perm:[2,3,0,1] row_mask:0xf bank_mask:0xf bound_ctrl:1
	v_add_f32_dpp v109, v109, v109 quad_perm:[2,3,0,1] row_mask:0xf bank_mask:0xf bound_ctrl:1
	v_add_f32_dpp v112, v112, v112 quad_perm:[2,3,0,1] row_mask:0xf bank_mask:0xf bound_ctrl:1
	v_add_f32_dpp v113, v113, v113 quad_perm:[2,3,0,1] row_mask:0xf bank_mask:0xf bound_ctrl:1
	ds_read_b128 v[44:47], v225 offset:17920
	v_add_f32_dpp v108, v108, v108 row_half_mirror row_mask:0xf bank_mask:0xf bound_ctrl:1
	v_add_f32_dpp v109, v109, v109 row_half_mirror row_mask:0xf bank_mask:0xf bound_ctrl:1
	v_add_f32_dpp v112, v112, v112 row_half_mirror row_mask:0xf bank_mask:0xf bound_ctrl:1
	v_add_f32_dpp v113, v113, v113 row_half_mirror row_mask:0xf bank_mask:0xf bound_ctrl:1
	ds_read_b128 v[48:51], v225 offset:17936
	s_waitcnt lgkmcnt(11)
	v_pk_fma_f32 v[116:117], v[108:109], v[88:89], v[116:117] op_sel_hi:[1,0,1] neg_lo:[1,0,0] neg_hi:[1,0,0]
	v_pk_fma_f32 v[118:119], v[108:109], v[88:89], v[118:119] op_sel:[0,1,0] neg_lo:[1,0,0] neg_hi:[1,0,0]
	v_pk_fma_f32 v[120:121], v[108:109], v[90:91], v[120:121] op_sel_hi:[1,0,1] neg_lo:[1,0,0] neg_hi:[1,0,0]
	v_pk_fma_f32 v[122:123], v[108:109], v[90:91], v[122:123] op_sel:[0,1,0] neg_lo:[1,0,0] neg_hi:[1,0,0]
	v_pk_fma_f32 v[124:125], v[108:109], v[92:93], v[124:125] op_sel_hi:[1,0,1] neg_lo:[1,0,0] neg_hi:[1,0,0]
	v_pk_fma_f32 v[126:127], v[108:109], v[92:93], v[126:127] op_sel:[0,1,0] neg_lo:[1,0,0] neg_hi:[1,0,0]
	v_pk_fma_f32 v[128:129], v[108:109], v[94:95], v[128:129] op_sel_hi:[1,0,1] neg_lo:[1,0,0] neg_hi:[1,0,0]
	v_pk_fma_f32 v[130:131], v[108:109], v[94:95], v[130:131] op_sel:[0,1,0] neg_lo:[1,0,0] neg_hi:[1,0,0]
	ds_read_b128 v[52:55], v225 offset:9728
	v_pk_fma_f32 v[132:133], v[108:109], v[106:107], v[112:113] op_sel_hi:[1,0,1] neg_lo:[1,0,0] neg_hi:[1,0,0]
	ds_read_b128 v[56:59], v225 offset:9744
	v_pk_fma_f32 v[2:3], v[2:3], v[96:97], v[116:117] op_sel_hi:[1,0,1]
	v_pk_fma_f32 v[4:5], v[4:5], v[96:97], v[118:119] op_sel:[0,1,0]
	v_pk_fma_f32 v[6:7], v[6:7], v[98:99], v[120:121] op_sel_hi:[1,0,1]
	v_pk_fma_f32 v[8:9], v[8:9], v[98:99], v[122:123] op_sel:[0,1,0]
	v_pk_fma_f32 v[132:133], v[104:105], v[106:107], v[132:133] op_sel:[0,1,0]
	v_pk_fma_f32 v[10:11], v[10:11], v[100:101], v[124:125] op_sel_hi:[1,0,1]
	v_pk_fma_f32 v[12:13], v[12:13], v[100:101], v[126:127] op_sel:[0,1,0]
	v_pk_fma_f32 v[14:15], v[14:15], v[102:103], v[128:129] op_sel_hi:[1,0,1]
	v_pk_fma_f32 v[16:17], v[16:17], v[102:103], v[130:131] op_sel:[0,1,0]
	ds_write_b64 v135, v[132:133] offset:50432
	s_waitcnt lgkmcnt(9)
	v_pk_mul_f32 v[108:109], v[2:3], v[20:21] op_sel_hi:[1,0]
	v_pk_mul_f32 v[112:113], v[2:3], v[28:29] op_sel_hi:[1,0]
	v_pk_fma_f32 v[108:109], v[4:5], v[20:21], v[108:109] op_sel:[0,1,0]
	v_pk_fma_f32 v[112:113], v[4:5], v[28:29], v[112:113] op_sel:[0,1,0]
	ds_read_b128 v[64:67], v225 offset:1792
	v_pk_fma_f32 v[108:109], v[6:7], v[22:23], v[108:109] op_sel_hi:[1,0,1]
	v_pk_fma_f32 v[112:113], v[6:7], v[30:31], v[112:113] op_sel_hi:[1,0,1]
	v_pk_fma_f32 v[108:109], v[8:9], v[22:23], v[108:109] op_sel:[0,1,0]
	v_pk_fma_f32 v[112:113], v[8:9], v[30:31], v[112:113] op_sel:[0,1,0]
	ds_read_b128 v[68:71], v225 offset:1808
	v_pk_fma_f32 v[108:109], v[10:11], v[24:25], v[108:109] op_sel_hi:[1,0,1]
	v_pk_fma_f32 v[112:113], v[10:11], v[32:33], v[112:113] op_sel_hi:[1,0,1]
	v_pk_fma_f32 v[108:109], v[12:13], v[24:25], v[108:109] op_sel:[0,1,0]
	v_pk_fma_f32 v[112:113], v[12:13], v[32:33], v[112:113] op_sel:[0,1,0]
	ds_read_b128 v[72:75], v225 offset:34560
	v_pk_fma_f32 v[108:109], v[14:15], v[26:27], v[108:109] op_sel_hi:[1,0,1]
	v_pk_fma_f32 v[112:113], v[14:15], v[34:35], v[112:113] op_sel_hi:[1,0,1]
	v_pk_fma_f32 v[108:109], v[16:17], v[26:27], v[108:109] op_sel:[0,1,0]
	v_pk_fma_f32 v[112:113], v[16:17], v[34:35], v[112:113] op_sel:[0,1,0]
	ds_read_b128 v[76:79], v225 offset:34576
	s_waitcnt lgkmcnt(10)
	v_pk_mul_f32 v[116:117], v[60:61], v[36:37] op_sel_hi:[1,0]
	v_pk_mul_f32 v[118:119], v[60:61], v[36:37] op_sel:[0,1]
	v_pk_mul_f32 v[120:121], v[60:61], v[38:39] op_sel_hi:[1,0]
	v_pk_mul_f32 v[122:123], v[60:61], v[38:39] op_sel:[0,1]
	ds_read_b64 v[104:105], v224 offset:42752
	ds_read_b128 v[80:83], v225 offset:26368
	v_add_f32_dpp v108, v108, v108 quad_perm:[1,0,3,2] row_mask:0xf bank_mask:0xf bound_ctrl:1
	v_add_f32_dpp v109, v109, v109 quad_perm:[1,0,3,2] row_mask:0xf bank_mask:0xf bound_ctrl:1
	v_add_f32_dpp v112, v112, v112 quad_perm:[1,0,3,2] row_mask:0xf bank_mask:0xf bound_ctrl:1
	v_add_f32_dpp v113, v113, v113 quad_perm:[1,0,3,2] row_mask:0xf bank_mask:0xf bound_ctrl:1
	v_pk_mul_f32 v[124:125], v[60:61], v[40:41] op_sel_hi:[1,0]
	v_pk_mul_f32 v[126:127], v[60:61], v[40:41] op_sel:[0,1]
	v_pk_mul_f32 v[128:129], v[60:61], v[42:43] op_sel_hi:[1,0]
	v_pk_mul_f32 v[130:131], v[60:61], v[42:43] op_sel:[0,1]
	ds_read_b128 v[84:87], v225 offset:26384
	ds_read_b64 v[106:107], v134 offset:57400
	v_add_f32_dpp v108, v108, v108 quad_perm:[2,3,0,1] row_mask:0xf bank_mask:0xf bound_ctrl:1
	v_add_f32_dpp v109, v109, v109 quad_perm:[2,3,0,1] row_mask:0xf bank_mask:0xf bound_ctrl:1
	v_add_f32_dpp v112, v112, v112 quad_perm:[2,3,0,1] row_mask:0xf bank_mask:0xf bound_ctrl:1
	v_add_f32_dpp v113, v113, v113 quad_perm:[2,3,0,1] row_mask:0xf bank_mask:0xf bound_ctrl:1
	ds_read_b128 v[88:91], v225 offset:18176
	v_add_f32_dpp v108, v108, v108 row_half_mirror row_mask:0xf bank_mask:0xf bound_ctrl:1
	v_add_f32_dpp v109, v109, v109 row_half_mirror row_mask:0xf bank_mask:0xf bound_ctrl:1
	v_add_f32_dpp v112, v112, v112 row_half_mirror row_mask:0xf bank_mask:0xf bound_ctrl:1
	v_add_f32_dpp v113, v113, v113 row_half_mirror row_mask:0xf bank_mask:0xf bound_ctrl:1
	ds_read_b128 v[92:95], v225 offset:18192
	s_waitcnt lgkmcnt(11)
	v_pk_fma_f32 v[116:117], v[108:109], v[44:45], v[116:117] op_sel_hi:[1,0,1] neg_lo:[1,0,0] neg_hi:[1,0,0]
	v_pk_fma_f32 v[118:119], v[108:109], v[44:45], v[118:119] op_sel:[0,1,0] neg_lo:[1,0,0] neg_hi:[1,0,0]
	v_pk_fma_f32 v[120:121], v[108:109], v[46:47], v[120:121] op_sel_hi:[1,0,1] neg_lo:[1,0,0] neg_hi:[1,0,0]
	v_pk_fma_f32 v[122:123], v[108:109], v[46:47], v[122:123] op_sel:[0,1,0] neg_lo:[1,0,0] neg_hi:[1,0,0]
	v_pk_fma_f32 v[124:125], v[108:109], v[48:49], v[124:125] op_sel_hi:[1,0,1] neg_lo:[1,0,0] neg_hi:[1,0,0]
	v_pk_fma_f32 v[126:127], v[108:109], v[48:49], v[126:127] op_sel:[0,1,0] neg_lo:[1,0,0] neg_hi:[1,0,0]
	v_pk_fma_f32 v[128:129], v[108:109], v[50:51], v[128:129] op_sel_hi:[1,0,1] neg_lo:[1,0,0] neg_hi:[1,0,0]
	v_pk_fma_f32 v[130:131], v[108:109], v[50:51], v[130:131] op_sel:[0,1,0] neg_lo:[1,0,0] neg_hi:[1,0,0]
	ds_read_b128 v[96:99], v225 offset:9984
	v_pk_fma_f32 v[132:133], v[108:109], v[62:63], v[112:113] op_sel_hi:[1,0,1] neg_lo:[1,0,0] neg_hi:[1,0,0]
	ds_read_b128 v[100:103], v225 offset:10000
	v_pk_fma_f32 v[2:3], v[2:3], v[52:53], v[116:117] op_sel_hi:[1,0,1]
	v_pk_fma_f32 v[4:5], v[4:5], v[52:53], v[118:119] op_sel:[0,1,0]
	v_pk_fma_f32 v[6:7], v[6:7], v[54:55], v[120:121] op_sel_hi:[1,0,1]
	v_pk_fma_f32 v[8:9], v[8:9], v[54:55], v[122:123] op_sel:[0,1,0]
	v_pk_fma_f32 v[132:133], v[60:61], v[62:63], v[132:133] op_sel:[0,1,0]
	v_pk_fma_f32 v[10:11], v[10:11], v[56:57], v[124:125] op_sel_hi:[1,0,1]
	v_pk_fma_f32 v[12:13], v[12:13], v[56:57], v[126:127] op_sel:[0,1,0]
	v_pk_fma_f32 v[14:15], v[14:15], v[58:59], v[128:129] op_sel_hi:[1,0,1]
	v_pk_fma_f32 v[16:17], v[16:17], v[58:59], v[130:131] op_sel:[0,1,0]
	ds_write_b64 v135, v[132:133] offset:50688
	s_waitcnt lgkmcnt(9)
	v_pk_mul_f32 v[108:109], v[2:3], v[64:65] op_sel_hi:[1,0]
	v_pk_mul_f32 v[112:113], v[2:3], v[72:73] op_sel_hi:[1,0]
	v_pk_fma_f32 v[108:109], v[4:5], v[64:65], v[108:109] op_sel:[0,1,0]
	v_pk_fma_f32 v[112:113], v[4:5], v[72:73], v[112:113] op_sel:[0,1,0]
	ds_read_b128 v[20:23], v225 offset:2048
	v_pk_fma_f32 v[108:109], v[6:7], v[66:67], v[108:109] op_sel_hi:[1,0,1]
	v_pk_fma_f32 v[112:113], v[6:7], v[74:75], v[112:113] op_sel_hi:[1,0,1]
	v_pk_fma_f32 v[108:109], v[8:9], v[66:67], v[108:109] op_sel:[0,1,0]
	v_pk_fma_f32 v[112:113], v[8:9], v[74:75], v[112:113] op_sel:[0,1,0]
	ds_read_b128 v[24:27], v225 offset:2064
	v_pk_fma_f32 v[108:109], v[10:11], v[68:69], v[108:109] op_sel_hi:[1,0,1]
	v_pk_fma_f32 v[112:113], v[10:11], v[76:77], v[112:113] op_sel_hi:[1,0,1]
	v_pk_fma_f32 v[108:109], v[12:13], v[68:69], v[108:109] op_sel:[0,1,0]
	v_pk_fma_f32 v[112:113], v[12:13], v[76:77], v[112:113] op_sel:[0,1,0]
	ds_read_b128 v[28:31], v225 offset:34816
	v_pk_fma_f32 v[108:109], v[14:15], v[70:71], v[108:109] op_sel_hi:[1,0,1]
	v_pk_fma_f32 v[112:113], v[14:15], v[78:79], v[112:113] op_sel_hi:[1,0,1]
	v_pk_fma_f32 v[108:109], v[16:17], v[70:71], v[108:109] op_sel:[0,1,0]
	v_pk_fma_f32 v[112:113], v[16:17], v[78:79], v[112:113] op_sel:[0,1,0]
	ds_read_b128 v[32:35], v225 offset:34832
	s_waitcnt lgkmcnt(10)
	v_pk_mul_f32 v[116:117], v[104:105], v[80:81] op_sel_hi:[1,0]
	v_pk_mul_f32 v[118:119], v[104:105], v[80:81] op_sel:[0,1]
	v_pk_mul_f32 v[120:121], v[104:105], v[82:83] op_sel_hi:[1,0]
	v_pk_mul_f32 v[122:123], v[104:105], v[82:83] op_sel:[0,1]
	ds_read_b64 v[60:61], v224 offset:43008
	ds_read_b128 v[36:39], v225 offset:26624
	v_add_f32_dpp v108, v108, v108 quad_perm:[1,0,3,2] row_mask:0xf bank_mask:0xf bound_ctrl:1
	v_add_f32_dpp v109, v109, v109 quad_perm:[1,0,3,2] row_mask:0xf bank_mask:0xf bound_ctrl:1
	v_add_f32_dpp v112, v112, v112 quad_perm:[1,0,3,2] row_mask:0xf bank_mask:0xf bound_ctrl:1
	v_add_f32_dpp v113, v113, v113 quad_perm:[1,0,3,2] row_mask:0xf bank_mask:0xf bound_ctrl:1
	v_pk_mul_f32 v[124:125], v[104:105], v[84:85] op_sel_hi:[1,0]
	v_pk_mul_f32 v[126:127], v[104:105], v[84:85] op_sel:[0,1]
	v_pk_mul_f32 v[128:129], v[104:105], v[86:87] op_sel_hi:[1,0]
	v_pk_mul_f32 v[130:131], v[104:105], v[86:87] op_sel:[0,1]
	ds_read_b128 v[40:43], v225 offset:26640
	ds_read_b64 v[62:63], v134 offset:57408
	v_add_f32_dpp v108, v108, v108 quad_perm:[2,3,0,1] row_mask:0xf bank_mask:0xf bound_ctrl:1
	v_add_f32_dpp v109, v109, v109 quad_perm:[2,3,0,1] row_mask:0xf bank_mask:0xf bound_ctrl:1
	v_add_f32_dpp v112, v112, v112 quad_perm:[2,3,0,1] row_mask:0xf bank_mask:0xf bound_ctrl:1
	v_add_f32_dpp v113, v113, v113 quad_perm:[2,3,0,1] row_mask:0xf bank_mask:0xf bound_ctrl:1
	ds_read_b128 v[44:47], v225 offset:18432
	v_add_f32_dpp v108, v108, v108 row_half_mirror row_mask:0xf bank_mask:0xf bound_ctrl:1
	v_add_f32_dpp v109, v109, v109 row_half_mirror row_mask:0xf bank_mask:0xf bound_ctrl:1
	v_add_f32_dpp v112, v112, v112 row_half_mirror row_mask:0xf bank_mask:0xf bound_ctrl:1
	v_add_f32_dpp v113, v113, v113 row_half_mirror row_mask:0xf bank_mask:0xf bound_ctrl:1
	ds_read_b128 v[48:51], v225 offset:18448
	s_waitcnt lgkmcnt(11)
	v_pk_fma_f32 v[116:117], v[108:109], v[88:89], v[116:117] op_sel_hi:[1,0,1] neg_lo:[1,0,0] neg_hi:[1,0,0]
	v_pk_fma_f32 v[118:119], v[108:109], v[88:89], v[118:119] op_sel:[0,1,0] neg_lo:[1,0,0] neg_hi:[1,0,0]
	v_pk_fma_f32 v[120:121], v[108:109], v[90:91], v[120:121] op_sel_hi:[1,0,1] neg_lo:[1,0,0] neg_hi:[1,0,0]
	v_pk_fma_f32 v[122:123], v[108:109], v[90:91], v[122:123] op_sel:[0,1,0] neg_lo:[1,0,0] neg_hi:[1,0,0]
	v_pk_fma_f32 v[124:125], v[108:109], v[92:93], v[124:125] op_sel_hi:[1,0,1] neg_lo:[1,0,0] neg_hi:[1,0,0]
	v_pk_fma_f32 v[126:127], v[108:109], v[92:93], v[126:127] op_sel:[0,1,0] neg_lo:[1,0,0] neg_hi:[1,0,0]
	v_pk_fma_f32 v[128:129], v[108:109], v[94:95], v[128:129] op_sel_hi:[1,0,1] neg_lo:[1,0,0] neg_hi:[1,0,0]
	v_pk_fma_f32 v[130:131], v[108:109], v[94:95], v[130:131] op_sel:[0,1,0] neg_lo:[1,0,0] neg_hi:[1,0,0]
	ds_read_b128 v[52:55], v225 offset:10240
	v_pk_fma_f32 v[132:133], v[108:109], v[106:107], v[112:113] op_sel_hi:[1,0,1] neg_lo:[1,0,0] neg_hi:[1,0,0]
	ds_read_b128 v[56:59], v225 offset:10256
	v_pk_fma_f32 v[2:3], v[2:3], v[96:97], v[116:117] op_sel_hi:[1,0,1]
	v_pk_fma_f32 v[4:5], v[4:5], v[96:97], v[118:119] op_sel:[0,1,0]
	v_pk_fma_f32 v[6:7], v[6:7], v[98:99], v[120:121] op_sel_hi:[1,0,1]
	v_pk_fma_f32 v[8:9], v[8:9], v[98:99], v[122:123] op_sel:[0,1,0]
	v_pk_fma_f32 v[132:133], v[104:105], v[106:107], v[132:133] op_sel:[0,1,0]
	v_pk_fma_f32 v[10:11], v[10:11], v[100:101], v[124:125] op_sel_hi:[1,0,1]
	v_pk_fma_f32 v[12:13], v[12:13], v[100:101], v[126:127] op_sel:[0,1,0]
	v_pk_fma_f32 v[14:15], v[14:15], v[102:103], v[128:129] op_sel_hi:[1,0,1]
	v_pk_fma_f32 v[16:17], v[16:17], v[102:103], v[130:131] op_sel:[0,1,0]
	ds_write_b64 v135, v[132:133] offset:50944
	s_waitcnt lgkmcnt(9)
	v_pk_mul_f32 v[108:109], v[2:3], v[20:21] op_sel_hi:[1,0]
	v_pk_mul_f32 v[112:113], v[2:3], v[28:29] op_sel_hi:[1,0]
	v_pk_fma_f32 v[108:109], v[4:5], v[20:21], v[108:109] op_sel:[0,1,0]
	v_pk_fma_f32 v[112:113], v[4:5], v[28:29], v[112:113] op_sel:[0,1,0]
	ds_read_b128 v[64:67], v225 offset:2304
	v_pk_fma_f32 v[108:109], v[6:7], v[22:23], v[108:109] op_sel_hi:[1,0,1]
	v_pk_fma_f32 v[112:113], v[6:7], v[30:31], v[112:113] op_sel_hi:[1,0,1]
	v_pk_fma_f32 v[108:109], v[8:9], v[22:23], v[108:109] op_sel:[0,1,0]
	v_pk_fma_f32 v[112:113], v[8:9], v[30:31], v[112:113] op_sel:[0,1,0]
	ds_read_b128 v[68:71], v225 offset:2320
	v_pk_fma_f32 v[108:109], v[10:11], v[24:25], v[108:109] op_sel_hi:[1,0,1]
	v_pk_fma_f32 v[112:113], v[10:11], v[32:33], v[112:113] op_sel_hi:[1,0,1]
	v_pk_fma_f32 v[108:109], v[12:13], v[24:25], v[108:109] op_sel:[0,1,0]
	v_pk_fma_f32 v[112:113], v[12:13], v[32:33], v[112:113] op_sel:[0,1,0]
	ds_read_b128 v[72:75], v225 offset:35072
	v_pk_fma_f32 v[108:109], v[14:15], v[26:27], v[108:109] op_sel_hi:[1,0,1]
	v_pk_fma_f32 v[112:113], v[14:15], v[34:35], v[112:113] op_sel_hi:[1,0,1]
	v_pk_fma_f32 v[108:109], v[16:17], v[26:27], v[108:109] op_sel:[0,1,0]
	v_pk_fma_f32 v[112:113], v[16:17], v[34:35], v[112:113] op_sel:[0,1,0]
	ds_read_b128 v[76:79], v225 offset:35088
	s_waitcnt lgkmcnt(10)
	v_pk_mul_f32 v[116:117], v[60:61], v[36:37] op_sel_hi:[1,0]
	v_pk_mul_f32 v[118:119], v[60:61], v[36:37] op_sel:[0,1]
	v_pk_mul_f32 v[120:121], v[60:61], v[38:39] op_sel_hi:[1,0]
	v_pk_mul_f32 v[122:123], v[60:61], v[38:39] op_sel:[0,1]
	ds_read_b64 v[104:105], v224 offset:43264
	ds_read_b128 v[80:83], v225 offset:26880
	v_add_f32_dpp v108, v108, v108 quad_perm:[1,0,3,2] row_mask:0xf bank_mask:0xf bound_ctrl:1
	v_add_f32_dpp v109, v109, v109 quad_perm:[1,0,3,2] row_mask:0xf bank_mask:0xf bound_ctrl:1
	v_add_f32_dpp v112, v112, v112 quad_perm:[1,0,3,2] row_mask:0xf bank_mask:0xf bound_ctrl:1
	v_add_f32_dpp v113, v113, v113 quad_perm:[1,0,3,2] row_mask:0xf bank_mask:0xf bound_ctrl:1
	v_pk_mul_f32 v[124:125], v[60:61], v[40:41] op_sel_hi:[1,0]
	v_pk_mul_f32 v[126:127], v[60:61], v[40:41] op_sel:[0,1]
	v_pk_mul_f32 v[128:129], v[60:61], v[42:43] op_sel_hi:[1,0]
	v_pk_mul_f32 v[130:131], v[60:61], v[42:43] op_sel:[0,1]
	ds_read_b128 v[84:87], v225 offset:26896
	ds_read_b64 v[106:107], v134 offset:57416
	v_add_f32_dpp v108, v108, v108 quad_perm:[2,3,0,1] row_mask:0xf bank_mask:0xf bound_ctrl:1
	v_add_f32_dpp v109, v109, v109 quad_perm:[2,3,0,1] row_mask:0xf bank_mask:0xf bound_ctrl:1
	v_add_f32_dpp v112, v112, v112 quad_perm:[2,3,0,1] row_mask:0xf bank_mask:0xf bound_ctrl:1
	v_add_f32_dpp v113, v113, v113 quad_perm:[2,3,0,1] row_mask:0xf bank_mask:0xf bound_ctrl:1
	ds_read_b128 v[88:91], v225 offset:18688
	v_add_f32_dpp v108, v108, v108 row_half_mirror row_mask:0xf bank_mask:0xf bound_ctrl:1
	v_add_f32_dpp v109, v109, v109 row_half_mirror row_mask:0xf bank_mask:0xf bound_ctrl:1
	v_add_f32_dpp v112, v112, v112 row_half_mirror row_mask:0xf bank_mask:0xf bound_ctrl:1
	v_add_f32_dpp v113, v113, v113 row_half_mirror row_mask:0xf bank_mask:0xf bound_ctrl:1
	ds_read_b128 v[92:95], v225 offset:18704
	s_waitcnt lgkmcnt(11)
	v_pk_fma_f32 v[116:117], v[108:109], v[44:45], v[116:117] op_sel_hi:[1,0,1] neg_lo:[1,0,0] neg_hi:[1,0,0]
	v_pk_fma_f32 v[118:119], v[108:109], v[44:45], v[118:119] op_sel:[0,1,0] neg_lo:[1,0,0] neg_hi:[1,0,0]
	v_pk_fma_f32 v[120:121], v[108:109], v[46:47], v[120:121] op_sel_hi:[1,0,1] neg_lo:[1,0,0] neg_hi:[1,0,0]
	v_pk_fma_f32 v[122:123], v[108:109], v[46:47], v[122:123] op_sel:[0,1,0] neg_lo:[1,0,0] neg_hi:[1,0,0]
	v_pk_fma_f32 v[124:125], v[108:109], v[48:49], v[124:125] op_sel_hi:[1,0,1] neg_lo:[1,0,0] neg_hi:[1,0,0]
	v_pk_fma_f32 v[126:127], v[108:109], v[48:49], v[126:127] op_sel:[0,1,0] neg_lo:[1,0,0] neg_hi:[1,0,0]
	v_pk_fma_f32 v[128:129], v[108:109], v[50:51], v[128:129] op_sel_hi:[1,0,1] neg_lo:[1,0,0] neg_hi:[1,0,0]
	v_pk_fma_f32 v[130:131], v[108:109], v[50:51], v[130:131] op_sel:[0,1,0] neg_lo:[1,0,0] neg_hi:[1,0,0]
	ds_read_b128 v[96:99], v225 offset:10496
	v_pk_fma_f32 v[132:133], v[108:109], v[62:63], v[112:113] op_sel_hi:[1,0,1] neg_lo:[1,0,0] neg_hi:[1,0,0]
	ds_read_b128 v[100:103], v225 offset:10512
	v_pk_fma_f32 v[2:3], v[2:3], v[52:53], v[116:117] op_sel_hi:[1,0,1]
	v_pk_fma_f32 v[4:5], v[4:5], v[52:53], v[118:119] op_sel:[0,1,0]
	v_pk_fma_f32 v[6:7], v[6:7], v[54:55], v[120:121] op_sel_hi:[1,0,1]
	v_pk_fma_f32 v[8:9], v[8:9], v[54:55], v[122:123] op_sel:[0,1,0]
	v_pk_fma_f32 v[132:133], v[60:61], v[62:63], v[132:133] op_sel:[0,1,0]
	v_pk_fma_f32 v[10:11], v[10:11], v[56:57], v[124:125] op_sel_hi:[1,0,1]
	v_pk_fma_f32 v[12:13], v[12:13], v[56:57], v[126:127] op_sel:[0,1,0]
	v_pk_fma_f32 v[14:15], v[14:15], v[58:59], v[128:129] op_sel_hi:[1,0,1]
	v_pk_fma_f32 v[16:17], v[16:17], v[58:59], v[130:131] op_sel:[0,1,0]
	ds_write_b64 v135, v[132:133] offset:51200
	s_waitcnt lgkmcnt(9)
	v_pk_mul_f32 v[108:109], v[2:3], v[64:65] op_sel_hi:[1,0]
	v_pk_mul_f32 v[112:113], v[2:3], v[72:73] op_sel_hi:[1,0]
	v_pk_fma_f32 v[108:109], v[4:5], v[64:65], v[108:109] op_sel:[0,1,0]
	v_pk_fma_f32 v[112:113], v[4:5], v[72:73], v[112:113] op_sel:[0,1,0]
	ds_read_b128 v[20:23], v225 offset:2560
	v_pk_fma_f32 v[108:109], v[6:7], v[66:67], v[108:109] op_sel_hi:[1,0,1]
	v_pk_fma_f32 v[112:113], v[6:7], v[74:75], v[112:113] op_sel_hi:[1,0,1]
	v_pk_fma_f32 v[108:109], v[8:9], v[66:67], v[108:109] op_sel:[0,1,0]
	v_pk_fma_f32 v[112:113], v[8:9], v[74:75], v[112:113] op_sel:[0,1,0]
	ds_read_b128 v[24:27], v225 offset:2576
	v_pk_fma_f32 v[108:109], v[10:11], v[68:69], v[108:109] op_sel_hi:[1,0,1]
	v_pk_fma_f32 v[112:113], v[10:11], v[76:77], v[112:113] op_sel_hi:[1,0,1]
	v_pk_fma_f32 v[108:109], v[12:13], v[68:69], v[108:109] op_sel:[0,1,0]
	v_pk_fma_f32 v[112:113], v[12:13], v[76:77], v[112:113] op_sel:[0,1,0]
	ds_read_b128 v[28:31], v225 offset:35328
	v_pk_fma_f32 v[108:109], v[14:15], v[70:71], v[108:109] op_sel_hi:[1,0,1]
	v_pk_fma_f32 v[112:113], v[14:15], v[78:79], v[112:113] op_sel_hi:[1,0,1]
	v_pk_fma_f32 v[108:109], v[16:17], v[70:71], v[108:109] op_sel:[0,1,0]
	v_pk_fma_f32 v[112:113], v[16:17], v[78:79], v[112:113] op_sel:[0,1,0]
	ds_read_b128 v[32:35], v225 offset:35344
	s_waitcnt lgkmcnt(10)
	v_pk_mul_f32 v[116:117], v[104:105], v[80:81] op_sel_hi:[1,0]
	v_pk_mul_f32 v[118:119], v[104:105], v[80:81] op_sel:[0,1]
	v_pk_mul_f32 v[120:121], v[104:105], v[82:83] op_sel_hi:[1,0]
	v_pk_mul_f32 v[122:123], v[104:105], v[82:83] op_sel:[0,1]
	ds_read_b64 v[60:61], v224 offset:43520
	ds_read_b128 v[36:39], v225 offset:27136
	v_add_f32_dpp v108, v108, v108 quad_perm:[1,0,3,2] row_mask:0xf bank_mask:0xf bound_ctrl:1
	v_add_f32_dpp v109, v109, v109 quad_perm:[1,0,3,2] row_mask:0xf bank_mask:0xf bound_ctrl:1
	v_add_f32_dpp v112, v112, v112 quad_perm:[1,0,3,2] row_mask:0xf bank_mask:0xf bound_ctrl:1
	v_add_f32_dpp v113, v113, v113 quad_perm:[1,0,3,2] row_mask:0xf bank_mask:0xf bound_ctrl:1
	v_pk_mul_f32 v[124:125], v[104:105], v[84:85] op_sel_hi:[1,0]
	v_pk_mul_f32 v[126:127], v[104:105], v[84:85] op_sel:[0,1]
	v_pk_mul_f32 v[128:129], v[104:105], v[86:87] op_sel_hi:[1,0]
	v_pk_mul_f32 v[130:131], v[104:105], v[86:87] op_sel:[0,1]
	ds_read_b128 v[40:43], v225 offset:27152
	ds_read_b64 v[62:63], v134 offset:57424
	v_add_f32_dpp v108, v108, v108 quad_perm:[2,3,0,1] row_mask:0xf bank_mask:0xf bound_ctrl:1
	v_add_f32_dpp v109, v109, v109 quad_perm:[2,3,0,1] row_mask:0xf bank_mask:0xf bound_ctrl:1
	v_add_f32_dpp v112, v112, v112 quad_perm:[2,3,0,1] row_mask:0xf bank_mask:0xf bound_ctrl:1
	v_add_f32_dpp v113, v113, v113 quad_perm:[2,3,0,1] row_mask:0xf bank_mask:0xf bound_ctrl:1
	ds_read_b128 v[44:47], v225 offset:18944
	v_add_f32_dpp v108, v108, v108 row_half_mirror row_mask:0xf bank_mask:0xf bound_ctrl:1
	v_add_f32_dpp v109, v109, v109 row_half_mirror row_mask:0xf bank_mask:0xf bound_ctrl:1
	v_add_f32_dpp v112, v112, v112 row_half_mirror row_mask:0xf bank_mask:0xf bound_ctrl:1
	v_add_f32_dpp v113, v113, v113 row_half_mirror row_mask:0xf bank_mask:0xf bound_ctrl:1
	ds_read_b128 v[48:51], v225 offset:18960
	s_waitcnt lgkmcnt(11)
	v_pk_fma_f32 v[116:117], v[108:109], v[88:89], v[116:117] op_sel_hi:[1,0,1] neg_lo:[1,0,0] neg_hi:[1,0,0]
	v_pk_fma_f32 v[118:119], v[108:109], v[88:89], v[118:119] op_sel:[0,1,0] neg_lo:[1,0,0] neg_hi:[1,0,0]
	v_pk_fma_f32 v[120:121], v[108:109], v[90:91], v[120:121] op_sel_hi:[1,0,1] neg_lo:[1,0,0] neg_hi:[1,0,0]
	v_pk_fma_f32 v[122:123], v[108:109], v[90:91], v[122:123] op_sel:[0,1,0] neg_lo:[1,0,0] neg_hi:[1,0,0]
	v_pk_fma_f32 v[124:125], v[108:109], v[92:93], v[124:125] op_sel_hi:[1,0,1] neg_lo:[1,0,0] neg_hi:[1,0,0]
	v_pk_fma_f32 v[126:127], v[108:109], v[92:93], v[126:127] op_sel:[0,1,0] neg_lo:[1,0,0] neg_hi:[1,0,0]
	v_pk_fma_f32 v[128:129], v[108:109], v[94:95], v[128:129] op_sel_hi:[1,0,1] neg_lo:[1,0,0] neg_hi:[1,0,0]
	v_pk_fma_f32 v[130:131], v[108:109], v[94:95], v[130:131] op_sel:[0,1,0] neg_lo:[1,0,0] neg_hi:[1,0,0]
	ds_read_b128 v[52:55], v225 offset:10752
	v_pk_fma_f32 v[132:133], v[108:109], v[106:107], v[112:113] op_sel_hi:[1,0,1] neg_lo:[1,0,0] neg_hi:[1,0,0]
	ds_read_b128 v[56:59], v225 offset:10768
	v_pk_fma_f32 v[2:3], v[2:3], v[96:97], v[116:117] op_sel_hi:[1,0,1]
	v_pk_fma_f32 v[4:5], v[4:5], v[96:97], v[118:119] op_sel:[0,1,0]
	v_pk_fma_f32 v[6:7], v[6:7], v[98:99], v[120:121] op_sel_hi:[1,0,1]
	v_pk_fma_f32 v[8:9], v[8:9], v[98:99], v[122:123] op_sel:[0,1,0]
	v_pk_fma_f32 v[132:133], v[104:105], v[106:107], v[132:133] op_sel:[0,1,0]
	v_pk_fma_f32 v[10:11], v[10:11], v[100:101], v[124:125] op_sel_hi:[1,0,1]
	v_pk_fma_f32 v[12:13], v[12:13], v[100:101], v[126:127] op_sel:[0,1,0]
	v_pk_fma_f32 v[14:15], v[14:15], v[102:103], v[128:129] op_sel_hi:[1,0,1]
	v_pk_fma_f32 v[16:17], v[16:17], v[102:103], v[130:131] op_sel:[0,1,0]
	ds_write_b64 v135, v[132:133] offset:51456
	s_waitcnt lgkmcnt(9)
	v_pk_mul_f32 v[108:109], v[2:3], v[20:21] op_sel_hi:[1,0]
	v_pk_mul_f32 v[112:113], v[2:3], v[28:29] op_sel_hi:[1,0]
	v_pk_fma_f32 v[108:109], v[4:5], v[20:21], v[108:109] op_sel:[0,1,0]
	v_pk_fma_f32 v[112:113], v[4:5], v[28:29], v[112:113] op_sel:[0,1,0]
	ds_read_b128 v[64:67], v225 offset:2816
	v_pk_fma_f32 v[108:109], v[6:7], v[22:23], v[108:109] op_sel_hi:[1,0,1]
	v_pk_fma_f32 v[112:113], v[6:7], v[30:31], v[112:113] op_sel_hi:[1,0,1]
	v_pk_fma_f32 v[108:109], v[8:9], v[22:23], v[108:109] op_sel:[0,1,0]
	v_pk_fma_f32 v[112:113], v[8:9], v[30:31], v[112:113] op_sel:[0,1,0]
	ds_read_b128 v[68:71], v225 offset:2832
	v_pk_fma_f32 v[108:109], v[10:11], v[24:25], v[108:109] op_sel_hi:[1,0,1]
	v_pk_fma_f32 v[112:113], v[10:11], v[32:33], v[112:113] op_sel_hi:[1,0,1]
	v_pk_fma_f32 v[108:109], v[12:13], v[24:25], v[108:109] op_sel:[0,1,0]
	v_pk_fma_f32 v[112:113], v[12:13], v[32:33], v[112:113] op_sel:[0,1,0]
	ds_read_b128 v[72:75], v225 offset:35584
	v_pk_fma_f32 v[108:109], v[14:15], v[26:27], v[108:109] op_sel_hi:[1,0,1]
	v_pk_fma_f32 v[112:113], v[14:15], v[34:35], v[112:113] op_sel_hi:[1,0,1]
	v_pk_fma_f32 v[108:109], v[16:17], v[26:27], v[108:109] op_sel:[0,1,0]
	v_pk_fma_f32 v[112:113], v[16:17], v[34:35], v[112:113] op_sel:[0,1,0]
	ds_read_b128 v[76:79], v225 offset:35600
	s_waitcnt lgkmcnt(10)
	v_pk_mul_f32 v[116:117], v[60:61], v[36:37] op_sel_hi:[1,0]
	v_pk_mul_f32 v[118:119], v[60:61], v[36:37] op_sel:[0,1]
	v_pk_mul_f32 v[120:121], v[60:61], v[38:39] op_sel_hi:[1,0]
	v_pk_mul_f32 v[122:123], v[60:61], v[38:39] op_sel:[0,1]
	ds_read_b64 v[104:105], v224 offset:43776
	ds_read_b128 v[80:83], v225 offset:27392
	v_add_f32_dpp v108, v108, v108 quad_perm:[1,0,3,2] row_mask:0xf bank_mask:0xf bound_ctrl:1
	v_add_f32_dpp v109, v109, v109 quad_perm:[1,0,3,2] row_mask:0xf bank_mask:0xf bound_ctrl:1
	v_add_f32_dpp v112, v112, v112 quad_perm:[1,0,3,2] row_mask:0xf bank_mask:0xf bound_ctrl:1
	v_add_f32_dpp v113, v113, v113 quad_perm:[1,0,3,2] row_mask:0xf bank_mask:0xf bound_ctrl:1
	v_pk_mul_f32 v[124:125], v[60:61], v[40:41] op_sel_hi:[1,0]
	v_pk_mul_f32 v[126:127], v[60:61], v[40:41] op_sel:[0,1]
	v_pk_mul_f32 v[128:129], v[60:61], v[42:43] op_sel_hi:[1,0]
	v_pk_mul_f32 v[130:131], v[60:61], v[42:43] op_sel:[0,1]
	ds_read_b128 v[84:87], v225 offset:27408
	ds_read_b64 v[106:107], v134 offset:57432
	v_add_f32_dpp v108, v108, v108 quad_perm:[2,3,0,1] row_mask:0xf bank_mask:0xf bound_ctrl:1
	v_add_f32_dpp v109, v109, v109 quad_perm:[2,3,0,1] row_mask:0xf bank_mask:0xf bound_ctrl:1
	v_add_f32_dpp v112, v112, v112 quad_perm:[2,3,0,1] row_mask:0xf bank_mask:0xf bound_ctrl:1
	v_add_f32_dpp v113, v113, v113 quad_perm:[2,3,0,1] row_mask:0xf bank_mask:0xf bound_ctrl:1
	ds_read_b128 v[88:91], v225 offset:19200
	v_add_f32_dpp v108, v108, v108 row_half_mirror row_mask:0xf bank_mask:0xf bound_ctrl:1
	v_add_f32_dpp v109, v109, v109 row_half_mirror row_mask:0xf bank_mask:0xf bound_ctrl:1
	v_add_f32_dpp v112, v112, v112 row_half_mirror row_mask:0xf bank_mask:0xf bound_ctrl:1
	v_add_f32_dpp v113, v113, v113 row_half_mirror row_mask:0xf bank_mask:0xf bound_ctrl:1
	ds_read_b128 v[92:95], v225 offset:19216
	s_waitcnt lgkmcnt(11)
	v_pk_fma_f32 v[116:117], v[108:109], v[44:45], v[116:117] op_sel_hi:[1,0,1] neg_lo:[1,0,0] neg_hi:[1,0,0]
	v_pk_fma_f32 v[118:119], v[108:109], v[44:45], v[118:119] op_sel:[0,1,0] neg_lo:[1,0,0] neg_hi:[1,0,0]
	v_pk_fma_f32 v[120:121], v[108:109], v[46:47], v[120:121] op_sel_hi:[1,0,1] neg_lo:[1,0,0] neg_hi:[1,0,0]
	v_pk_fma_f32 v[122:123], v[108:109], v[46:47], v[122:123] op_sel:[0,1,0] neg_lo:[1,0,0] neg_hi:[1,0,0]
	v_pk_fma_f32 v[124:125], v[108:109], v[48:49], v[124:125] op_sel_hi:[1,0,1] neg_lo:[1,0,0] neg_hi:[1,0,0]
	v_pk_fma_f32 v[126:127], v[108:109], v[48:49], v[126:127] op_sel:[0,1,0] neg_lo:[1,0,0] neg_hi:[1,0,0]
	v_pk_fma_f32 v[128:129], v[108:109], v[50:51], v[128:129] op_sel_hi:[1,0,1] neg_lo:[1,0,0] neg_hi:[1,0,0]
	v_pk_fma_f32 v[130:131], v[108:109], v[50:51], v[130:131] op_sel:[0,1,0] neg_lo:[1,0,0] neg_hi:[1,0,0]
	ds_read_b128 v[96:99], v225 offset:11008
	v_pk_fma_f32 v[132:133], v[108:109], v[62:63], v[112:113] op_sel_hi:[1,0,1] neg_lo:[1,0,0] neg_hi:[1,0,0]
	ds_read_b128 v[100:103], v225 offset:11024
	v_pk_fma_f32 v[2:3], v[2:3], v[52:53], v[116:117] op_sel_hi:[1,0,1]
	v_pk_fma_f32 v[4:5], v[4:5], v[52:53], v[118:119] op_sel:[0,1,0]
	v_pk_fma_f32 v[6:7], v[6:7], v[54:55], v[120:121] op_sel_hi:[1,0,1]
	v_pk_fma_f32 v[8:9], v[8:9], v[54:55], v[122:123] op_sel:[0,1,0]
	v_pk_fma_f32 v[132:133], v[60:61], v[62:63], v[132:133] op_sel:[0,1,0]
	v_pk_fma_f32 v[10:11], v[10:11], v[56:57], v[124:125] op_sel_hi:[1,0,1]
	v_pk_fma_f32 v[12:13], v[12:13], v[56:57], v[126:127] op_sel:[0,1,0]
	v_pk_fma_f32 v[14:15], v[14:15], v[58:59], v[128:129] op_sel_hi:[1,0,1]
	v_pk_fma_f32 v[16:17], v[16:17], v[58:59], v[130:131] op_sel:[0,1,0]
	ds_write_b64 v135, v[132:133] offset:51712
	s_waitcnt lgkmcnt(9)
	v_pk_mul_f32 v[108:109], v[2:3], v[64:65] op_sel_hi:[1,0]
	v_pk_mul_f32 v[112:113], v[2:3], v[72:73] op_sel_hi:[1,0]
	v_pk_fma_f32 v[108:109], v[4:5], v[64:65], v[108:109] op_sel:[0,1,0]
	v_pk_fma_f32 v[112:113], v[4:5], v[72:73], v[112:113] op_sel:[0,1,0]
	ds_read_b128 v[20:23], v225 offset:3072
	v_pk_fma_f32 v[108:109], v[6:7], v[66:67], v[108:109] op_sel_hi:[1,0,1]
	v_pk_fma_f32 v[112:113], v[6:7], v[74:75], v[112:113] op_sel_hi:[1,0,1]
	v_pk_fma_f32 v[108:109], v[8:9], v[66:67], v[108:109] op_sel:[0,1,0]
	v_pk_fma_f32 v[112:113], v[8:9], v[74:75], v[112:113] op_sel:[0,1,0]
	ds_read_b128 v[24:27], v225 offset:3088
	v_pk_fma_f32 v[108:109], v[10:11], v[68:69], v[108:109] op_sel_hi:[1,0,1]
	v_pk_fma_f32 v[112:113], v[10:11], v[76:77], v[112:113] op_sel_hi:[1,0,1]
	v_pk_fma_f32 v[108:109], v[12:13], v[68:69], v[108:109] op_sel:[0,1,0]
	v_pk_fma_f32 v[112:113], v[12:13], v[76:77], v[112:113] op_sel:[0,1,0]
	ds_read_b128 v[28:31], v225 offset:35840
	v_pk_fma_f32 v[108:109], v[14:15], v[70:71], v[108:109] op_sel_hi:[1,0,1]
	v_pk_fma_f32 v[112:113], v[14:15], v[78:79], v[112:113] op_sel_hi:[1,0,1]
	v_pk_fma_f32 v[108:109], v[16:17], v[70:71], v[108:109] op_sel:[0,1,0]
	v_pk_fma_f32 v[112:113], v[16:17], v[78:79], v[112:113] op_sel:[0,1,0]
	ds_read_b128 v[32:35], v225 offset:35856
	s_waitcnt lgkmcnt(10)
	v_pk_mul_f32 v[116:117], v[104:105], v[80:81] op_sel_hi:[1,0]
	v_pk_mul_f32 v[118:119], v[104:105], v[80:81] op_sel:[0,1]
	v_pk_mul_f32 v[120:121], v[104:105], v[82:83] op_sel_hi:[1,0]
	v_pk_mul_f32 v[122:123], v[104:105], v[82:83] op_sel:[0,1]
	ds_read_b64 v[60:61], v224 offset:44032
	ds_read_b128 v[36:39], v225 offset:27648
	v_add_f32_dpp v108, v108, v108 quad_perm:[1,0,3,2] row_mask:0xf bank_mask:0xf bound_ctrl:1
	v_add_f32_dpp v109, v109, v109 quad_perm:[1,0,3,2] row_mask:0xf bank_mask:0xf bound_ctrl:1
	v_add_f32_dpp v112, v112, v112 quad_perm:[1,0,3,2] row_mask:0xf bank_mask:0xf bound_ctrl:1
	v_add_f32_dpp v113, v113, v113 quad_perm:[1,0,3,2] row_mask:0xf bank_mask:0xf bound_ctrl:1
	v_pk_mul_f32 v[124:125], v[104:105], v[84:85] op_sel_hi:[1,0]
	v_pk_mul_f32 v[126:127], v[104:105], v[84:85] op_sel:[0,1]
	v_pk_mul_f32 v[128:129], v[104:105], v[86:87] op_sel_hi:[1,0]
	v_pk_mul_f32 v[130:131], v[104:105], v[86:87] op_sel:[0,1]
	ds_read_b128 v[40:43], v225 offset:27664
	ds_read_b64 v[62:63], v134 offset:57440
	v_add_f32_dpp v108, v108, v108 quad_perm:[2,3,0,1] row_mask:0xf bank_mask:0xf bound_ctrl:1
	v_add_f32_dpp v109, v109, v109 quad_perm:[2,3,0,1] row_mask:0xf bank_mask:0xf bound_ctrl:1
	v_add_f32_dpp v112, v112, v112 quad_perm:[2,3,0,1] row_mask:0xf bank_mask:0xf bound_ctrl:1
	v_add_f32_dpp v113, v113, v113 quad_perm:[2,3,0,1] row_mask:0xf bank_mask:0xf bound_ctrl:1
	ds_read_b128 v[44:47], v225 offset:19456
	v_add_f32_dpp v108, v108, v108 row_half_mirror row_mask:0xf bank_mask:0xf bound_ctrl:1
	v_add_f32_dpp v109, v109, v109 row_half_mirror row_mask:0xf bank_mask:0xf bound_ctrl:1
	v_add_f32_dpp v112, v112, v112 row_half_mirror row_mask:0xf bank_mask:0xf bound_ctrl:1
	v_add_f32_dpp v113, v113, v113 row_half_mirror row_mask:0xf bank_mask:0xf bound_ctrl:1
	ds_read_b128 v[48:51], v225 offset:19472
	s_waitcnt lgkmcnt(11)
	v_pk_fma_f32 v[116:117], v[108:109], v[88:89], v[116:117] op_sel_hi:[1,0,1] neg_lo:[1,0,0] neg_hi:[1,0,0]
	v_pk_fma_f32 v[118:119], v[108:109], v[88:89], v[118:119] op_sel:[0,1,0] neg_lo:[1,0,0] neg_hi:[1,0,0]
	v_pk_fma_f32 v[120:121], v[108:109], v[90:91], v[120:121] op_sel_hi:[1,0,1] neg_lo:[1,0,0] neg_hi:[1,0,0]
	v_pk_fma_f32 v[122:123], v[108:109], v[90:91], v[122:123] op_sel:[0,1,0] neg_lo:[1,0,0] neg_hi:[1,0,0]
	v_pk_fma_f32 v[124:125], v[108:109], v[92:93], v[124:125] op_sel_hi:[1,0,1] neg_lo:[1,0,0] neg_hi:[1,0,0]
	v_pk_fma_f32 v[126:127], v[108:109], v[92:93], v[126:127] op_sel:[0,1,0] neg_lo:[1,0,0] neg_hi:[1,0,0]
	v_pk_fma_f32 v[128:129], v[108:109], v[94:95], v[128:129] op_sel_hi:[1,0,1] neg_lo:[1,0,0] neg_hi:[1,0,0]
	v_pk_fma_f32 v[130:131], v[108:109], v[94:95], v[130:131] op_sel:[0,1,0] neg_lo:[1,0,0] neg_hi:[1,0,0]
	ds_read_b128 v[52:55], v225 offset:11264
	v_pk_fma_f32 v[132:133], v[108:109], v[106:107], v[112:113] op_sel_hi:[1,0,1] neg_lo:[1,0,0] neg_hi:[1,0,0]
	ds_read_b128 v[56:59], v225 offset:11280
	v_pk_fma_f32 v[2:3], v[2:3], v[96:97], v[116:117] op_sel_hi:[1,0,1]
	v_pk_fma_f32 v[4:5], v[4:5], v[96:97], v[118:119] op_sel:[0,1,0]
	v_pk_fma_f32 v[6:7], v[6:7], v[98:99], v[120:121] op_sel_hi:[1,0,1]
	v_pk_fma_f32 v[8:9], v[8:9], v[98:99], v[122:123] op_sel:[0,1,0]
	v_pk_fma_f32 v[132:133], v[104:105], v[106:107], v[132:133] op_sel:[0,1,0]
	v_pk_fma_f32 v[10:11], v[10:11], v[100:101], v[124:125] op_sel_hi:[1,0,1]
	v_pk_fma_f32 v[12:13], v[12:13], v[100:101], v[126:127] op_sel:[0,1,0]
	v_pk_fma_f32 v[14:15], v[14:15], v[102:103], v[128:129] op_sel_hi:[1,0,1]
	v_pk_fma_f32 v[16:17], v[16:17], v[102:103], v[130:131] op_sel:[0,1,0]
	ds_write_b64 v135, v[132:133] offset:51968
	s_waitcnt lgkmcnt(9)
	v_pk_mul_f32 v[108:109], v[2:3], v[20:21] op_sel_hi:[1,0]
	v_pk_mul_f32 v[112:113], v[2:3], v[28:29] op_sel_hi:[1,0]
	v_pk_fma_f32 v[108:109], v[4:5], v[20:21], v[108:109] op_sel:[0,1,0]
	v_pk_fma_f32 v[112:113], v[4:5], v[28:29], v[112:113] op_sel:[0,1,0]
	ds_read_b128 v[64:67], v225 offset:3328
	v_pk_fma_f32 v[108:109], v[6:7], v[22:23], v[108:109] op_sel_hi:[1,0,1]
	v_pk_fma_f32 v[112:113], v[6:7], v[30:31], v[112:113] op_sel_hi:[1,0,1]
	v_pk_fma_f32 v[108:109], v[8:9], v[22:23], v[108:109] op_sel:[0,1,0]
	v_pk_fma_f32 v[112:113], v[8:9], v[30:31], v[112:113] op_sel:[0,1,0]
	ds_read_b128 v[68:71], v225 offset:3344
	v_pk_fma_f32 v[108:109], v[10:11], v[24:25], v[108:109] op_sel_hi:[1,0,1]
	v_pk_fma_f32 v[112:113], v[10:11], v[32:33], v[112:113] op_sel_hi:[1,0,1]
	v_pk_fma_f32 v[108:109], v[12:13], v[24:25], v[108:109] op_sel:[0,1,0]
	v_pk_fma_f32 v[112:113], v[12:13], v[32:33], v[112:113] op_sel:[0,1,0]
	ds_read_b128 v[72:75], v225 offset:36096
	v_pk_fma_f32 v[108:109], v[14:15], v[26:27], v[108:109] op_sel_hi:[1,0,1]
	v_pk_fma_f32 v[112:113], v[14:15], v[34:35], v[112:113] op_sel_hi:[1,0,1]
	v_pk_fma_f32 v[108:109], v[16:17], v[26:27], v[108:109] op_sel:[0,1,0]
	v_pk_fma_f32 v[112:113], v[16:17], v[34:35], v[112:113] op_sel:[0,1,0]
	ds_read_b128 v[76:79], v225 offset:36112
	s_waitcnt lgkmcnt(10)
	v_pk_mul_f32 v[116:117], v[60:61], v[36:37] op_sel_hi:[1,0]
	v_pk_mul_f32 v[118:119], v[60:61], v[36:37] op_sel:[0,1]
	v_pk_mul_f32 v[120:121], v[60:61], v[38:39] op_sel_hi:[1,0]
	v_pk_mul_f32 v[122:123], v[60:61], v[38:39] op_sel:[0,1]
	ds_read_b64 v[104:105], v224 offset:44288
	ds_read_b128 v[80:83], v225 offset:27904
	v_add_f32_dpp v108, v108, v108 quad_perm:[1,0,3,2] row_mask:0xf bank_mask:0xf bound_ctrl:1
	v_add_f32_dpp v109, v109, v109 quad_perm:[1,0,3,2] row_mask:0xf bank_mask:0xf bound_ctrl:1
	v_add_f32_dpp v112, v112, v112 quad_perm:[1,0,3,2] row_mask:0xf bank_mask:0xf bound_ctrl:1
	v_add_f32_dpp v113, v113, v113 quad_perm:[1,0,3,2] row_mask:0xf bank_mask:0xf bound_ctrl:1
	v_pk_mul_f32 v[124:125], v[60:61], v[40:41] op_sel_hi:[1,0]
	v_pk_mul_f32 v[126:127], v[60:61], v[40:41] op_sel:[0,1]
	v_pk_mul_f32 v[128:129], v[60:61], v[42:43] op_sel_hi:[1,0]
	v_pk_mul_f32 v[130:131], v[60:61], v[42:43] op_sel:[0,1]
	ds_read_b128 v[84:87], v225 offset:27920
	ds_read_b64 v[106:107], v134 offset:57448
	v_add_f32_dpp v108, v108, v108 quad_perm:[2,3,0,1] row_mask:0xf bank_mask:0xf bound_ctrl:1
	v_add_f32_dpp v109, v109, v109 quad_perm:[2,3,0,1] row_mask:0xf bank_mask:0xf bound_ctrl:1
	v_add_f32_dpp v112, v112, v112 quad_perm:[2,3,0,1] row_mask:0xf bank_mask:0xf bound_ctrl:1
	v_add_f32_dpp v113, v113, v113 quad_perm:[2,3,0,1] row_mask:0xf bank_mask:0xf bound_ctrl:1
	ds_read_b128 v[88:91], v225 offset:19712
	v_add_f32_dpp v108, v108, v108 row_half_mirror row_mask:0xf bank_mask:0xf bound_ctrl:1
	v_add_f32_dpp v109, v109, v109 row_half_mirror row_mask:0xf bank_mask:0xf bound_ctrl:1
	v_add_f32_dpp v112, v112, v112 row_half_mirror row_mask:0xf bank_mask:0xf bound_ctrl:1
	v_add_f32_dpp v113, v113, v113 row_half_mirror row_mask:0xf bank_mask:0xf bound_ctrl:1
	ds_read_b128 v[92:95], v225 offset:19728
	s_waitcnt lgkmcnt(11)
	v_pk_fma_f32 v[116:117], v[108:109], v[44:45], v[116:117] op_sel_hi:[1,0,1] neg_lo:[1,0,0] neg_hi:[1,0,0]
	v_pk_fma_f32 v[118:119], v[108:109], v[44:45], v[118:119] op_sel:[0,1,0] neg_lo:[1,0,0] neg_hi:[1,0,0]
	v_pk_fma_f32 v[120:121], v[108:109], v[46:47], v[120:121] op_sel_hi:[1,0,1] neg_lo:[1,0,0] neg_hi:[1,0,0]
	v_pk_fma_f32 v[122:123], v[108:109], v[46:47], v[122:123] op_sel:[0,1,0] neg_lo:[1,0,0] neg_hi:[1,0,0]
	v_pk_fma_f32 v[124:125], v[108:109], v[48:49], v[124:125] op_sel_hi:[1,0,1] neg_lo:[1,0,0] neg_hi:[1,0,0]
	v_pk_fma_f32 v[126:127], v[108:109], v[48:49], v[126:127] op_sel:[0,1,0] neg_lo:[1,0,0] neg_hi:[1,0,0]
	v_pk_fma_f32 v[128:129], v[108:109], v[50:51], v[128:129] op_sel_hi:[1,0,1] neg_lo:[1,0,0] neg_hi:[1,0,0]
	v_pk_fma_f32 v[130:131], v[108:109], v[50:51], v[130:131] op_sel:[0,1,0] neg_lo:[1,0,0] neg_hi:[1,0,0]
	ds_read_b128 v[96:99], v225 offset:11520
	v_pk_fma_f32 v[132:133], v[108:109], v[62:63], v[112:113] op_sel_hi:[1,0,1] neg_lo:[1,0,0] neg_hi:[1,0,0]
	ds_read_b128 v[100:103], v225 offset:11536
	v_pk_fma_f32 v[2:3], v[2:3], v[52:53], v[116:117] op_sel_hi:[1,0,1]
	v_pk_fma_f32 v[4:5], v[4:5], v[52:53], v[118:119] op_sel:[0,1,0]
	v_pk_fma_f32 v[6:7], v[6:7], v[54:55], v[120:121] op_sel_hi:[1,0,1]
	v_pk_fma_f32 v[8:9], v[8:9], v[54:55], v[122:123] op_sel:[0,1,0]
	v_pk_fma_f32 v[132:133], v[60:61], v[62:63], v[132:133] op_sel:[0,1,0]
	v_pk_fma_f32 v[10:11], v[10:11], v[56:57], v[124:125] op_sel_hi:[1,0,1]
	v_pk_fma_f32 v[12:13], v[12:13], v[56:57], v[126:127] op_sel:[0,1,0]
	v_pk_fma_f32 v[14:15], v[14:15], v[58:59], v[128:129] op_sel_hi:[1,0,1]
	v_pk_fma_f32 v[16:17], v[16:17], v[58:59], v[130:131] op_sel:[0,1,0]
	ds_write_b64 v135, v[132:133] offset:52224
	s_waitcnt lgkmcnt(9)
	v_pk_mul_f32 v[108:109], v[2:3], v[64:65] op_sel_hi:[1,0]
	v_pk_mul_f32 v[112:113], v[2:3], v[72:73] op_sel_hi:[1,0]
	v_pk_fma_f32 v[108:109], v[4:5], v[64:65], v[108:109] op_sel:[0,1,0]
	v_pk_fma_f32 v[112:113], v[4:5], v[72:73], v[112:113] op_sel:[0,1,0]
	ds_read_b128 v[20:23], v225 offset:3584
	v_pk_fma_f32 v[108:109], v[6:7], v[66:67], v[108:109] op_sel_hi:[1,0,1]
	v_pk_fma_f32 v[112:113], v[6:7], v[74:75], v[112:113] op_sel_hi:[1,0,1]
	v_pk_fma_f32 v[108:109], v[8:9], v[66:67], v[108:109] op_sel:[0,1,0]
	v_pk_fma_f32 v[112:113], v[8:9], v[74:75], v[112:113] op_sel:[0,1,0]
	ds_read_b128 v[24:27], v225 offset:3600
	v_pk_fma_f32 v[108:109], v[10:11], v[68:69], v[108:109] op_sel_hi:[1,0,1]
	v_pk_fma_f32 v[112:113], v[10:11], v[76:77], v[112:113] op_sel_hi:[1,0,1]
	v_pk_fma_f32 v[108:109], v[12:13], v[68:69], v[108:109] op_sel:[0,1,0]
	v_pk_fma_f32 v[112:113], v[12:13], v[76:77], v[112:113] op_sel:[0,1,0]
	ds_read_b128 v[28:31], v225 offset:36352
	v_pk_fma_f32 v[108:109], v[14:15], v[70:71], v[108:109] op_sel_hi:[1,0,1]
	v_pk_fma_f32 v[112:113], v[14:15], v[78:79], v[112:113] op_sel_hi:[1,0,1]
	v_pk_fma_f32 v[108:109], v[16:17], v[70:71], v[108:109] op_sel:[0,1,0]
	v_pk_fma_f32 v[112:113], v[16:17], v[78:79], v[112:113] op_sel:[0,1,0]
	ds_read_b128 v[32:35], v225 offset:36368
	s_waitcnt lgkmcnt(10)
	v_pk_mul_f32 v[116:117], v[104:105], v[80:81] op_sel_hi:[1,0]
	v_pk_mul_f32 v[118:119], v[104:105], v[80:81] op_sel:[0,1]
	v_pk_mul_f32 v[120:121], v[104:105], v[82:83] op_sel_hi:[1,0]
	v_pk_mul_f32 v[122:123], v[104:105], v[82:83] op_sel:[0,1]
	ds_read_b64 v[60:61], v224 offset:44544
	ds_read_b128 v[36:39], v225 offset:28160
	v_add_f32_dpp v108, v108, v108 quad_perm:[1,0,3,2] row_mask:0xf bank_mask:0xf bound_ctrl:1
	v_add_f32_dpp v109, v109, v109 quad_perm:[1,0,3,2] row_mask:0xf bank_mask:0xf bound_ctrl:1
	v_add_f32_dpp v112, v112, v112 quad_perm:[1,0,3,2] row_mask:0xf bank_mask:0xf bound_ctrl:1
	v_add_f32_dpp v113, v113, v113 quad_perm:[1,0,3,2] row_mask:0xf bank_mask:0xf bound_ctrl:1
	v_pk_mul_f32 v[124:125], v[104:105], v[84:85] op_sel_hi:[1,0]
	v_pk_mul_f32 v[126:127], v[104:105], v[84:85] op_sel:[0,1]
	v_pk_mul_f32 v[128:129], v[104:105], v[86:87] op_sel_hi:[1,0]
	v_pk_mul_f32 v[130:131], v[104:105], v[86:87] op_sel:[0,1]
	ds_read_b128 v[40:43], v225 offset:28176
	ds_read_b64 v[62:63], v134 offset:57456
	v_add_f32_dpp v108, v108, v108 quad_perm:[2,3,0,1] row_mask:0xf bank_mask:0xf bound_ctrl:1
	v_add_f32_dpp v109, v109, v109 quad_perm:[2,3,0,1] row_mask:0xf bank_mask:0xf bound_ctrl:1
	v_add_f32_dpp v112, v112, v112 quad_perm:[2,3,0,1] row_mask:0xf bank_mask:0xf bound_ctrl:1
	v_add_f32_dpp v113, v113, v113 quad_perm:[2,3,0,1] row_mask:0xf bank_mask:0xf bound_ctrl:1
	ds_read_b128 v[44:47], v225 offset:19968
	v_add_f32_dpp v108, v108, v108 row_half_mirror row_mask:0xf bank_mask:0xf bound_ctrl:1
	v_add_f32_dpp v109, v109, v109 row_half_mirror row_mask:0xf bank_mask:0xf bound_ctrl:1
	v_add_f32_dpp v112, v112, v112 row_half_mirror row_mask:0xf bank_mask:0xf bound_ctrl:1
	v_add_f32_dpp v113, v113, v113 row_half_mirror row_mask:0xf bank_mask:0xf bound_ctrl:1
	ds_read_b128 v[48:51], v225 offset:19984
	s_waitcnt lgkmcnt(11)
	v_pk_fma_f32 v[116:117], v[108:109], v[88:89], v[116:117] op_sel_hi:[1,0,1] neg_lo:[1,0,0] neg_hi:[1,0,0]
	v_pk_fma_f32 v[118:119], v[108:109], v[88:89], v[118:119] op_sel:[0,1,0] neg_lo:[1,0,0] neg_hi:[1,0,0]
	v_pk_fma_f32 v[120:121], v[108:109], v[90:91], v[120:121] op_sel_hi:[1,0,1] neg_lo:[1,0,0] neg_hi:[1,0,0]
	v_pk_fma_f32 v[122:123], v[108:109], v[90:91], v[122:123] op_sel:[0,1,0] neg_lo:[1,0,0] neg_hi:[1,0,0]
	v_pk_fma_f32 v[124:125], v[108:109], v[92:93], v[124:125] op_sel_hi:[1,0,1] neg_lo:[1,0,0] neg_hi:[1,0,0]
	v_pk_fma_f32 v[126:127], v[108:109], v[92:93], v[126:127] op_sel:[0,1,0] neg_lo:[1,0,0] neg_hi:[1,0,0]
	v_pk_fma_f32 v[128:129], v[108:109], v[94:95], v[128:129] op_sel_hi:[1,0,1] neg_lo:[1,0,0] neg_hi:[1,0,0]
	v_pk_fma_f32 v[130:131], v[108:109], v[94:95], v[130:131] op_sel:[0,1,0] neg_lo:[1,0,0] neg_hi:[1,0,0]
	ds_read_b128 v[52:55], v225 offset:11776
	v_pk_fma_f32 v[132:133], v[108:109], v[106:107], v[112:113] op_sel_hi:[1,0,1] neg_lo:[1,0,0] neg_hi:[1,0,0]
	ds_read_b128 v[56:59], v225 offset:11792
	v_pk_fma_f32 v[2:3], v[2:3], v[96:97], v[116:117] op_sel_hi:[1,0,1]
	v_pk_fma_f32 v[4:5], v[4:5], v[96:97], v[118:119] op_sel:[0,1,0]
	v_pk_fma_f32 v[6:7], v[6:7], v[98:99], v[120:121] op_sel_hi:[1,0,1]
	v_pk_fma_f32 v[8:9], v[8:9], v[98:99], v[122:123] op_sel:[0,1,0]
	v_pk_fma_f32 v[132:133], v[104:105], v[106:107], v[132:133] op_sel:[0,1,0]
	v_pk_fma_f32 v[10:11], v[10:11], v[100:101], v[124:125] op_sel_hi:[1,0,1]
	v_pk_fma_f32 v[12:13], v[12:13], v[100:101], v[126:127] op_sel:[0,1,0]
	v_pk_fma_f32 v[14:15], v[14:15], v[102:103], v[128:129] op_sel_hi:[1,0,1]
	v_pk_fma_f32 v[16:17], v[16:17], v[102:103], v[130:131] op_sel:[0,1,0]
	ds_write_b64 v135, v[132:133] offset:52480
	s_waitcnt lgkmcnt(9)
	v_pk_mul_f32 v[108:109], v[2:3], v[20:21] op_sel_hi:[1,0]
	v_pk_mul_f32 v[112:113], v[2:3], v[28:29] op_sel_hi:[1,0]
	v_pk_fma_f32 v[108:109], v[4:5], v[20:21], v[108:109] op_sel:[0,1,0]
	v_pk_fma_f32 v[112:113], v[4:5], v[28:29], v[112:113] op_sel:[0,1,0]
	ds_read_b128 v[64:67], v225 offset:3840
	v_pk_fma_f32 v[108:109], v[6:7], v[22:23], v[108:109] op_sel_hi:[1,0,1]
	v_pk_fma_f32 v[112:113], v[6:7], v[30:31], v[112:113] op_sel_hi:[1,0,1]
	v_pk_fma_f32 v[108:109], v[8:9], v[22:23], v[108:109] op_sel:[0,1,0]
	v_pk_fma_f32 v[112:113], v[8:9], v[30:31], v[112:113] op_sel:[0,1,0]
	ds_read_b128 v[68:71], v225 offset:3856
	v_pk_fma_f32 v[108:109], v[10:11], v[24:25], v[108:109] op_sel_hi:[1,0,1]
	v_pk_fma_f32 v[112:113], v[10:11], v[32:33], v[112:113] op_sel_hi:[1,0,1]
	v_pk_fma_f32 v[108:109], v[12:13], v[24:25], v[108:109] op_sel:[0,1,0]
	v_pk_fma_f32 v[112:113], v[12:13], v[32:33], v[112:113] op_sel:[0,1,0]
	ds_read_b128 v[72:75], v225 offset:36608
	v_pk_fma_f32 v[108:109], v[14:15], v[26:27], v[108:109] op_sel_hi:[1,0,1]
	v_pk_fma_f32 v[112:113], v[14:15], v[34:35], v[112:113] op_sel_hi:[1,0,1]
	v_pk_fma_f32 v[108:109], v[16:17], v[26:27], v[108:109] op_sel:[0,1,0]
	v_pk_fma_f32 v[112:113], v[16:17], v[34:35], v[112:113] op_sel:[0,1,0]
	ds_read_b128 v[76:79], v225 offset:36624
	s_waitcnt lgkmcnt(10)
	v_pk_mul_f32 v[116:117], v[60:61], v[36:37] op_sel_hi:[1,0]
	v_pk_mul_f32 v[118:119], v[60:61], v[36:37] op_sel:[0,1]
	v_pk_mul_f32 v[120:121], v[60:61], v[38:39] op_sel_hi:[1,0]
	v_pk_mul_f32 v[122:123], v[60:61], v[38:39] op_sel:[0,1]
	ds_read_b64 v[104:105], v224 offset:44800
	ds_read_b128 v[80:83], v225 offset:28416
	v_add_f32_dpp v108, v108, v108 quad_perm:[1,0,3,2] row_mask:0xf bank_mask:0xf bound_ctrl:1
	v_add_f32_dpp v109, v109, v109 quad_perm:[1,0,3,2] row_mask:0xf bank_mask:0xf bound_ctrl:1
	v_add_f32_dpp v112, v112, v112 quad_perm:[1,0,3,2] row_mask:0xf bank_mask:0xf bound_ctrl:1
	v_add_f32_dpp v113, v113, v113 quad_perm:[1,0,3,2] row_mask:0xf bank_mask:0xf bound_ctrl:1
	v_pk_mul_f32 v[124:125], v[60:61], v[40:41] op_sel_hi:[1,0]
	v_pk_mul_f32 v[126:127], v[60:61], v[40:41] op_sel:[0,1]
	v_pk_mul_f32 v[128:129], v[60:61], v[42:43] op_sel_hi:[1,0]
	v_pk_mul_f32 v[130:131], v[60:61], v[42:43] op_sel:[0,1]
	ds_read_b128 v[84:87], v225 offset:28432
	ds_read_b64 v[106:107], v134 offset:57464
	v_add_f32_dpp v108, v108, v108 quad_perm:[2,3,0,1] row_mask:0xf bank_mask:0xf bound_ctrl:1
	v_add_f32_dpp v109, v109, v109 quad_perm:[2,3,0,1] row_mask:0xf bank_mask:0xf bound_ctrl:1
	v_add_f32_dpp v112, v112, v112 quad_perm:[2,3,0,1] row_mask:0xf bank_mask:0xf bound_ctrl:1
	v_add_f32_dpp v113, v113, v113 quad_perm:[2,3,0,1] row_mask:0xf bank_mask:0xf bound_ctrl:1
	ds_read_b128 v[88:91], v225 offset:20224
	v_add_f32_dpp v108, v108, v108 row_half_mirror row_mask:0xf bank_mask:0xf bound_ctrl:1
	v_add_f32_dpp v109, v109, v109 row_half_mirror row_mask:0xf bank_mask:0xf bound_ctrl:1
	v_add_f32_dpp v112, v112, v112 row_half_mirror row_mask:0xf bank_mask:0xf bound_ctrl:1
	v_add_f32_dpp v113, v113, v113 row_half_mirror row_mask:0xf bank_mask:0xf bound_ctrl:1
	ds_read_b128 v[92:95], v225 offset:20240
	s_waitcnt lgkmcnt(11)
	v_pk_fma_f32 v[116:117], v[108:109], v[44:45], v[116:117] op_sel_hi:[1,0,1] neg_lo:[1,0,0] neg_hi:[1,0,0]
	v_pk_fma_f32 v[118:119], v[108:109], v[44:45], v[118:119] op_sel:[0,1,0] neg_lo:[1,0,0] neg_hi:[1,0,0]
	v_pk_fma_f32 v[120:121], v[108:109], v[46:47], v[120:121] op_sel_hi:[1,0,1] neg_lo:[1,0,0] neg_hi:[1,0,0]
	v_pk_fma_f32 v[122:123], v[108:109], v[46:47], v[122:123] op_sel:[0,1,0] neg_lo:[1,0,0] neg_hi:[1,0,0]
	v_pk_fma_f32 v[124:125], v[108:109], v[48:49], v[124:125] op_sel_hi:[1,0,1] neg_lo:[1,0,0] neg_hi:[1,0,0]
	v_pk_fma_f32 v[126:127], v[108:109], v[48:49], v[126:127] op_sel:[0,1,0] neg_lo:[1,0,0] neg_hi:[1,0,0]
	v_pk_fma_f32 v[128:129], v[108:109], v[50:51], v[128:129] op_sel_hi:[1,0,1] neg_lo:[1,0,0] neg_hi:[1,0,0]
	v_pk_fma_f32 v[130:131], v[108:109], v[50:51], v[130:131] op_sel:[0,1,0] neg_lo:[1,0,0] neg_hi:[1,0,0]
	ds_read_b128 v[96:99], v225 offset:12032
	v_pk_fma_f32 v[132:133], v[108:109], v[62:63], v[112:113] op_sel_hi:[1,0,1] neg_lo:[1,0,0] neg_hi:[1,0,0]
	ds_read_b128 v[100:103], v225 offset:12048
	v_pk_fma_f32 v[2:3], v[2:3], v[52:53], v[116:117] op_sel_hi:[1,0,1]
	v_pk_fma_f32 v[4:5], v[4:5], v[52:53], v[118:119] op_sel:[0,1,0]
	v_pk_fma_f32 v[6:7], v[6:7], v[54:55], v[120:121] op_sel_hi:[1,0,1]
	v_pk_fma_f32 v[8:9], v[8:9], v[54:55], v[122:123] op_sel:[0,1,0]
	v_pk_fma_f32 v[132:133], v[60:61], v[62:63], v[132:133] op_sel:[0,1,0]
	v_pk_fma_f32 v[10:11], v[10:11], v[56:57], v[124:125] op_sel_hi:[1,0,1]
	v_pk_fma_f32 v[12:13], v[12:13], v[56:57], v[126:127] op_sel:[0,1,0]
	v_pk_fma_f32 v[14:15], v[14:15], v[58:59], v[128:129] op_sel_hi:[1,0,1]
	v_pk_fma_f32 v[16:17], v[16:17], v[58:59], v[130:131] op_sel:[0,1,0]
	ds_write_b64 v135, v[132:133] offset:52736
	s_waitcnt lgkmcnt(9)
	v_pk_mul_f32 v[108:109], v[2:3], v[64:65] op_sel_hi:[1,0]
	v_pk_mul_f32 v[112:113], v[2:3], v[72:73] op_sel_hi:[1,0]
	v_pk_fma_f32 v[108:109], v[4:5], v[64:65], v[108:109] op_sel:[0,1,0]
	v_pk_fma_f32 v[112:113], v[4:5], v[72:73], v[112:113] op_sel:[0,1,0]
	ds_read_b128 v[20:23], v225 offset:4096
	v_pk_fma_f32 v[108:109], v[6:7], v[66:67], v[108:109] op_sel_hi:[1,0,1]
	v_pk_fma_f32 v[112:113], v[6:7], v[74:75], v[112:113] op_sel_hi:[1,0,1]
	v_pk_fma_f32 v[108:109], v[8:9], v[66:67], v[108:109] op_sel:[0,1,0]
	v_pk_fma_f32 v[112:113], v[8:9], v[74:75], v[112:113] op_sel:[0,1,0]
	ds_read_b128 v[24:27], v225 offset:4112
	v_pk_fma_f32 v[108:109], v[10:11], v[68:69], v[108:109] op_sel_hi:[1,0,1]
	v_pk_fma_f32 v[112:113], v[10:11], v[76:77], v[112:113] op_sel_hi:[1,0,1]
	v_pk_fma_f32 v[108:109], v[12:13], v[68:69], v[108:109] op_sel:[0,1,0]
	v_pk_fma_f32 v[112:113], v[12:13], v[76:77], v[112:113] op_sel:[0,1,0]
	ds_read_b128 v[28:31], v225 offset:36864
	v_pk_fma_f32 v[108:109], v[14:15], v[70:71], v[108:109] op_sel_hi:[1,0,1]
	v_pk_fma_f32 v[112:113], v[14:15], v[78:79], v[112:113] op_sel_hi:[1,0,1]
	v_pk_fma_f32 v[108:109], v[16:17], v[70:71], v[108:109] op_sel:[0,1,0]
	v_pk_fma_f32 v[112:113], v[16:17], v[78:79], v[112:113] op_sel:[0,1,0]
	ds_read_b128 v[32:35], v225 offset:36880
	s_waitcnt lgkmcnt(10)
	v_pk_mul_f32 v[116:117], v[104:105], v[80:81] op_sel_hi:[1,0]
	v_pk_mul_f32 v[118:119], v[104:105], v[80:81] op_sel:[0,1]
	v_pk_mul_f32 v[120:121], v[104:105], v[82:83] op_sel_hi:[1,0]
	v_pk_mul_f32 v[122:123], v[104:105], v[82:83] op_sel:[0,1]
	ds_read_b64 v[60:61], v224 offset:45056
	ds_read_b128 v[36:39], v225 offset:28672
	v_add_f32_dpp v108, v108, v108 quad_perm:[1,0,3,2] row_mask:0xf bank_mask:0xf bound_ctrl:1
	v_add_f32_dpp v109, v109, v109 quad_perm:[1,0,3,2] row_mask:0xf bank_mask:0xf bound_ctrl:1
	v_add_f32_dpp v112, v112, v112 quad_perm:[1,0,3,2] row_mask:0xf bank_mask:0xf bound_ctrl:1
	v_add_f32_dpp v113, v113, v113 quad_perm:[1,0,3,2] row_mask:0xf bank_mask:0xf bound_ctrl:1
	v_pk_mul_f32 v[124:125], v[104:105], v[84:85] op_sel_hi:[1,0]
	v_pk_mul_f32 v[126:127], v[104:105], v[84:85] op_sel:[0,1]
	v_pk_mul_f32 v[128:129], v[104:105], v[86:87] op_sel_hi:[1,0]
	v_pk_mul_f32 v[130:131], v[104:105], v[86:87] op_sel:[0,1]
	ds_read_b128 v[40:43], v225 offset:28688
	ds_read_b64 v[62:63], v134 offset:57472
	v_add_f32_dpp v108, v108, v108 quad_perm:[2,3,0,1] row_mask:0xf bank_mask:0xf bound_ctrl:1
	v_add_f32_dpp v109, v109, v109 quad_perm:[2,3,0,1] row_mask:0xf bank_mask:0xf bound_ctrl:1
	v_add_f32_dpp v112, v112, v112 quad_perm:[2,3,0,1] row_mask:0xf bank_mask:0xf bound_ctrl:1
	v_add_f32_dpp v113, v113, v113 quad_perm:[2,3,0,1] row_mask:0xf bank_mask:0xf bound_ctrl:1
	ds_read_b128 v[44:47], v225 offset:20480
	v_add_f32_dpp v108, v108, v108 row_half_mirror row_mask:0xf bank_mask:0xf bound_ctrl:1
	v_add_f32_dpp v109, v109, v109 row_half_mirror row_mask:0xf bank_mask:0xf bound_ctrl:1
	v_add_f32_dpp v112, v112, v112 row_half_mirror row_mask:0xf bank_mask:0xf bound_ctrl:1
	v_add_f32_dpp v113, v113, v113 row_half_mirror row_mask:0xf bank_mask:0xf bound_ctrl:1
	ds_read_b128 v[48:51], v225 offset:20496
	s_waitcnt lgkmcnt(11)
	v_pk_fma_f32 v[116:117], v[108:109], v[88:89], v[116:117] op_sel_hi:[1,0,1] neg_lo:[1,0,0] neg_hi:[1,0,0]
	v_pk_fma_f32 v[118:119], v[108:109], v[88:89], v[118:119] op_sel:[0,1,0] neg_lo:[1,0,0] neg_hi:[1,0,0]
	v_pk_fma_f32 v[120:121], v[108:109], v[90:91], v[120:121] op_sel_hi:[1,0,1] neg_lo:[1,0,0] neg_hi:[1,0,0]
	v_pk_fma_f32 v[122:123], v[108:109], v[90:91], v[122:123] op_sel:[0,1,0] neg_lo:[1,0,0] neg_hi:[1,0,0]
	v_pk_fma_f32 v[124:125], v[108:109], v[92:93], v[124:125] op_sel_hi:[1,0,1] neg_lo:[1,0,0] neg_hi:[1,0,0]
	v_pk_fma_f32 v[126:127], v[108:109], v[92:93], v[126:127] op_sel:[0,1,0] neg_lo:[1,0,0] neg_hi:[1,0,0]
	v_pk_fma_f32 v[128:129], v[108:109], v[94:95], v[128:129] op_sel_hi:[1,0,1] neg_lo:[1,0,0] neg_hi:[1,0,0]
	v_pk_fma_f32 v[130:131], v[108:109], v[94:95], v[130:131] op_sel:[0,1,0] neg_lo:[1,0,0] neg_hi:[1,0,0]
	ds_read_b128 v[52:55], v225 offset:12288
	v_pk_fma_f32 v[132:133], v[108:109], v[106:107], v[112:113] op_sel_hi:[1,0,1] neg_lo:[1,0,0] neg_hi:[1,0,0]
	ds_read_b128 v[56:59], v225 offset:12304
	v_pk_fma_f32 v[2:3], v[2:3], v[96:97], v[116:117] op_sel_hi:[1,0,1]
	v_pk_fma_f32 v[4:5], v[4:5], v[96:97], v[118:119] op_sel:[0,1,0]
	v_pk_fma_f32 v[6:7], v[6:7], v[98:99], v[120:121] op_sel_hi:[1,0,1]
	v_pk_fma_f32 v[8:9], v[8:9], v[98:99], v[122:123] op_sel:[0,1,0]
	v_pk_fma_f32 v[132:133], v[104:105], v[106:107], v[132:133] op_sel:[0,1,0]
	v_pk_fma_f32 v[10:11], v[10:11], v[100:101], v[124:125] op_sel_hi:[1,0,1]
	v_pk_fma_f32 v[12:13], v[12:13], v[100:101], v[126:127] op_sel:[0,1,0]
	v_pk_fma_f32 v[14:15], v[14:15], v[102:103], v[128:129] op_sel_hi:[1,0,1]
	v_pk_fma_f32 v[16:17], v[16:17], v[102:103], v[130:131] op_sel:[0,1,0]
	ds_write_b64 v135, v[132:133] offset:52992
	s_waitcnt lgkmcnt(9)
	v_pk_mul_f32 v[108:109], v[2:3], v[20:21] op_sel_hi:[1,0]
	v_pk_mul_f32 v[112:113], v[2:3], v[28:29] op_sel_hi:[1,0]
	v_pk_fma_f32 v[108:109], v[4:5], v[20:21], v[108:109] op_sel:[0,1,0]
	v_pk_fma_f32 v[112:113], v[4:5], v[28:29], v[112:113] op_sel:[0,1,0]
	ds_read_b128 v[64:67], v225 offset:4352
	v_pk_fma_f32 v[108:109], v[6:7], v[22:23], v[108:109] op_sel_hi:[1,0,1]
	v_pk_fma_f32 v[112:113], v[6:7], v[30:31], v[112:113] op_sel_hi:[1,0,1]
	v_pk_fma_f32 v[108:109], v[8:9], v[22:23], v[108:109] op_sel:[0,1,0]
	v_pk_fma_f32 v[112:113], v[8:9], v[30:31], v[112:113] op_sel:[0,1,0]
	ds_read_b128 v[68:71], v225 offset:4368
	v_pk_fma_f32 v[108:109], v[10:11], v[24:25], v[108:109] op_sel_hi:[1,0,1]
	v_pk_fma_f32 v[112:113], v[10:11], v[32:33], v[112:113] op_sel_hi:[1,0,1]
	v_pk_fma_f32 v[108:109], v[12:13], v[24:25], v[108:109] op_sel:[0,1,0]
	v_pk_fma_f32 v[112:113], v[12:13], v[32:33], v[112:113] op_sel:[0,1,0]
	ds_read_b128 v[72:75], v225 offset:37120
	v_pk_fma_f32 v[108:109], v[14:15], v[26:27], v[108:109] op_sel_hi:[1,0,1]
	v_pk_fma_f32 v[112:113], v[14:15], v[34:35], v[112:113] op_sel_hi:[1,0,1]
	v_pk_fma_f32 v[108:109], v[16:17], v[26:27], v[108:109] op_sel:[0,1,0]
	v_pk_fma_f32 v[112:113], v[16:17], v[34:35], v[112:113] op_sel:[0,1,0]
	ds_read_b128 v[76:79], v225 offset:37136
	s_waitcnt lgkmcnt(10)
	v_pk_mul_f32 v[116:117], v[60:61], v[36:37] op_sel_hi:[1,0]
	v_pk_mul_f32 v[118:119], v[60:61], v[36:37] op_sel:[0,1]
	v_pk_mul_f32 v[120:121], v[60:61], v[38:39] op_sel_hi:[1,0]
	v_pk_mul_f32 v[122:123], v[60:61], v[38:39] op_sel:[0,1]
	ds_read_b64 v[104:105], v224 offset:45312
	ds_read_b128 v[80:83], v225 offset:28928
	v_add_f32_dpp v108, v108, v108 quad_perm:[1,0,3,2] row_mask:0xf bank_mask:0xf bound_ctrl:1
	v_add_f32_dpp v109, v109, v109 quad_perm:[1,0,3,2] row_mask:0xf bank_mask:0xf bound_ctrl:1
	v_add_f32_dpp v112, v112, v112 quad_perm:[1,0,3,2] row_mask:0xf bank_mask:0xf bound_ctrl:1
	v_add_f32_dpp v113, v113, v113 quad_perm:[1,0,3,2] row_mask:0xf bank_mask:0xf bound_ctrl:1
	v_pk_mul_f32 v[124:125], v[60:61], v[40:41] op_sel_hi:[1,0]
	v_pk_mul_f32 v[126:127], v[60:61], v[40:41] op_sel:[0,1]
	v_pk_mul_f32 v[128:129], v[60:61], v[42:43] op_sel_hi:[1,0]
	v_pk_mul_f32 v[130:131], v[60:61], v[42:43] op_sel:[0,1]
	ds_read_b128 v[84:87], v225 offset:28944
	ds_read_b64 v[106:107], v134 offset:57480
	v_add_f32_dpp v108, v108, v108 quad_perm:[2,3,0,1] row_mask:0xf bank_mask:0xf bound_ctrl:1
	v_add_f32_dpp v109, v109, v109 quad_perm:[2,3,0,1] row_mask:0xf bank_mask:0xf bound_ctrl:1
	v_add_f32_dpp v112, v112, v112 quad_perm:[2,3,0,1] row_mask:0xf bank_mask:0xf bound_ctrl:1
	v_add_f32_dpp v113, v113, v113 quad_perm:[2,3,0,1] row_mask:0xf bank_mask:0xf bound_ctrl:1
	ds_read_b128 v[88:91], v225 offset:20736
	v_add_f32_dpp v108, v108, v108 row_half_mirror row_mask:0xf bank_mask:0xf bound_ctrl:1
	v_add_f32_dpp v109, v109, v109 row_half_mirror row_mask:0xf bank_mask:0xf bound_ctrl:1
	v_add_f32_dpp v112, v112, v112 row_half_mirror row_mask:0xf bank_mask:0xf bound_ctrl:1
	v_add_f32_dpp v113, v113, v113 row_half_mirror row_mask:0xf bank_mask:0xf bound_ctrl:1
	ds_read_b128 v[92:95], v225 offset:20752
	s_waitcnt lgkmcnt(11)
	v_pk_fma_f32 v[116:117], v[108:109], v[44:45], v[116:117] op_sel_hi:[1,0,1] neg_lo:[1,0,0] neg_hi:[1,0,0]
	v_pk_fma_f32 v[118:119], v[108:109], v[44:45], v[118:119] op_sel:[0,1,0] neg_lo:[1,0,0] neg_hi:[1,0,0]
	v_pk_fma_f32 v[120:121], v[108:109], v[46:47], v[120:121] op_sel_hi:[1,0,1] neg_lo:[1,0,0] neg_hi:[1,0,0]
	v_pk_fma_f32 v[122:123], v[108:109], v[46:47], v[122:123] op_sel:[0,1,0] neg_lo:[1,0,0] neg_hi:[1,0,0]
	v_pk_fma_f32 v[124:125], v[108:109], v[48:49], v[124:125] op_sel_hi:[1,0,1] neg_lo:[1,0,0] neg_hi:[1,0,0]
	v_pk_fma_f32 v[126:127], v[108:109], v[48:49], v[126:127] op_sel:[0,1,0] neg_lo:[1,0,0] neg_hi:[1,0,0]
	v_pk_fma_f32 v[128:129], v[108:109], v[50:51], v[128:129] op_sel_hi:[1,0,1] neg_lo:[1,0,0] neg_hi:[1,0,0]
	v_pk_fma_f32 v[130:131], v[108:109], v[50:51], v[130:131] op_sel:[0,1,0] neg_lo:[1,0,0] neg_hi:[1,0,0]
	ds_read_b128 v[96:99], v225 offset:12544
	v_pk_fma_f32 v[132:133], v[108:109], v[62:63], v[112:113] op_sel_hi:[1,0,1] neg_lo:[1,0,0] neg_hi:[1,0,0]
	ds_read_b128 v[100:103], v225 offset:12560
	v_pk_fma_f32 v[2:3], v[2:3], v[52:53], v[116:117] op_sel_hi:[1,0,1]
	v_pk_fma_f32 v[4:5], v[4:5], v[52:53], v[118:119] op_sel:[0,1,0]
	v_pk_fma_f32 v[6:7], v[6:7], v[54:55], v[120:121] op_sel_hi:[1,0,1]
	v_pk_fma_f32 v[8:9], v[8:9], v[54:55], v[122:123] op_sel:[0,1,0]
	v_pk_fma_f32 v[132:133], v[60:61], v[62:63], v[132:133] op_sel:[0,1,0]
	v_pk_fma_f32 v[10:11], v[10:11], v[56:57], v[124:125] op_sel_hi:[1,0,1]
	v_pk_fma_f32 v[12:13], v[12:13], v[56:57], v[126:127] op_sel:[0,1,0]
	v_pk_fma_f32 v[14:15], v[14:15], v[58:59], v[128:129] op_sel_hi:[1,0,1]
	v_pk_fma_f32 v[16:17], v[16:17], v[58:59], v[130:131] op_sel:[0,1,0]
	ds_write_b64 v135, v[132:133] offset:53248
	s_waitcnt lgkmcnt(9)
	v_pk_mul_f32 v[108:109], v[2:3], v[64:65] op_sel_hi:[1,0]
	v_pk_mul_f32 v[112:113], v[2:3], v[72:73] op_sel_hi:[1,0]
	v_pk_fma_f32 v[108:109], v[4:5], v[64:65], v[108:109] op_sel:[0,1,0]
	v_pk_fma_f32 v[112:113], v[4:5], v[72:73], v[112:113] op_sel:[0,1,0]
	ds_read_b128 v[20:23], v225 offset:4608
	v_pk_fma_f32 v[108:109], v[6:7], v[66:67], v[108:109] op_sel_hi:[1,0,1]
	v_pk_fma_f32 v[112:113], v[6:7], v[74:75], v[112:113] op_sel_hi:[1,0,1]
	v_pk_fma_f32 v[108:109], v[8:9], v[66:67], v[108:109] op_sel:[0,1,0]
	v_pk_fma_f32 v[112:113], v[8:9], v[74:75], v[112:113] op_sel:[0,1,0]
	ds_read_b128 v[24:27], v225 offset:4624
	v_pk_fma_f32 v[108:109], v[10:11], v[68:69], v[108:109] op_sel_hi:[1,0,1]
	v_pk_fma_f32 v[112:113], v[10:11], v[76:77], v[112:113] op_sel_hi:[1,0,1]
	v_pk_fma_f32 v[108:109], v[12:13], v[68:69], v[108:109] op_sel:[0,1,0]
	v_pk_fma_f32 v[112:113], v[12:13], v[76:77], v[112:113] op_sel:[0,1,0]
	ds_read_b128 v[28:31], v225 offset:37376
	v_pk_fma_f32 v[108:109], v[14:15], v[70:71], v[108:109] op_sel_hi:[1,0,1]
	v_pk_fma_f32 v[112:113], v[14:15], v[78:79], v[112:113] op_sel_hi:[1,0,1]
	v_pk_fma_f32 v[108:109], v[16:17], v[70:71], v[108:109] op_sel:[0,1,0]
	v_pk_fma_f32 v[112:113], v[16:17], v[78:79], v[112:113] op_sel:[0,1,0]
	ds_read_b128 v[32:35], v225 offset:37392
	s_waitcnt lgkmcnt(10)
	v_pk_mul_f32 v[116:117], v[104:105], v[80:81] op_sel_hi:[1,0]
	v_pk_mul_f32 v[118:119], v[104:105], v[80:81] op_sel:[0,1]
	v_pk_mul_f32 v[120:121], v[104:105], v[82:83] op_sel_hi:[1,0]
	v_pk_mul_f32 v[122:123], v[104:105], v[82:83] op_sel:[0,1]
	ds_read_b64 v[60:61], v224 offset:45568
	ds_read_b128 v[36:39], v225 offset:29184
	v_add_f32_dpp v108, v108, v108 quad_perm:[1,0,3,2] row_mask:0xf bank_mask:0xf bound_ctrl:1
	v_add_f32_dpp v109, v109, v109 quad_perm:[1,0,3,2] row_mask:0xf bank_mask:0xf bound_ctrl:1
	v_add_f32_dpp v112, v112, v112 quad_perm:[1,0,3,2] row_mask:0xf bank_mask:0xf bound_ctrl:1
	v_add_f32_dpp v113, v113, v113 quad_perm:[1,0,3,2] row_mask:0xf bank_mask:0xf bound_ctrl:1
	v_pk_mul_f32 v[124:125], v[104:105], v[84:85] op_sel_hi:[1,0]
	v_pk_mul_f32 v[126:127], v[104:105], v[84:85] op_sel:[0,1]
	v_pk_mul_f32 v[128:129], v[104:105], v[86:87] op_sel_hi:[1,0]
	v_pk_mul_f32 v[130:131], v[104:105], v[86:87] op_sel:[0,1]
	ds_read_b128 v[40:43], v225 offset:29200
	ds_read_b64 v[62:63], v134 offset:57488
	v_add_f32_dpp v108, v108, v108 quad_perm:[2,3,0,1] row_mask:0xf bank_mask:0xf bound_ctrl:1
	v_add_f32_dpp v109, v109, v109 quad_perm:[2,3,0,1] row_mask:0xf bank_mask:0xf bound_ctrl:1
	v_add_f32_dpp v112, v112, v112 quad_perm:[2,3,0,1] row_mask:0xf bank_mask:0xf bound_ctrl:1
	v_add_f32_dpp v113, v113, v113 quad_perm:[2,3,0,1] row_mask:0xf bank_mask:0xf bound_ctrl:1
	ds_read_b128 v[44:47], v225 offset:20992
	v_add_f32_dpp v108, v108, v108 row_half_mirror row_mask:0xf bank_mask:0xf bound_ctrl:1
	v_add_f32_dpp v109, v109, v109 row_half_mirror row_mask:0xf bank_mask:0xf bound_ctrl:1
	v_add_f32_dpp v112, v112, v112 row_half_mirror row_mask:0xf bank_mask:0xf bound_ctrl:1
	v_add_f32_dpp v113, v113, v113 row_half_mirror row_mask:0xf bank_mask:0xf bound_ctrl:1
	ds_read_b128 v[48:51], v225 offset:21008
	s_waitcnt lgkmcnt(11)
	v_pk_fma_f32 v[116:117], v[108:109], v[88:89], v[116:117] op_sel_hi:[1,0,1] neg_lo:[1,0,0] neg_hi:[1,0,0]
	v_pk_fma_f32 v[118:119], v[108:109], v[88:89], v[118:119] op_sel:[0,1,0] neg_lo:[1,0,0] neg_hi:[1,0,0]
	v_pk_fma_f32 v[120:121], v[108:109], v[90:91], v[120:121] op_sel_hi:[1,0,1] neg_lo:[1,0,0] neg_hi:[1,0,0]
	v_pk_fma_f32 v[122:123], v[108:109], v[90:91], v[122:123] op_sel:[0,1,0] neg_lo:[1,0,0] neg_hi:[1,0,0]
	v_pk_fma_f32 v[124:125], v[108:109], v[92:93], v[124:125] op_sel_hi:[1,0,1] neg_lo:[1,0,0] neg_hi:[1,0,0]
	v_pk_fma_f32 v[126:127], v[108:109], v[92:93], v[126:127] op_sel:[0,1,0] neg_lo:[1,0,0] neg_hi:[1,0,0]
	v_pk_fma_f32 v[128:129], v[108:109], v[94:95], v[128:129] op_sel_hi:[1,0,1] neg_lo:[1,0,0] neg_hi:[1,0,0]
	v_pk_fma_f32 v[130:131], v[108:109], v[94:95], v[130:131] op_sel:[0,1,0] neg_lo:[1,0,0] neg_hi:[1,0,0]
	ds_read_b128 v[52:55], v225 offset:12800
	v_pk_fma_f32 v[132:133], v[108:109], v[106:107], v[112:113] op_sel_hi:[1,0,1] neg_lo:[1,0,0] neg_hi:[1,0,0]
	ds_read_b128 v[56:59], v225 offset:12816
	v_pk_fma_f32 v[2:3], v[2:3], v[96:97], v[116:117] op_sel_hi:[1,0,1]
	v_pk_fma_f32 v[4:5], v[4:5], v[96:97], v[118:119] op_sel:[0,1,0]
	v_pk_fma_f32 v[6:7], v[6:7], v[98:99], v[120:121] op_sel_hi:[1,0,1]
	v_pk_fma_f32 v[8:9], v[8:9], v[98:99], v[122:123] op_sel:[0,1,0]
	v_pk_fma_f32 v[132:133], v[104:105], v[106:107], v[132:133] op_sel:[0,1,0]
	v_pk_fma_f32 v[10:11], v[10:11], v[100:101], v[124:125] op_sel_hi:[1,0,1]
	v_pk_fma_f32 v[12:13], v[12:13], v[100:101], v[126:127] op_sel:[0,1,0]
	v_pk_fma_f32 v[14:15], v[14:15], v[102:103], v[128:129] op_sel_hi:[1,0,1]
	v_pk_fma_f32 v[16:17], v[16:17], v[102:103], v[130:131] op_sel:[0,1,0]
	ds_write_b64 v135, v[132:133] offset:53504
	s_waitcnt lgkmcnt(9)
	v_pk_mul_f32 v[108:109], v[2:3], v[20:21] op_sel_hi:[1,0]
	v_pk_mul_f32 v[112:113], v[2:3], v[28:29] op_sel_hi:[1,0]
	v_pk_fma_f32 v[108:109], v[4:5], v[20:21], v[108:109] op_sel:[0,1,0]
	v_pk_fma_f32 v[112:113], v[4:5], v[28:29], v[112:113] op_sel:[0,1,0]
	ds_read_b128 v[64:67], v225 offset:4864
	v_pk_fma_f32 v[108:109], v[6:7], v[22:23], v[108:109] op_sel_hi:[1,0,1]
	v_pk_fma_f32 v[112:113], v[6:7], v[30:31], v[112:113] op_sel_hi:[1,0,1]
	v_pk_fma_f32 v[108:109], v[8:9], v[22:23], v[108:109] op_sel:[0,1,0]
	v_pk_fma_f32 v[112:113], v[8:9], v[30:31], v[112:113] op_sel:[0,1,0]
	ds_read_b128 v[68:71], v225 offset:4880
	v_pk_fma_f32 v[108:109], v[10:11], v[24:25], v[108:109] op_sel_hi:[1,0,1]
	v_pk_fma_f32 v[112:113], v[10:11], v[32:33], v[112:113] op_sel_hi:[1,0,1]
	v_pk_fma_f32 v[108:109], v[12:13], v[24:25], v[108:109] op_sel:[0,1,0]
	v_pk_fma_f32 v[112:113], v[12:13], v[32:33], v[112:113] op_sel:[0,1,0]
	ds_read_b128 v[72:75], v225 offset:37632
	v_pk_fma_f32 v[108:109], v[14:15], v[26:27], v[108:109] op_sel_hi:[1,0,1]
	v_pk_fma_f32 v[112:113], v[14:15], v[34:35], v[112:113] op_sel_hi:[1,0,1]
	v_pk_fma_f32 v[108:109], v[16:17], v[26:27], v[108:109] op_sel:[0,1,0]
	v_pk_fma_f32 v[112:113], v[16:17], v[34:35], v[112:113] op_sel:[0,1,0]
	ds_read_b128 v[76:79], v225 offset:37648
	s_waitcnt lgkmcnt(10)
	v_pk_mul_f32 v[116:117], v[60:61], v[36:37] op_sel_hi:[1,0]
	v_pk_mul_f32 v[118:119], v[60:61], v[36:37] op_sel:[0,1]
	v_pk_mul_f32 v[120:121], v[60:61], v[38:39] op_sel_hi:[1,0]
	v_pk_mul_f32 v[122:123], v[60:61], v[38:39] op_sel:[0,1]
	ds_read_b64 v[104:105], v224 offset:45824
	ds_read_b128 v[80:83], v225 offset:29440
	v_add_f32_dpp v108, v108, v108 quad_perm:[1,0,3,2] row_mask:0xf bank_mask:0xf bound_ctrl:1
	v_add_f32_dpp v109, v109, v109 quad_perm:[1,0,3,2] row_mask:0xf bank_mask:0xf bound_ctrl:1
	v_add_f32_dpp v112, v112, v112 quad_perm:[1,0,3,2] row_mask:0xf bank_mask:0xf bound_ctrl:1
	v_add_f32_dpp v113, v113, v113 quad_perm:[1,0,3,2] row_mask:0xf bank_mask:0xf bound_ctrl:1
	v_pk_mul_f32 v[124:125], v[60:61], v[40:41] op_sel_hi:[1,0]
	v_pk_mul_f32 v[126:127], v[60:61], v[40:41] op_sel:[0,1]
	v_pk_mul_f32 v[128:129], v[60:61], v[42:43] op_sel_hi:[1,0]
	v_pk_mul_f32 v[130:131], v[60:61], v[42:43] op_sel:[0,1]
	ds_read_b128 v[84:87], v225 offset:29456
	ds_read_b64 v[106:107], v134 offset:57496
	v_add_f32_dpp v108, v108, v108 quad_perm:[2,3,0,1] row_mask:0xf bank_mask:0xf bound_ctrl:1
	v_add_f32_dpp v109, v109, v109 quad_perm:[2,3,0,1] row_mask:0xf bank_mask:0xf bound_ctrl:1
	v_add_f32_dpp v112, v112, v112 quad_perm:[2,3,0,1] row_mask:0xf bank_mask:0xf bound_ctrl:1
	v_add_f32_dpp v113, v113, v113 quad_perm:[2,3,0,1] row_mask:0xf bank_mask:0xf bound_ctrl:1
	ds_read_b128 v[88:91], v225 offset:21248
	v_add_f32_dpp v108, v108, v108 row_half_mirror row_mask:0xf bank_mask:0xf bound_ctrl:1
	v_add_f32_dpp v109, v109, v109 row_half_mirror row_mask:0xf bank_mask:0xf bound_ctrl:1
	v_add_f32_dpp v112, v112, v112 row_half_mirror row_mask:0xf bank_mask:0xf bound_ctrl:1
	v_add_f32_dpp v113, v113, v113 row_half_mirror row_mask:0xf bank_mask:0xf bound_ctrl:1
	ds_read_b128 v[92:95], v225 offset:21264
	s_waitcnt lgkmcnt(11)
	v_pk_fma_f32 v[116:117], v[108:109], v[44:45], v[116:117] op_sel_hi:[1,0,1] neg_lo:[1,0,0] neg_hi:[1,0,0]
	v_pk_fma_f32 v[118:119], v[108:109], v[44:45], v[118:119] op_sel:[0,1,0] neg_lo:[1,0,0] neg_hi:[1,0,0]
	v_pk_fma_f32 v[120:121], v[108:109], v[46:47], v[120:121] op_sel_hi:[1,0,1] neg_lo:[1,0,0] neg_hi:[1,0,0]
	v_pk_fma_f32 v[122:123], v[108:109], v[46:47], v[122:123] op_sel:[0,1,0] neg_lo:[1,0,0] neg_hi:[1,0,0]
	v_pk_fma_f32 v[124:125], v[108:109], v[48:49], v[124:125] op_sel_hi:[1,0,1] neg_lo:[1,0,0] neg_hi:[1,0,0]
	v_pk_fma_f32 v[126:127], v[108:109], v[48:49], v[126:127] op_sel:[0,1,0] neg_lo:[1,0,0] neg_hi:[1,0,0]
	v_pk_fma_f32 v[128:129], v[108:109], v[50:51], v[128:129] op_sel_hi:[1,0,1] neg_lo:[1,0,0] neg_hi:[1,0,0]
	v_pk_fma_f32 v[130:131], v[108:109], v[50:51], v[130:131] op_sel:[0,1,0] neg_lo:[1,0,0] neg_hi:[1,0,0]
	ds_read_b128 v[96:99], v225 offset:13056
	v_pk_fma_f32 v[132:133], v[108:109], v[62:63], v[112:113] op_sel_hi:[1,0,1] neg_lo:[1,0,0] neg_hi:[1,0,0]
	ds_read_b128 v[100:103], v225 offset:13072
	v_pk_fma_f32 v[2:3], v[2:3], v[52:53], v[116:117] op_sel_hi:[1,0,1]
	v_pk_fma_f32 v[4:5], v[4:5], v[52:53], v[118:119] op_sel:[0,1,0]
	v_pk_fma_f32 v[6:7], v[6:7], v[54:55], v[120:121] op_sel_hi:[1,0,1]
	v_pk_fma_f32 v[8:9], v[8:9], v[54:55], v[122:123] op_sel:[0,1,0]
	v_pk_fma_f32 v[132:133], v[60:61], v[62:63], v[132:133] op_sel:[0,1,0]
	v_pk_fma_f32 v[10:11], v[10:11], v[56:57], v[124:125] op_sel_hi:[1,0,1]
	v_pk_fma_f32 v[12:13], v[12:13], v[56:57], v[126:127] op_sel:[0,1,0]
	v_pk_fma_f32 v[14:15], v[14:15], v[58:59], v[128:129] op_sel_hi:[1,0,1]
	v_pk_fma_f32 v[16:17], v[16:17], v[58:59], v[130:131] op_sel:[0,1,0]
	ds_write_b64 v135, v[132:133] offset:53760
	s_waitcnt lgkmcnt(9)
	v_pk_mul_f32 v[108:109], v[2:3], v[64:65] op_sel_hi:[1,0]
	v_pk_mul_f32 v[112:113], v[2:3], v[72:73] op_sel_hi:[1,0]
	v_pk_fma_f32 v[108:109], v[4:5], v[64:65], v[108:109] op_sel:[0,1,0]
	v_pk_fma_f32 v[112:113], v[4:5], v[72:73], v[112:113] op_sel:[0,1,0]
	ds_read_b128 v[20:23], v225 offset:5120
	v_pk_fma_f32 v[108:109], v[6:7], v[66:67], v[108:109] op_sel_hi:[1,0,1]
	v_pk_fma_f32 v[112:113], v[6:7], v[74:75], v[112:113] op_sel_hi:[1,0,1]
	v_pk_fma_f32 v[108:109], v[8:9], v[66:67], v[108:109] op_sel:[0,1,0]
	v_pk_fma_f32 v[112:113], v[8:9], v[74:75], v[112:113] op_sel:[0,1,0]
	ds_read_b128 v[24:27], v225 offset:5136
	v_pk_fma_f32 v[108:109], v[10:11], v[68:69], v[108:109] op_sel_hi:[1,0,1]
	v_pk_fma_f32 v[112:113], v[10:11], v[76:77], v[112:113] op_sel_hi:[1,0,1]
	v_pk_fma_f32 v[108:109], v[12:13], v[68:69], v[108:109] op_sel:[0,1,0]
	v_pk_fma_f32 v[112:113], v[12:13], v[76:77], v[112:113] op_sel:[0,1,0]
	ds_read_b128 v[28:31], v225 offset:37888
	v_pk_fma_f32 v[108:109], v[14:15], v[70:71], v[108:109] op_sel_hi:[1,0,1]
	v_pk_fma_f32 v[112:113], v[14:15], v[78:79], v[112:113] op_sel_hi:[1,0,1]
	v_pk_fma_f32 v[108:109], v[16:17], v[70:71], v[108:109] op_sel:[0,1,0]
	v_pk_fma_f32 v[112:113], v[16:17], v[78:79], v[112:113] op_sel:[0,1,0]
	ds_read_b128 v[32:35], v225 offset:37904
	s_waitcnt lgkmcnt(10)
	v_pk_mul_f32 v[116:117], v[104:105], v[80:81] op_sel_hi:[1,0]
	v_pk_mul_f32 v[118:119], v[104:105], v[80:81] op_sel:[0,1]
	v_pk_mul_f32 v[120:121], v[104:105], v[82:83] op_sel_hi:[1,0]
	v_pk_mul_f32 v[122:123], v[104:105], v[82:83] op_sel:[0,1]
	ds_read_b64 v[60:61], v224 offset:46080
	ds_read_b128 v[36:39], v225 offset:29696
	v_add_f32_dpp v108, v108, v108 quad_perm:[1,0,3,2] row_mask:0xf bank_mask:0xf bound_ctrl:1
	v_add_f32_dpp v109, v109, v109 quad_perm:[1,0,3,2] row_mask:0xf bank_mask:0xf bound_ctrl:1
	v_add_f32_dpp v112, v112, v112 quad_perm:[1,0,3,2] row_mask:0xf bank_mask:0xf bound_ctrl:1
	v_add_f32_dpp v113, v113, v113 quad_perm:[1,0,3,2] row_mask:0xf bank_mask:0xf bound_ctrl:1
	v_pk_mul_f32 v[124:125], v[104:105], v[84:85] op_sel_hi:[1,0]
	v_pk_mul_f32 v[126:127], v[104:105], v[84:85] op_sel:[0,1]
	v_pk_mul_f32 v[128:129], v[104:105], v[86:87] op_sel_hi:[1,0]
	v_pk_mul_f32 v[130:131], v[104:105], v[86:87] op_sel:[0,1]
	ds_read_b128 v[40:43], v225 offset:29712
	ds_read_b64 v[62:63], v134 offset:57504
	v_add_f32_dpp v108, v108, v108 quad_perm:[2,3,0,1] row_mask:0xf bank_mask:0xf bound_ctrl:1
	v_add_f32_dpp v109, v109, v109 quad_perm:[2,3,0,1] row_mask:0xf bank_mask:0xf bound_ctrl:1
	v_add_f32_dpp v112, v112, v112 quad_perm:[2,3,0,1] row_mask:0xf bank_mask:0xf bound_ctrl:1
	v_add_f32_dpp v113, v113, v113 quad_perm:[2,3,0,1] row_mask:0xf bank_mask:0xf bound_ctrl:1
	ds_read_b128 v[44:47], v225 offset:21504
	v_add_f32_dpp v108, v108, v108 row_half_mirror row_mask:0xf bank_mask:0xf bound_ctrl:1
	v_add_f32_dpp v109, v109, v109 row_half_mirror row_mask:0xf bank_mask:0xf bound_ctrl:1
	v_add_f32_dpp v112, v112, v112 row_half_mirror row_mask:0xf bank_mask:0xf bound_ctrl:1
	v_add_f32_dpp v113, v113, v113 row_half_mirror row_mask:0xf bank_mask:0xf bound_ctrl:1
	ds_read_b128 v[48:51], v225 offset:21520
	s_waitcnt lgkmcnt(11)
	v_pk_fma_f32 v[116:117], v[108:109], v[88:89], v[116:117] op_sel_hi:[1,0,1] neg_lo:[1,0,0] neg_hi:[1,0,0]
	v_pk_fma_f32 v[118:119], v[108:109], v[88:89], v[118:119] op_sel:[0,1,0] neg_lo:[1,0,0] neg_hi:[1,0,0]
	v_pk_fma_f32 v[120:121], v[108:109], v[90:91], v[120:121] op_sel_hi:[1,0,1] neg_lo:[1,0,0] neg_hi:[1,0,0]
	v_pk_fma_f32 v[122:123], v[108:109], v[90:91], v[122:123] op_sel:[0,1,0] neg_lo:[1,0,0] neg_hi:[1,0,0]
	v_pk_fma_f32 v[124:125], v[108:109], v[92:93], v[124:125] op_sel_hi:[1,0,1] neg_lo:[1,0,0] neg_hi:[1,0,0]
	v_pk_fma_f32 v[126:127], v[108:109], v[92:93], v[126:127] op_sel:[0,1,0] neg_lo:[1,0,0] neg_hi:[1,0,0]
	v_pk_fma_f32 v[128:129], v[108:109], v[94:95], v[128:129] op_sel_hi:[1,0,1] neg_lo:[1,0,0] neg_hi:[1,0,0]
	v_pk_fma_f32 v[130:131], v[108:109], v[94:95], v[130:131] op_sel:[0,1,0] neg_lo:[1,0,0] neg_hi:[1,0,0]
	ds_read_b128 v[52:55], v225 offset:13312
	v_pk_fma_f32 v[132:133], v[108:109], v[106:107], v[112:113] op_sel_hi:[1,0,1] neg_lo:[1,0,0] neg_hi:[1,0,0]
	ds_read_b128 v[56:59], v225 offset:13328
	v_pk_fma_f32 v[2:3], v[2:3], v[96:97], v[116:117] op_sel_hi:[1,0,1]
	v_pk_fma_f32 v[4:5], v[4:5], v[96:97], v[118:119] op_sel:[0,1,0]
	v_pk_fma_f32 v[6:7], v[6:7], v[98:99], v[120:121] op_sel_hi:[1,0,1]
	v_pk_fma_f32 v[8:9], v[8:9], v[98:99], v[122:123] op_sel:[0,1,0]
	v_pk_fma_f32 v[132:133], v[104:105], v[106:107], v[132:133] op_sel:[0,1,0]
	v_pk_fma_f32 v[10:11], v[10:11], v[100:101], v[124:125] op_sel_hi:[1,0,1]
	v_pk_fma_f32 v[12:13], v[12:13], v[100:101], v[126:127] op_sel:[0,1,0]
	v_pk_fma_f32 v[14:15], v[14:15], v[102:103], v[128:129] op_sel_hi:[1,0,1]
	v_pk_fma_f32 v[16:17], v[16:17], v[102:103], v[130:131] op_sel:[0,1,0]
	ds_write_b64 v135, v[132:133] offset:54016
	s_waitcnt lgkmcnt(9)
	v_pk_mul_f32 v[108:109], v[2:3], v[20:21] op_sel_hi:[1,0]
	v_pk_mul_f32 v[112:113], v[2:3], v[28:29] op_sel_hi:[1,0]
	v_pk_fma_f32 v[108:109], v[4:5], v[20:21], v[108:109] op_sel:[0,1,0]
	v_pk_fma_f32 v[112:113], v[4:5], v[28:29], v[112:113] op_sel:[0,1,0]
	ds_read_b128 v[64:67], v225 offset:5376
	v_pk_fma_f32 v[108:109], v[6:7], v[22:23], v[108:109] op_sel_hi:[1,0,1]
	v_pk_fma_f32 v[112:113], v[6:7], v[30:31], v[112:113] op_sel_hi:[1,0,1]
	v_pk_fma_f32 v[108:109], v[8:9], v[22:23], v[108:109] op_sel:[0,1,0]
	v_pk_fma_f32 v[112:113], v[8:9], v[30:31], v[112:113] op_sel:[0,1,0]
	ds_read_b128 v[68:71], v225 offset:5392
	v_pk_fma_f32 v[108:109], v[10:11], v[24:25], v[108:109] op_sel_hi:[1,0,1]
	v_pk_fma_f32 v[112:113], v[10:11], v[32:33], v[112:113] op_sel_hi:[1,0,1]
	v_pk_fma_f32 v[108:109], v[12:13], v[24:25], v[108:109] op_sel:[0,1,0]
	v_pk_fma_f32 v[112:113], v[12:13], v[32:33], v[112:113] op_sel:[0,1,0]
	ds_read_b128 v[72:75], v225 offset:38144
	v_pk_fma_f32 v[108:109], v[14:15], v[26:27], v[108:109] op_sel_hi:[1,0,1]
	v_pk_fma_f32 v[112:113], v[14:15], v[34:35], v[112:113] op_sel_hi:[1,0,1]
	v_pk_fma_f32 v[108:109], v[16:17], v[26:27], v[108:109] op_sel:[0,1,0]
	v_pk_fma_f32 v[112:113], v[16:17], v[34:35], v[112:113] op_sel:[0,1,0]
	ds_read_b128 v[76:79], v225 offset:38160
	s_waitcnt lgkmcnt(10)
	v_pk_mul_f32 v[116:117], v[60:61], v[36:37] op_sel_hi:[1,0]
	v_pk_mul_f32 v[118:119], v[60:61], v[36:37] op_sel:[0,1]
	v_pk_mul_f32 v[120:121], v[60:61], v[38:39] op_sel_hi:[1,0]
	v_pk_mul_f32 v[122:123], v[60:61], v[38:39] op_sel:[0,1]
	ds_read_b64 v[104:105], v224 offset:46336
	ds_read_b128 v[80:83], v225 offset:29952
	v_add_f32_dpp v108, v108, v108 quad_perm:[1,0,3,2] row_mask:0xf bank_mask:0xf bound_ctrl:1
	v_add_f32_dpp v109, v109, v109 quad_perm:[1,0,3,2] row_mask:0xf bank_mask:0xf bound_ctrl:1
	v_add_f32_dpp v112, v112, v112 quad_perm:[1,0,3,2] row_mask:0xf bank_mask:0xf bound_ctrl:1
	v_add_f32_dpp v113, v113, v113 quad_perm:[1,0,3,2] row_mask:0xf bank_mask:0xf bound_ctrl:1
	v_pk_mul_f32 v[124:125], v[60:61], v[40:41] op_sel_hi:[1,0]
	v_pk_mul_f32 v[126:127], v[60:61], v[40:41] op_sel:[0,1]
	v_pk_mul_f32 v[128:129], v[60:61], v[42:43] op_sel_hi:[1,0]
	v_pk_mul_f32 v[130:131], v[60:61], v[42:43] op_sel:[0,1]
	ds_read_b128 v[84:87], v225 offset:29968
	ds_read_b64 v[106:107], v134 offset:57512
	v_add_f32_dpp v108, v108, v108 quad_perm:[2,3,0,1] row_mask:0xf bank_mask:0xf bound_ctrl:1
	v_add_f32_dpp v109, v109, v109 quad_perm:[2,3,0,1] row_mask:0xf bank_mask:0xf bound_ctrl:1
	v_add_f32_dpp v112, v112, v112 quad_perm:[2,3,0,1] row_mask:0xf bank_mask:0xf bound_ctrl:1
	v_add_f32_dpp v113, v113, v113 quad_perm:[2,3,0,1] row_mask:0xf bank_mask:0xf bound_ctrl:1
	ds_read_b128 v[88:91], v225 offset:21760
	v_add_f32_dpp v108, v108, v108 row_half_mirror row_mask:0xf bank_mask:0xf bound_ctrl:1
	v_add_f32_dpp v109, v109, v109 row_half_mirror row_mask:0xf bank_mask:0xf bound_ctrl:1
	v_add_f32_dpp v112, v112, v112 row_half_mirror row_mask:0xf bank_mask:0xf bound_ctrl:1
	v_add_f32_dpp v113, v113, v113 row_half_mirror row_mask:0xf bank_mask:0xf bound_ctrl:1
	ds_read_b128 v[92:95], v225 offset:21776
	s_waitcnt lgkmcnt(11)
	v_pk_fma_f32 v[116:117], v[108:109], v[44:45], v[116:117] op_sel_hi:[1,0,1] neg_lo:[1,0,0] neg_hi:[1,0,0]
	v_pk_fma_f32 v[118:119], v[108:109], v[44:45], v[118:119] op_sel:[0,1,0] neg_lo:[1,0,0] neg_hi:[1,0,0]
	v_pk_fma_f32 v[120:121], v[108:109], v[46:47], v[120:121] op_sel_hi:[1,0,1] neg_lo:[1,0,0] neg_hi:[1,0,0]
	v_pk_fma_f32 v[122:123], v[108:109], v[46:47], v[122:123] op_sel:[0,1,0] neg_lo:[1,0,0] neg_hi:[1,0,0]
	v_pk_fma_f32 v[124:125], v[108:109], v[48:49], v[124:125] op_sel_hi:[1,0,1] neg_lo:[1,0,0] neg_hi:[1,0,0]
	v_pk_fma_f32 v[126:127], v[108:109], v[48:49], v[126:127] op_sel:[0,1,0] neg_lo:[1,0,0] neg_hi:[1,0,0]
	v_pk_fma_f32 v[128:129], v[108:109], v[50:51], v[128:129] op_sel_hi:[1,0,1] neg_lo:[1,0,0] neg_hi:[1,0,0]
	v_pk_fma_f32 v[130:131], v[108:109], v[50:51], v[130:131] op_sel:[0,1,0] neg_lo:[1,0,0] neg_hi:[1,0,0]
	ds_read_b128 v[96:99], v225 offset:13568
	v_pk_fma_f32 v[132:133], v[108:109], v[62:63], v[112:113] op_sel_hi:[1,0,1] neg_lo:[1,0,0] neg_hi:[1,0,0]
	ds_read_b128 v[100:103], v225 offset:13584
	v_pk_fma_f32 v[2:3], v[2:3], v[52:53], v[116:117] op_sel_hi:[1,0,1]
	v_pk_fma_f32 v[4:5], v[4:5], v[52:53], v[118:119] op_sel:[0,1,0]
	v_pk_fma_f32 v[6:7], v[6:7], v[54:55], v[120:121] op_sel_hi:[1,0,1]
	v_pk_fma_f32 v[8:9], v[8:9], v[54:55], v[122:123] op_sel:[0,1,0]
	v_pk_fma_f32 v[132:133], v[60:61], v[62:63], v[132:133] op_sel:[0,1,0]
	v_pk_fma_f32 v[10:11], v[10:11], v[56:57], v[124:125] op_sel_hi:[1,0,1]
	v_pk_fma_f32 v[12:13], v[12:13], v[56:57], v[126:127] op_sel:[0,1,0]
	v_pk_fma_f32 v[14:15], v[14:15], v[58:59], v[128:129] op_sel_hi:[1,0,1]
	v_pk_fma_f32 v[16:17], v[16:17], v[58:59], v[130:131] op_sel:[0,1,0]
	ds_write_b64 v135, v[132:133] offset:54272
	s_waitcnt lgkmcnt(9)
	v_pk_mul_f32 v[108:109], v[2:3], v[64:65] op_sel_hi:[1,0]
	v_pk_mul_f32 v[112:113], v[2:3], v[72:73] op_sel_hi:[1,0]
	v_pk_fma_f32 v[108:109], v[4:5], v[64:65], v[108:109] op_sel:[0,1,0]
	v_pk_fma_f32 v[112:113], v[4:5], v[72:73], v[112:113] op_sel:[0,1,0]
	ds_read_b128 v[20:23], v225 offset:5632
	v_pk_fma_f32 v[108:109], v[6:7], v[66:67], v[108:109] op_sel_hi:[1,0,1]
	v_pk_fma_f32 v[112:113], v[6:7], v[74:75], v[112:113] op_sel_hi:[1,0,1]
	v_pk_fma_f32 v[108:109], v[8:9], v[66:67], v[108:109] op_sel:[0,1,0]
	v_pk_fma_f32 v[112:113], v[8:9], v[74:75], v[112:113] op_sel:[0,1,0]
	ds_read_b128 v[24:27], v225 offset:5648
	v_pk_fma_f32 v[108:109], v[10:11], v[68:69], v[108:109] op_sel_hi:[1,0,1]
	v_pk_fma_f32 v[112:113], v[10:11], v[76:77], v[112:113] op_sel_hi:[1,0,1]
	v_pk_fma_f32 v[108:109], v[12:13], v[68:69], v[108:109] op_sel:[0,1,0]
	v_pk_fma_f32 v[112:113], v[12:13], v[76:77], v[112:113] op_sel:[0,1,0]
	ds_read_b128 v[28:31], v225 offset:38400
	v_pk_fma_f32 v[108:109], v[14:15], v[70:71], v[108:109] op_sel_hi:[1,0,1]
	v_pk_fma_f32 v[112:113], v[14:15], v[78:79], v[112:113] op_sel_hi:[1,0,1]
	v_pk_fma_f32 v[108:109], v[16:17], v[70:71], v[108:109] op_sel:[0,1,0]
	v_pk_fma_f32 v[112:113], v[16:17], v[78:79], v[112:113] op_sel:[0,1,0]
	ds_read_b128 v[32:35], v225 offset:38416
	s_waitcnt lgkmcnt(10)
	v_pk_mul_f32 v[116:117], v[104:105], v[80:81] op_sel_hi:[1,0]
	v_pk_mul_f32 v[118:119], v[104:105], v[80:81] op_sel:[0,1]
	v_pk_mul_f32 v[120:121], v[104:105], v[82:83] op_sel_hi:[1,0]
	v_pk_mul_f32 v[122:123], v[104:105], v[82:83] op_sel:[0,1]
	ds_read_b64 v[60:61], v224 offset:46592
	ds_read_b128 v[36:39], v225 offset:30208
	v_add_f32_dpp v108, v108, v108 quad_perm:[1,0,3,2] row_mask:0xf bank_mask:0xf bound_ctrl:1
	v_add_f32_dpp v109, v109, v109 quad_perm:[1,0,3,2] row_mask:0xf bank_mask:0xf bound_ctrl:1
	v_add_f32_dpp v112, v112, v112 quad_perm:[1,0,3,2] row_mask:0xf bank_mask:0xf bound_ctrl:1
	v_add_f32_dpp v113, v113, v113 quad_perm:[1,0,3,2] row_mask:0xf bank_mask:0xf bound_ctrl:1
	v_pk_mul_f32 v[124:125], v[104:105], v[84:85] op_sel_hi:[1,0]
	v_pk_mul_f32 v[126:127], v[104:105], v[84:85] op_sel:[0,1]
	v_pk_mul_f32 v[128:129], v[104:105], v[86:87] op_sel_hi:[1,0]
	v_pk_mul_f32 v[130:131], v[104:105], v[86:87] op_sel:[0,1]
	ds_read_b128 v[40:43], v225 offset:30224
	ds_read_b64 v[62:63], v134 offset:57520
	v_add_f32_dpp v108, v108, v108 quad_perm:[2,3,0,1] row_mask:0xf bank_mask:0xf bound_ctrl:1
	v_add_f32_dpp v109, v109, v109 quad_perm:[2,3,0,1] row_mask:0xf bank_mask:0xf bound_ctrl:1
	v_add_f32_dpp v112, v112, v112 quad_perm:[2,3,0,1] row_mask:0xf bank_mask:0xf bound_ctrl:1
	v_add_f32_dpp v113, v113, v113 quad_perm:[2,3,0,1] row_mask:0xf bank_mask:0xf bound_ctrl:1
	ds_read_b128 v[44:47], v225 offset:22016
	v_add_f32_dpp v108, v108, v108 row_half_mirror row_mask:0xf bank_mask:0xf bound_ctrl:1
	v_add_f32_dpp v109, v109, v109 row_half_mirror row_mask:0xf bank_mask:0xf bound_ctrl:1
	v_add_f32_dpp v112, v112, v112 row_half_mirror row_mask:0xf bank_mask:0xf bound_ctrl:1
	v_add_f32_dpp v113, v113, v113 row_half_mirror row_mask:0xf bank_mask:0xf bound_ctrl:1
	ds_read_b128 v[48:51], v225 offset:22032
	s_waitcnt lgkmcnt(11)
	v_pk_fma_f32 v[116:117], v[108:109], v[88:89], v[116:117] op_sel_hi:[1,0,1] neg_lo:[1,0,0] neg_hi:[1,0,0]
	v_pk_fma_f32 v[118:119], v[108:109], v[88:89], v[118:119] op_sel:[0,1,0] neg_lo:[1,0,0] neg_hi:[1,0,0]
	v_pk_fma_f32 v[120:121], v[108:109], v[90:91], v[120:121] op_sel_hi:[1,0,1] neg_lo:[1,0,0] neg_hi:[1,0,0]
	v_pk_fma_f32 v[122:123], v[108:109], v[90:91], v[122:123] op_sel:[0,1,0] neg_lo:[1,0,0] neg_hi:[1,0,0]
	v_pk_fma_f32 v[124:125], v[108:109], v[92:93], v[124:125] op_sel_hi:[1,0,1] neg_lo:[1,0,0] neg_hi:[1,0,0]
	v_pk_fma_f32 v[126:127], v[108:109], v[92:93], v[126:127] op_sel:[0,1,0] neg_lo:[1,0,0] neg_hi:[1,0,0]
	v_pk_fma_f32 v[128:129], v[108:109], v[94:95], v[128:129] op_sel_hi:[1,0,1] neg_lo:[1,0,0] neg_hi:[1,0,0]
	v_pk_fma_f32 v[130:131], v[108:109], v[94:95], v[130:131] op_sel:[0,1,0] neg_lo:[1,0,0] neg_hi:[1,0,0]
	ds_read_b128 v[52:55], v225 offset:13824
	v_pk_fma_f32 v[132:133], v[108:109], v[106:107], v[112:113] op_sel_hi:[1,0,1] neg_lo:[1,0,0] neg_hi:[1,0,0]
	ds_read_b128 v[56:59], v225 offset:13840
	v_pk_fma_f32 v[2:3], v[2:3], v[96:97], v[116:117] op_sel_hi:[1,0,1]
	v_pk_fma_f32 v[4:5], v[4:5], v[96:97], v[118:119] op_sel:[0,1,0]
	v_pk_fma_f32 v[6:7], v[6:7], v[98:99], v[120:121] op_sel_hi:[1,0,1]
	v_pk_fma_f32 v[8:9], v[8:9], v[98:99], v[122:123] op_sel:[0,1,0]
	v_pk_fma_f32 v[132:133], v[104:105], v[106:107], v[132:133] op_sel:[0,1,0]
	v_pk_fma_f32 v[10:11], v[10:11], v[100:101], v[124:125] op_sel_hi:[1,0,1]
	v_pk_fma_f32 v[12:13], v[12:13], v[100:101], v[126:127] op_sel:[0,1,0]
	v_pk_fma_f32 v[14:15], v[14:15], v[102:103], v[128:129] op_sel_hi:[1,0,1]
	v_pk_fma_f32 v[16:17], v[16:17], v[102:103], v[130:131] op_sel:[0,1,0]
	ds_write_b64 v135, v[132:133] offset:54528
	s_waitcnt lgkmcnt(9)
	v_pk_mul_f32 v[108:109], v[2:3], v[20:21] op_sel_hi:[1,0]
	v_pk_mul_f32 v[112:113], v[2:3], v[28:29] op_sel_hi:[1,0]
	v_pk_fma_f32 v[108:109], v[4:5], v[20:21], v[108:109] op_sel:[0,1,0]
	v_pk_fma_f32 v[112:113], v[4:5], v[28:29], v[112:113] op_sel:[0,1,0]
	ds_read_b128 v[64:67], v225 offset:5888
	v_pk_fma_f32 v[108:109], v[6:7], v[22:23], v[108:109] op_sel_hi:[1,0,1]
	v_pk_fma_f32 v[112:113], v[6:7], v[30:31], v[112:113] op_sel_hi:[1,0,1]
	v_pk_fma_f32 v[108:109], v[8:9], v[22:23], v[108:109] op_sel:[0,1,0]
	v_pk_fma_f32 v[112:113], v[8:9], v[30:31], v[112:113] op_sel:[0,1,0]
	ds_read_b128 v[68:71], v225 offset:5904
	v_pk_fma_f32 v[108:109], v[10:11], v[24:25], v[108:109] op_sel_hi:[1,0,1]
	v_pk_fma_f32 v[112:113], v[10:11], v[32:33], v[112:113] op_sel_hi:[1,0,1]
	v_pk_fma_f32 v[108:109], v[12:13], v[24:25], v[108:109] op_sel:[0,1,0]
	v_pk_fma_f32 v[112:113], v[12:13], v[32:33], v[112:113] op_sel:[0,1,0]
	ds_read_b128 v[72:75], v225 offset:38656
	v_pk_fma_f32 v[108:109], v[14:15], v[26:27], v[108:109] op_sel_hi:[1,0,1]
	v_pk_fma_f32 v[112:113], v[14:15], v[34:35], v[112:113] op_sel_hi:[1,0,1]
	v_pk_fma_f32 v[108:109], v[16:17], v[26:27], v[108:109] op_sel:[0,1,0]
	v_pk_fma_f32 v[112:113], v[16:17], v[34:35], v[112:113] op_sel:[0,1,0]
	ds_read_b128 v[76:79], v225 offset:38672
	s_waitcnt lgkmcnt(10)
	v_pk_mul_f32 v[116:117], v[60:61], v[36:37] op_sel_hi:[1,0]
	v_pk_mul_f32 v[118:119], v[60:61], v[36:37] op_sel:[0,1]
	v_pk_mul_f32 v[120:121], v[60:61], v[38:39] op_sel_hi:[1,0]
	v_pk_mul_f32 v[122:123], v[60:61], v[38:39] op_sel:[0,1]
	ds_read_b64 v[104:105], v224 offset:46848
	ds_read_b128 v[80:83], v225 offset:30464
	v_add_f32_dpp v108, v108, v108 quad_perm:[1,0,3,2] row_mask:0xf bank_mask:0xf bound_ctrl:1
	v_add_f32_dpp v109, v109, v109 quad_perm:[1,0,3,2] row_mask:0xf bank_mask:0xf bound_ctrl:1
	v_add_f32_dpp v112, v112, v112 quad_perm:[1,0,3,2] row_mask:0xf bank_mask:0xf bound_ctrl:1
	v_add_f32_dpp v113, v113, v113 quad_perm:[1,0,3,2] row_mask:0xf bank_mask:0xf bound_ctrl:1
	v_pk_mul_f32 v[124:125], v[60:61], v[40:41] op_sel_hi:[1,0]
	v_pk_mul_f32 v[126:127], v[60:61], v[40:41] op_sel:[0,1]
	v_pk_mul_f32 v[128:129], v[60:61], v[42:43] op_sel_hi:[1,0]
	v_pk_mul_f32 v[130:131], v[60:61], v[42:43] op_sel:[0,1]
	ds_read_b128 v[84:87], v225 offset:30480
	ds_read_b64 v[106:107], v134 offset:57528
	v_add_f32_dpp v108, v108, v108 quad_perm:[2,3,0,1] row_mask:0xf bank_mask:0xf bound_ctrl:1
	v_add_f32_dpp v109, v109, v109 quad_perm:[2,3,0,1] row_mask:0xf bank_mask:0xf bound_ctrl:1
	v_add_f32_dpp v112, v112, v112 quad_perm:[2,3,0,1] row_mask:0xf bank_mask:0xf bound_ctrl:1
	v_add_f32_dpp v113, v113, v113 quad_perm:[2,3,0,1] row_mask:0xf bank_mask:0xf bound_ctrl:1
	ds_read_b128 v[88:91], v225 offset:22272
	v_add_f32_dpp v108, v108, v108 row_half_mirror row_mask:0xf bank_mask:0xf bound_ctrl:1
	v_add_f32_dpp v109, v109, v109 row_half_mirror row_mask:0xf bank_mask:0xf bound_ctrl:1
	v_add_f32_dpp v112, v112, v112 row_half_mirror row_mask:0xf bank_mask:0xf bound_ctrl:1
	v_add_f32_dpp v113, v113, v113 row_half_mirror row_mask:0xf bank_mask:0xf bound_ctrl:1
	ds_read_b128 v[92:95], v225 offset:22288
	s_waitcnt lgkmcnt(11)
	v_pk_fma_f32 v[116:117], v[108:109], v[44:45], v[116:117] op_sel_hi:[1,0,1] neg_lo:[1,0,0] neg_hi:[1,0,0]
	v_pk_fma_f32 v[118:119], v[108:109], v[44:45], v[118:119] op_sel:[0,1,0] neg_lo:[1,0,0] neg_hi:[1,0,0]
	v_pk_fma_f32 v[120:121], v[108:109], v[46:47], v[120:121] op_sel_hi:[1,0,1] neg_lo:[1,0,0] neg_hi:[1,0,0]
	v_pk_fma_f32 v[122:123], v[108:109], v[46:47], v[122:123] op_sel:[0,1,0] neg_lo:[1,0,0] neg_hi:[1,0,0]
	v_pk_fma_f32 v[124:125], v[108:109], v[48:49], v[124:125] op_sel_hi:[1,0,1] neg_lo:[1,0,0] neg_hi:[1,0,0]
	v_pk_fma_f32 v[126:127], v[108:109], v[48:49], v[126:127] op_sel:[0,1,0] neg_lo:[1,0,0] neg_hi:[1,0,0]
	v_pk_fma_f32 v[128:129], v[108:109], v[50:51], v[128:129] op_sel_hi:[1,0,1] neg_lo:[1,0,0] neg_hi:[1,0,0]
	v_pk_fma_f32 v[130:131], v[108:109], v[50:51], v[130:131] op_sel:[0,1,0] neg_lo:[1,0,0] neg_hi:[1,0,0]
	ds_read_b128 v[96:99], v225 offset:14080
	v_pk_fma_f32 v[132:133], v[108:109], v[62:63], v[112:113] op_sel_hi:[1,0,1] neg_lo:[1,0,0] neg_hi:[1,0,0]
	ds_read_b128 v[100:103], v225 offset:14096
	v_pk_fma_f32 v[2:3], v[2:3], v[52:53], v[116:117] op_sel_hi:[1,0,1]
	v_pk_fma_f32 v[4:5], v[4:5], v[52:53], v[118:119] op_sel:[0,1,0]
	v_pk_fma_f32 v[6:7], v[6:7], v[54:55], v[120:121] op_sel_hi:[1,0,1]
	v_pk_fma_f32 v[8:9], v[8:9], v[54:55], v[122:123] op_sel:[0,1,0]
	v_pk_fma_f32 v[132:133], v[60:61], v[62:63], v[132:133] op_sel:[0,1,0]
	v_pk_fma_f32 v[10:11], v[10:11], v[56:57], v[124:125] op_sel_hi:[1,0,1]
	v_pk_fma_f32 v[12:13], v[12:13], v[56:57], v[126:127] op_sel:[0,1,0]
	v_pk_fma_f32 v[14:15], v[14:15], v[58:59], v[128:129] op_sel_hi:[1,0,1]
	v_pk_fma_f32 v[16:17], v[16:17], v[58:59], v[130:131] op_sel:[0,1,0]
	ds_write_b64 v135, v[132:133] offset:54784
	s_waitcnt lgkmcnt(9)
	v_pk_mul_f32 v[108:109], v[2:3], v[64:65] op_sel_hi:[1,0]
	v_pk_mul_f32 v[112:113], v[2:3], v[72:73] op_sel_hi:[1,0]
	v_pk_fma_f32 v[108:109], v[4:5], v[64:65], v[108:109] op_sel:[0,1,0]
	v_pk_fma_f32 v[112:113], v[4:5], v[72:73], v[112:113] op_sel:[0,1,0]
	ds_read_b128 v[20:23], v225 offset:6144
	v_pk_fma_f32 v[108:109], v[6:7], v[66:67], v[108:109] op_sel_hi:[1,0,1]
	v_pk_fma_f32 v[112:113], v[6:7], v[74:75], v[112:113] op_sel_hi:[1,0,1]
	v_pk_fma_f32 v[108:109], v[8:9], v[66:67], v[108:109] op_sel:[0,1,0]
	v_pk_fma_f32 v[112:113], v[8:9], v[74:75], v[112:113] op_sel:[0,1,0]
	ds_read_b128 v[24:27], v225 offset:6160
	v_pk_fma_f32 v[108:109], v[10:11], v[68:69], v[108:109] op_sel_hi:[1,0,1]
	v_pk_fma_f32 v[112:113], v[10:11], v[76:77], v[112:113] op_sel_hi:[1,0,1]
	v_pk_fma_f32 v[108:109], v[12:13], v[68:69], v[108:109] op_sel:[0,1,0]
	v_pk_fma_f32 v[112:113], v[12:13], v[76:77], v[112:113] op_sel:[0,1,0]
	ds_read_b128 v[28:31], v225 offset:38912
	v_pk_fma_f32 v[108:109], v[14:15], v[70:71], v[108:109] op_sel_hi:[1,0,1]
	v_pk_fma_f32 v[112:113], v[14:15], v[78:79], v[112:113] op_sel_hi:[1,0,1]
	v_pk_fma_f32 v[108:109], v[16:17], v[70:71], v[108:109] op_sel:[0,1,0]
	v_pk_fma_f32 v[112:113], v[16:17], v[78:79], v[112:113] op_sel:[0,1,0]
	ds_read_b128 v[32:35], v225 offset:38928
	s_waitcnt lgkmcnt(10)
	v_pk_mul_f32 v[116:117], v[104:105], v[80:81] op_sel_hi:[1,0]
	v_pk_mul_f32 v[118:119], v[104:105], v[80:81] op_sel:[0,1]
	v_pk_mul_f32 v[120:121], v[104:105], v[82:83] op_sel_hi:[1,0]
	v_pk_mul_f32 v[122:123], v[104:105], v[82:83] op_sel:[0,1]
	ds_read_b64 v[60:61], v224 offset:47104
	ds_read_b128 v[36:39], v225 offset:30720
	v_add_f32_dpp v108, v108, v108 quad_perm:[1,0,3,2] row_mask:0xf bank_mask:0xf bound_ctrl:1
	v_add_f32_dpp v109, v109, v109 quad_perm:[1,0,3,2] row_mask:0xf bank_mask:0xf bound_ctrl:1
	v_add_f32_dpp v112, v112, v112 quad_perm:[1,0,3,2] row_mask:0xf bank_mask:0xf bound_ctrl:1
	v_add_f32_dpp v113, v113, v113 quad_perm:[1,0,3,2] row_mask:0xf bank_mask:0xf bound_ctrl:1
	v_pk_mul_f32 v[124:125], v[104:105], v[84:85] op_sel_hi:[1,0]
	v_pk_mul_f32 v[126:127], v[104:105], v[84:85] op_sel:[0,1]
	v_pk_mul_f32 v[128:129], v[104:105], v[86:87] op_sel_hi:[1,0]
	v_pk_mul_f32 v[130:131], v[104:105], v[86:87] op_sel:[0,1]
	ds_read_b128 v[40:43], v225 offset:30736
	ds_read_b64 v[62:63], v134 offset:57536
	v_add_f32_dpp v108, v108, v108 quad_perm:[2,3,0,1] row_mask:0xf bank_mask:0xf bound_ctrl:1
	v_add_f32_dpp v109, v109, v109 quad_perm:[2,3,0,1] row_mask:0xf bank_mask:0xf bound_ctrl:1
	v_add_f32_dpp v112, v112, v112 quad_perm:[2,3,0,1] row_mask:0xf bank_mask:0xf bound_ctrl:1
	v_add_f32_dpp v113, v113, v113 quad_perm:[2,3,0,1] row_mask:0xf bank_mask:0xf bound_ctrl:1
	ds_read_b128 v[44:47], v225 offset:22528
	v_add_f32_dpp v108, v108, v108 row_half_mirror row_mask:0xf bank_mask:0xf bound_ctrl:1
	v_add_f32_dpp v109, v109, v109 row_half_mirror row_mask:0xf bank_mask:0xf bound_ctrl:1
	v_add_f32_dpp v112, v112, v112 row_half_mirror row_mask:0xf bank_mask:0xf bound_ctrl:1
	v_add_f32_dpp v113, v113, v113 row_half_mirror row_mask:0xf bank_mask:0xf bound_ctrl:1
	ds_read_b128 v[48:51], v225 offset:22544
	s_waitcnt lgkmcnt(11)
	v_pk_fma_f32 v[116:117], v[108:109], v[88:89], v[116:117] op_sel_hi:[1,0,1] neg_lo:[1,0,0] neg_hi:[1,0,0]
	v_pk_fma_f32 v[118:119], v[108:109], v[88:89], v[118:119] op_sel:[0,1,0] neg_lo:[1,0,0] neg_hi:[1,0,0]
	v_pk_fma_f32 v[120:121], v[108:109], v[90:91], v[120:121] op_sel_hi:[1,0,1] neg_lo:[1,0,0] neg_hi:[1,0,0]
	v_pk_fma_f32 v[122:123], v[108:109], v[90:91], v[122:123] op_sel:[0,1,0] neg_lo:[1,0,0] neg_hi:[1,0,0]
	v_pk_fma_f32 v[124:125], v[108:109], v[92:93], v[124:125] op_sel_hi:[1,0,1] neg_lo:[1,0,0] neg_hi:[1,0,0]
	v_pk_fma_f32 v[126:127], v[108:109], v[92:93], v[126:127] op_sel:[0,1,0] neg_lo:[1,0,0] neg_hi:[1,0,0]
	v_pk_fma_f32 v[128:129], v[108:109], v[94:95], v[128:129] op_sel_hi:[1,0,1] neg_lo:[1,0,0] neg_hi:[1,0,0]
	v_pk_fma_f32 v[130:131], v[108:109], v[94:95], v[130:131] op_sel:[0,1,0] neg_lo:[1,0,0] neg_hi:[1,0,0]
	ds_read_b128 v[52:55], v225 offset:14336
	v_pk_fma_f32 v[132:133], v[108:109], v[106:107], v[112:113] op_sel_hi:[1,0,1] neg_lo:[1,0,0] neg_hi:[1,0,0]
	ds_read_b128 v[56:59], v225 offset:14352
	v_pk_fma_f32 v[2:3], v[2:3], v[96:97], v[116:117] op_sel_hi:[1,0,1]
	v_pk_fma_f32 v[4:5], v[4:5], v[96:97], v[118:119] op_sel:[0,1,0]
	v_pk_fma_f32 v[6:7], v[6:7], v[98:99], v[120:121] op_sel_hi:[1,0,1]
	v_pk_fma_f32 v[8:9], v[8:9], v[98:99], v[122:123] op_sel:[0,1,0]
	v_pk_fma_f32 v[132:133], v[104:105], v[106:107], v[132:133] op_sel:[0,1,0]
	v_pk_fma_f32 v[10:11], v[10:11], v[100:101], v[124:125] op_sel_hi:[1,0,1]
	v_pk_fma_f32 v[12:13], v[12:13], v[100:101], v[126:127] op_sel:[0,1,0]
	v_pk_fma_f32 v[14:15], v[14:15], v[102:103], v[128:129] op_sel_hi:[1,0,1]
	v_pk_fma_f32 v[16:17], v[16:17], v[102:103], v[130:131] op_sel:[0,1,0]
	ds_write_b64 v135, v[132:133] offset:55040
	s_waitcnt lgkmcnt(9)
	v_pk_mul_f32 v[108:109], v[2:3], v[20:21] op_sel_hi:[1,0]
	v_pk_mul_f32 v[112:113], v[2:3], v[28:29] op_sel_hi:[1,0]
	v_pk_fma_f32 v[108:109], v[4:5], v[20:21], v[108:109] op_sel:[0,1,0]
	v_pk_fma_f32 v[112:113], v[4:5], v[28:29], v[112:113] op_sel:[0,1,0]
	ds_read_b128 v[64:67], v225 offset:6400
	v_pk_fma_f32 v[108:109], v[6:7], v[22:23], v[108:109] op_sel_hi:[1,0,1]
	v_pk_fma_f32 v[112:113], v[6:7], v[30:31], v[112:113] op_sel_hi:[1,0,1]
	v_pk_fma_f32 v[108:109], v[8:9], v[22:23], v[108:109] op_sel:[0,1,0]
	v_pk_fma_f32 v[112:113], v[8:9], v[30:31], v[112:113] op_sel:[0,1,0]
	ds_read_b128 v[68:71], v225 offset:6416
	v_pk_fma_f32 v[108:109], v[10:11], v[24:25], v[108:109] op_sel_hi:[1,0,1]
	v_pk_fma_f32 v[112:113], v[10:11], v[32:33], v[112:113] op_sel_hi:[1,0,1]
	v_pk_fma_f32 v[108:109], v[12:13], v[24:25], v[108:109] op_sel:[0,1,0]
	v_pk_fma_f32 v[112:113], v[12:13], v[32:33], v[112:113] op_sel:[0,1,0]
	ds_read_b128 v[72:75], v225 offset:39168
	v_pk_fma_f32 v[108:109], v[14:15], v[26:27], v[108:109] op_sel_hi:[1,0,1]
	v_pk_fma_f32 v[112:113], v[14:15], v[34:35], v[112:113] op_sel_hi:[1,0,1]
	v_pk_fma_f32 v[108:109], v[16:17], v[26:27], v[108:109] op_sel:[0,1,0]
	v_pk_fma_f32 v[112:113], v[16:17], v[34:35], v[112:113] op_sel:[0,1,0]
	ds_read_b128 v[76:79], v225 offset:39184
	s_waitcnt lgkmcnt(10)
	v_pk_mul_f32 v[116:117], v[60:61], v[36:37] op_sel_hi:[1,0]
	v_pk_mul_f32 v[118:119], v[60:61], v[36:37] op_sel:[0,1]
	v_pk_mul_f32 v[120:121], v[60:61], v[38:39] op_sel_hi:[1,0]
	v_pk_mul_f32 v[122:123], v[60:61], v[38:39] op_sel:[0,1]
	ds_read_b64 v[104:105], v224 offset:47360
	ds_read_b128 v[80:83], v225 offset:30976
	v_add_f32_dpp v108, v108, v108 quad_perm:[1,0,3,2] row_mask:0xf bank_mask:0xf bound_ctrl:1
	v_add_f32_dpp v109, v109, v109 quad_perm:[1,0,3,2] row_mask:0xf bank_mask:0xf bound_ctrl:1
	v_add_f32_dpp v112, v112, v112 quad_perm:[1,0,3,2] row_mask:0xf bank_mask:0xf bound_ctrl:1
	v_add_f32_dpp v113, v113, v113 quad_perm:[1,0,3,2] row_mask:0xf bank_mask:0xf bound_ctrl:1
	v_pk_mul_f32 v[124:125], v[60:61], v[40:41] op_sel_hi:[1,0]
	v_pk_mul_f32 v[126:127], v[60:61], v[40:41] op_sel:[0,1]
	v_pk_mul_f32 v[128:129], v[60:61], v[42:43] op_sel_hi:[1,0]
	v_pk_mul_f32 v[130:131], v[60:61], v[42:43] op_sel:[0,1]
	ds_read_b128 v[84:87], v225 offset:30992
	ds_read_b64 v[106:107], v134 offset:57544
	v_add_f32_dpp v108, v108, v108 quad_perm:[2,3,0,1] row_mask:0xf bank_mask:0xf bound_ctrl:1
	v_add_f32_dpp v109, v109, v109 quad_perm:[2,3,0,1] row_mask:0xf bank_mask:0xf bound_ctrl:1
	v_add_f32_dpp v112, v112, v112 quad_perm:[2,3,0,1] row_mask:0xf bank_mask:0xf bound_ctrl:1
	v_add_f32_dpp v113, v113, v113 quad_perm:[2,3,0,1] row_mask:0xf bank_mask:0xf bound_ctrl:1
	ds_read_b128 v[88:91], v225 offset:22784
	v_add_f32_dpp v108, v108, v108 row_half_mirror row_mask:0xf bank_mask:0xf bound_ctrl:1
	v_add_f32_dpp v109, v109, v109 row_half_mirror row_mask:0xf bank_mask:0xf bound_ctrl:1
	v_add_f32_dpp v112, v112, v112 row_half_mirror row_mask:0xf bank_mask:0xf bound_ctrl:1
	v_add_f32_dpp v113, v113, v113 row_half_mirror row_mask:0xf bank_mask:0xf bound_ctrl:1
	ds_read_b128 v[92:95], v225 offset:22800
	s_waitcnt lgkmcnt(11)
	v_pk_fma_f32 v[116:117], v[108:109], v[44:45], v[116:117] op_sel_hi:[1,0,1] neg_lo:[1,0,0] neg_hi:[1,0,0]
	v_pk_fma_f32 v[118:119], v[108:109], v[44:45], v[118:119] op_sel:[0,1,0] neg_lo:[1,0,0] neg_hi:[1,0,0]
	v_pk_fma_f32 v[120:121], v[108:109], v[46:47], v[120:121] op_sel_hi:[1,0,1] neg_lo:[1,0,0] neg_hi:[1,0,0]
	v_pk_fma_f32 v[122:123], v[108:109], v[46:47], v[122:123] op_sel:[0,1,0] neg_lo:[1,0,0] neg_hi:[1,0,0]
	v_pk_fma_f32 v[124:125], v[108:109], v[48:49], v[124:125] op_sel_hi:[1,0,1] neg_lo:[1,0,0] neg_hi:[1,0,0]
	v_pk_fma_f32 v[126:127], v[108:109], v[48:49], v[126:127] op_sel:[0,1,0] neg_lo:[1,0,0] neg_hi:[1,0,0]
	v_pk_fma_f32 v[128:129], v[108:109], v[50:51], v[128:129] op_sel_hi:[1,0,1] neg_lo:[1,0,0] neg_hi:[1,0,0]
	v_pk_fma_f32 v[130:131], v[108:109], v[50:51], v[130:131] op_sel:[0,1,0] neg_lo:[1,0,0] neg_hi:[1,0,0]
	ds_read_b128 v[96:99], v225 offset:14592
	v_pk_fma_f32 v[132:133], v[108:109], v[62:63], v[112:113] op_sel_hi:[1,0,1] neg_lo:[1,0,0] neg_hi:[1,0,0]
	ds_read_b128 v[100:103], v225 offset:14608
	v_pk_fma_f32 v[2:3], v[2:3], v[52:53], v[116:117] op_sel_hi:[1,0,1]
	v_pk_fma_f32 v[4:5], v[4:5], v[52:53], v[118:119] op_sel:[0,1,0]
	v_pk_fma_f32 v[6:7], v[6:7], v[54:55], v[120:121] op_sel_hi:[1,0,1]
	v_pk_fma_f32 v[8:9], v[8:9], v[54:55], v[122:123] op_sel:[0,1,0]
	v_pk_fma_f32 v[132:133], v[60:61], v[62:63], v[132:133] op_sel:[0,1,0]
	v_pk_fma_f32 v[10:11], v[10:11], v[56:57], v[124:125] op_sel_hi:[1,0,1]
	v_pk_fma_f32 v[12:13], v[12:13], v[56:57], v[126:127] op_sel:[0,1,0]
	v_pk_fma_f32 v[14:15], v[14:15], v[58:59], v[128:129] op_sel_hi:[1,0,1]
	v_pk_fma_f32 v[16:17], v[16:17], v[58:59], v[130:131] op_sel:[0,1,0]
	ds_write_b64 v135, v[132:133] offset:55296
	s_waitcnt lgkmcnt(9)
	v_pk_mul_f32 v[108:109], v[2:3], v[64:65] op_sel_hi:[1,0]
	v_pk_mul_f32 v[112:113], v[2:3], v[72:73] op_sel_hi:[1,0]
	v_pk_fma_f32 v[108:109], v[4:5], v[64:65], v[108:109] op_sel:[0,1,0]
	v_pk_fma_f32 v[112:113], v[4:5], v[72:73], v[112:113] op_sel:[0,1,0]
	ds_read_b128 v[20:23], v225 offset:6656
	v_pk_fma_f32 v[108:109], v[6:7], v[66:67], v[108:109] op_sel_hi:[1,0,1]
	v_pk_fma_f32 v[112:113], v[6:7], v[74:75], v[112:113] op_sel_hi:[1,0,1]
	v_pk_fma_f32 v[108:109], v[8:9], v[66:67], v[108:109] op_sel:[0,1,0]
	v_pk_fma_f32 v[112:113], v[8:9], v[74:75], v[112:113] op_sel:[0,1,0]
	ds_read_b128 v[24:27], v225 offset:6672
	v_pk_fma_f32 v[108:109], v[10:11], v[68:69], v[108:109] op_sel_hi:[1,0,1]
	v_pk_fma_f32 v[112:113], v[10:11], v[76:77], v[112:113] op_sel_hi:[1,0,1]
	v_pk_fma_f32 v[108:109], v[12:13], v[68:69], v[108:109] op_sel:[0,1,0]
	v_pk_fma_f32 v[112:113], v[12:13], v[76:77], v[112:113] op_sel:[0,1,0]
	ds_read_b128 v[28:31], v225 offset:39424
	v_pk_fma_f32 v[108:109], v[14:15], v[70:71], v[108:109] op_sel_hi:[1,0,1]
	v_pk_fma_f32 v[112:113], v[14:15], v[78:79], v[112:113] op_sel_hi:[1,0,1]
	v_pk_fma_f32 v[108:109], v[16:17], v[70:71], v[108:109] op_sel:[0,1,0]
	v_pk_fma_f32 v[112:113], v[16:17], v[78:79], v[112:113] op_sel:[0,1,0]
	ds_read_b128 v[32:35], v225 offset:39440
	s_waitcnt lgkmcnt(10)
	v_pk_mul_f32 v[116:117], v[104:105], v[80:81] op_sel_hi:[1,0]
	v_pk_mul_f32 v[118:119], v[104:105], v[80:81] op_sel:[0,1]
	v_pk_mul_f32 v[120:121], v[104:105], v[82:83] op_sel_hi:[1,0]
	v_pk_mul_f32 v[122:123], v[104:105], v[82:83] op_sel:[0,1]
	ds_read_b64 v[60:61], v224 offset:47616
	ds_read_b128 v[36:39], v225 offset:31232
	v_add_f32_dpp v108, v108, v108 quad_perm:[1,0,3,2] row_mask:0xf bank_mask:0xf bound_ctrl:1
	v_add_f32_dpp v109, v109, v109 quad_perm:[1,0,3,2] row_mask:0xf bank_mask:0xf bound_ctrl:1
	v_add_f32_dpp v112, v112, v112 quad_perm:[1,0,3,2] row_mask:0xf bank_mask:0xf bound_ctrl:1
	v_add_f32_dpp v113, v113, v113 quad_perm:[1,0,3,2] row_mask:0xf bank_mask:0xf bound_ctrl:1
	v_pk_mul_f32 v[124:125], v[104:105], v[84:85] op_sel_hi:[1,0]
	v_pk_mul_f32 v[126:127], v[104:105], v[84:85] op_sel:[0,1]
	v_pk_mul_f32 v[128:129], v[104:105], v[86:87] op_sel_hi:[1,0]
	v_pk_mul_f32 v[130:131], v[104:105], v[86:87] op_sel:[0,1]
	ds_read_b128 v[40:43], v225 offset:31248
	ds_read_b64 v[62:63], v134 offset:57552
	v_add_f32_dpp v108, v108, v108 quad_perm:[2,3,0,1] row_mask:0xf bank_mask:0xf bound_ctrl:1
	v_add_f32_dpp v109, v109, v109 quad_perm:[2,3,0,1] row_mask:0xf bank_mask:0xf bound_ctrl:1
	v_add_f32_dpp v112, v112, v112 quad_perm:[2,3,0,1] row_mask:0xf bank_mask:0xf bound_ctrl:1
	v_add_f32_dpp v113, v113, v113 quad_perm:[2,3,0,1] row_mask:0xf bank_mask:0xf bound_ctrl:1
	ds_read_b128 v[44:47], v225 offset:23040
	v_add_f32_dpp v108, v108, v108 row_half_mirror row_mask:0xf bank_mask:0xf bound_ctrl:1
	v_add_f32_dpp v109, v109, v109 row_half_mirror row_mask:0xf bank_mask:0xf bound_ctrl:1
	v_add_f32_dpp v112, v112, v112 row_half_mirror row_mask:0xf bank_mask:0xf bound_ctrl:1
	v_add_f32_dpp v113, v113, v113 row_half_mirror row_mask:0xf bank_mask:0xf bound_ctrl:1
	ds_read_b128 v[48:51], v225 offset:23056
	s_waitcnt lgkmcnt(11)
	v_pk_fma_f32 v[116:117], v[108:109], v[88:89], v[116:117] op_sel_hi:[1,0,1] neg_lo:[1,0,0] neg_hi:[1,0,0]
	v_pk_fma_f32 v[118:119], v[108:109], v[88:89], v[118:119] op_sel:[0,1,0] neg_lo:[1,0,0] neg_hi:[1,0,0]
	v_pk_fma_f32 v[120:121], v[108:109], v[90:91], v[120:121] op_sel_hi:[1,0,1] neg_lo:[1,0,0] neg_hi:[1,0,0]
	v_pk_fma_f32 v[122:123], v[108:109], v[90:91], v[122:123] op_sel:[0,1,0] neg_lo:[1,0,0] neg_hi:[1,0,0]
	v_pk_fma_f32 v[124:125], v[108:109], v[92:93], v[124:125] op_sel_hi:[1,0,1] neg_lo:[1,0,0] neg_hi:[1,0,0]
	v_pk_fma_f32 v[126:127], v[108:109], v[92:93], v[126:127] op_sel:[0,1,0] neg_lo:[1,0,0] neg_hi:[1,0,0]
	v_pk_fma_f32 v[128:129], v[108:109], v[94:95], v[128:129] op_sel_hi:[1,0,1] neg_lo:[1,0,0] neg_hi:[1,0,0]
	v_pk_fma_f32 v[130:131], v[108:109], v[94:95], v[130:131] op_sel:[0,1,0] neg_lo:[1,0,0] neg_hi:[1,0,0]
	ds_read_b128 v[52:55], v225 offset:14848
	v_pk_fma_f32 v[132:133], v[108:109], v[106:107], v[112:113] op_sel_hi:[1,0,1] neg_lo:[1,0,0] neg_hi:[1,0,0]
	ds_read_b128 v[56:59], v225 offset:14864
	v_pk_fma_f32 v[2:3], v[2:3], v[96:97], v[116:117] op_sel_hi:[1,0,1]
	v_pk_fma_f32 v[4:5], v[4:5], v[96:97], v[118:119] op_sel:[0,1,0]
	v_pk_fma_f32 v[6:7], v[6:7], v[98:99], v[120:121] op_sel_hi:[1,0,1]
	v_pk_fma_f32 v[8:9], v[8:9], v[98:99], v[122:123] op_sel:[0,1,0]
	v_pk_fma_f32 v[132:133], v[104:105], v[106:107], v[132:133] op_sel:[0,1,0]
	v_pk_fma_f32 v[10:11], v[10:11], v[100:101], v[124:125] op_sel_hi:[1,0,1]
	v_pk_fma_f32 v[12:13], v[12:13], v[100:101], v[126:127] op_sel:[0,1,0]
	v_pk_fma_f32 v[14:15], v[14:15], v[102:103], v[128:129] op_sel_hi:[1,0,1]
	v_pk_fma_f32 v[16:17], v[16:17], v[102:103], v[130:131] op_sel:[0,1,0]
	ds_write_b64 v135, v[132:133] offset:55552
	s_waitcnt lgkmcnt(9)
	v_pk_mul_f32 v[108:109], v[2:3], v[20:21] op_sel_hi:[1,0]
	v_pk_mul_f32 v[112:113], v[2:3], v[28:29] op_sel_hi:[1,0]
	v_pk_fma_f32 v[108:109], v[4:5], v[20:21], v[108:109] op_sel:[0,1,0]
	v_pk_fma_f32 v[112:113], v[4:5], v[28:29], v[112:113] op_sel:[0,1,0]
	ds_read_b128 v[64:67], v225 offset:6912
	v_pk_fma_f32 v[108:109], v[6:7], v[22:23], v[108:109] op_sel_hi:[1,0,1]
	v_pk_fma_f32 v[112:113], v[6:7], v[30:31], v[112:113] op_sel_hi:[1,0,1]
	v_pk_fma_f32 v[108:109], v[8:9], v[22:23], v[108:109] op_sel:[0,1,0]
	v_pk_fma_f32 v[112:113], v[8:9], v[30:31], v[112:113] op_sel:[0,1,0]
	ds_read_b128 v[68:71], v225 offset:6928
	v_pk_fma_f32 v[108:109], v[10:11], v[24:25], v[108:109] op_sel_hi:[1,0,1]
	v_pk_fma_f32 v[112:113], v[10:11], v[32:33], v[112:113] op_sel_hi:[1,0,1]
	v_pk_fma_f32 v[108:109], v[12:13], v[24:25], v[108:109] op_sel:[0,1,0]
	v_pk_fma_f32 v[112:113], v[12:13], v[32:33], v[112:113] op_sel:[0,1,0]
	ds_read_b128 v[72:75], v225 offset:39680
	v_pk_fma_f32 v[108:109], v[14:15], v[26:27], v[108:109] op_sel_hi:[1,0,1]
	v_pk_fma_f32 v[112:113], v[14:15], v[34:35], v[112:113] op_sel_hi:[1,0,1]
	v_pk_fma_f32 v[108:109], v[16:17], v[26:27], v[108:109] op_sel:[0,1,0]
	v_pk_fma_f32 v[112:113], v[16:17], v[34:35], v[112:113] op_sel:[0,1,0]
	ds_read_b128 v[76:79], v225 offset:39696
	s_waitcnt lgkmcnt(10)
	v_pk_mul_f32 v[116:117], v[60:61], v[36:37] op_sel_hi:[1,0]
	v_pk_mul_f32 v[118:119], v[60:61], v[36:37] op_sel:[0,1]
	v_pk_mul_f32 v[120:121], v[60:61], v[38:39] op_sel_hi:[1,0]
	v_pk_mul_f32 v[122:123], v[60:61], v[38:39] op_sel:[0,1]
	ds_read_b64 v[104:105], v224 offset:47872
	ds_read_b128 v[80:83], v225 offset:31488
	v_add_f32_dpp v108, v108, v108 quad_perm:[1,0,3,2] row_mask:0xf bank_mask:0xf bound_ctrl:1
	v_add_f32_dpp v109, v109, v109 quad_perm:[1,0,3,2] row_mask:0xf bank_mask:0xf bound_ctrl:1
	v_add_f32_dpp v112, v112, v112 quad_perm:[1,0,3,2] row_mask:0xf bank_mask:0xf bound_ctrl:1
	v_add_f32_dpp v113, v113, v113 quad_perm:[1,0,3,2] row_mask:0xf bank_mask:0xf bound_ctrl:1
	v_pk_mul_f32 v[124:125], v[60:61], v[40:41] op_sel_hi:[1,0]
	v_pk_mul_f32 v[126:127], v[60:61], v[40:41] op_sel:[0,1]
	v_pk_mul_f32 v[128:129], v[60:61], v[42:43] op_sel_hi:[1,0]
	v_pk_mul_f32 v[130:131], v[60:61], v[42:43] op_sel:[0,1]
	ds_read_b128 v[84:87], v225 offset:31504
	ds_read_b64 v[106:107], v134 offset:57560
	v_add_f32_dpp v108, v108, v108 quad_perm:[2,3,0,1] row_mask:0xf bank_mask:0xf bound_ctrl:1
	v_add_f32_dpp v109, v109, v109 quad_perm:[2,3,0,1] row_mask:0xf bank_mask:0xf bound_ctrl:1
	v_add_f32_dpp v112, v112, v112 quad_perm:[2,3,0,1] row_mask:0xf bank_mask:0xf bound_ctrl:1
	v_add_f32_dpp v113, v113, v113 quad_perm:[2,3,0,1] row_mask:0xf bank_mask:0xf bound_ctrl:1
	ds_read_b128 v[88:91], v225 offset:23296
	v_add_f32_dpp v108, v108, v108 row_half_mirror row_mask:0xf bank_mask:0xf bound_ctrl:1
	v_add_f32_dpp v109, v109, v109 row_half_mirror row_mask:0xf bank_mask:0xf bound_ctrl:1
	v_add_f32_dpp v112, v112, v112 row_half_mirror row_mask:0xf bank_mask:0xf bound_ctrl:1
	v_add_f32_dpp v113, v113, v113 row_half_mirror row_mask:0xf bank_mask:0xf bound_ctrl:1
	ds_read_b128 v[92:95], v225 offset:23312
	s_waitcnt lgkmcnt(11)
	v_pk_fma_f32 v[116:117], v[108:109], v[44:45], v[116:117] op_sel_hi:[1,0,1] neg_lo:[1,0,0] neg_hi:[1,0,0]
	v_pk_fma_f32 v[118:119], v[108:109], v[44:45], v[118:119] op_sel:[0,1,0] neg_lo:[1,0,0] neg_hi:[1,0,0]
	v_pk_fma_f32 v[120:121], v[108:109], v[46:47], v[120:121] op_sel_hi:[1,0,1] neg_lo:[1,0,0] neg_hi:[1,0,0]
	v_pk_fma_f32 v[122:123], v[108:109], v[46:47], v[122:123] op_sel:[0,1,0] neg_lo:[1,0,0] neg_hi:[1,0,0]
	v_pk_fma_f32 v[124:125], v[108:109], v[48:49], v[124:125] op_sel_hi:[1,0,1] neg_lo:[1,0,0] neg_hi:[1,0,0]
	v_pk_fma_f32 v[126:127], v[108:109], v[48:49], v[126:127] op_sel:[0,1,0] neg_lo:[1,0,0] neg_hi:[1,0,0]
	v_pk_fma_f32 v[128:129], v[108:109], v[50:51], v[128:129] op_sel_hi:[1,0,1] neg_lo:[1,0,0] neg_hi:[1,0,0]
	v_pk_fma_f32 v[130:131], v[108:109], v[50:51], v[130:131] op_sel:[0,1,0] neg_lo:[1,0,0] neg_hi:[1,0,0]
	ds_read_b128 v[96:99], v225 offset:15104
	v_pk_fma_f32 v[132:133], v[108:109], v[62:63], v[112:113] op_sel_hi:[1,0,1] neg_lo:[1,0,0] neg_hi:[1,0,0]
	ds_read_b128 v[100:103], v225 offset:15120
	v_pk_fma_f32 v[2:3], v[2:3], v[52:53], v[116:117] op_sel_hi:[1,0,1]
	v_pk_fma_f32 v[4:5], v[4:5], v[52:53], v[118:119] op_sel:[0,1,0]
	v_pk_fma_f32 v[6:7], v[6:7], v[54:55], v[120:121] op_sel_hi:[1,0,1]
	v_pk_fma_f32 v[8:9], v[8:9], v[54:55], v[122:123] op_sel:[0,1,0]
	v_pk_fma_f32 v[132:133], v[60:61], v[62:63], v[132:133] op_sel:[0,1,0]
	v_pk_fma_f32 v[10:11], v[10:11], v[56:57], v[124:125] op_sel_hi:[1,0,1]
	v_pk_fma_f32 v[12:13], v[12:13], v[56:57], v[126:127] op_sel:[0,1,0]
	v_pk_fma_f32 v[14:15], v[14:15], v[58:59], v[128:129] op_sel_hi:[1,0,1]
	v_pk_fma_f32 v[16:17], v[16:17], v[58:59], v[130:131] op_sel:[0,1,0]
	ds_write_b64 v135, v[132:133] offset:55808
	s_waitcnt lgkmcnt(9)
	v_pk_mul_f32 v[108:109], v[2:3], v[64:65] op_sel_hi:[1,0]
	v_pk_mul_f32 v[112:113], v[2:3], v[72:73] op_sel_hi:[1,0]
	v_pk_fma_f32 v[108:109], v[4:5], v[64:65], v[108:109] op_sel:[0,1,0]
	v_pk_fma_f32 v[112:113], v[4:5], v[72:73], v[112:113] op_sel:[0,1,0]
	ds_read_b128 v[20:23], v225 offset:7168
	v_pk_fma_f32 v[108:109], v[6:7], v[66:67], v[108:109] op_sel_hi:[1,0,1]
	v_pk_fma_f32 v[112:113], v[6:7], v[74:75], v[112:113] op_sel_hi:[1,0,1]
	v_pk_fma_f32 v[108:109], v[8:9], v[66:67], v[108:109] op_sel:[0,1,0]
	v_pk_fma_f32 v[112:113], v[8:9], v[74:75], v[112:113] op_sel:[0,1,0]
	ds_read_b128 v[24:27], v225 offset:7184
	v_pk_fma_f32 v[108:109], v[10:11], v[68:69], v[108:109] op_sel_hi:[1,0,1]
	v_pk_fma_f32 v[112:113], v[10:11], v[76:77], v[112:113] op_sel_hi:[1,0,1]
	v_pk_fma_f32 v[108:109], v[12:13], v[68:69], v[108:109] op_sel:[0,1,0]
	v_pk_fma_f32 v[112:113], v[12:13], v[76:77], v[112:113] op_sel:[0,1,0]
	ds_read_b128 v[28:31], v225 offset:39936
	v_pk_fma_f32 v[108:109], v[14:15], v[70:71], v[108:109] op_sel_hi:[1,0,1]
	v_pk_fma_f32 v[112:113], v[14:15], v[78:79], v[112:113] op_sel_hi:[1,0,1]
	v_pk_fma_f32 v[108:109], v[16:17], v[70:71], v[108:109] op_sel:[0,1,0]
	v_pk_fma_f32 v[112:113], v[16:17], v[78:79], v[112:113] op_sel:[0,1,0]
	ds_read_b128 v[32:35], v225 offset:39952
	s_waitcnt lgkmcnt(10)
	v_pk_mul_f32 v[116:117], v[104:105], v[80:81] op_sel_hi:[1,0]
	v_pk_mul_f32 v[118:119], v[104:105], v[80:81] op_sel:[0,1]
	v_pk_mul_f32 v[120:121], v[104:105], v[82:83] op_sel_hi:[1,0]
	v_pk_mul_f32 v[122:123], v[104:105], v[82:83] op_sel:[0,1]
	ds_read_b64 v[60:61], v224 offset:48128
	ds_read_b128 v[36:39], v225 offset:31744
	v_add_f32_dpp v108, v108, v108 quad_perm:[1,0,3,2] row_mask:0xf bank_mask:0xf bound_ctrl:1
	v_add_f32_dpp v109, v109, v109 quad_perm:[1,0,3,2] row_mask:0xf bank_mask:0xf bound_ctrl:1
	v_add_f32_dpp v112, v112, v112 quad_perm:[1,0,3,2] row_mask:0xf bank_mask:0xf bound_ctrl:1
	v_add_f32_dpp v113, v113, v113 quad_perm:[1,0,3,2] row_mask:0xf bank_mask:0xf bound_ctrl:1
	v_pk_mul_f32 v[124:125], v[104:105], v[84:85] op_sel_hi:[1,0]
	v_pk_mul_f32 v[126:127], v[104:105], v[84:85] op_sel:[0,1]
	v_pk_mul_f32 v[128:129], v[104:105], v[86:87] op_sel_hi:[1,0]
	v_pk_mul_f32 v[130:131], v[104:105], v[86:87] op_sel:[0,1]
	ds_read_b128 v[40:43], v225 offset:31760
	ds_read_b64 v[62:63], v134 offset:57568
	v_add_f32_dpp v108, v108, v108 quad_perm:[2,3,0,1] row_mask:0xf bank_mask:0xf bound_ctrl:1
	v_add_f32_dpp v109, v109, v109 quad_perm:[2,3,0,1] row_mask:0xf bank_mask:0xf bound_ctrl:1
	v_add_f32_dpp v112, v112, v112 quad_perm:[2,3,0,1] row_mask:0xf bank_mask:0xf bound_ctrl:1
	v_add_f32_dpp v113, v113, v113 quad_perm:[2,3,0,1] row_mask:0xf bank_mask:0xf bound_ctrl:1
	ds_read_b128 v[44:47], v225 offset:23552
	v_add_f32_dpp v108, v108, v108 row_half_mirror row_mask:0xf bank_mask:0xf bound_ctrl:1
	v_add_f32_dpp v109, v109, v109 row_half_mirror row_mask:0xf bank_mask:0xf bound_ctrl:1
	v_add_f32_dpp v112, v112, v112 row_half_mirror row_mask:0xf bank_mask:0xf bound_ctrl:1
	v_add_f32_dpp v113, v113, v113 row_half_mirror row_mask:0xf bank_mask:0xf bound_ctrl:1
	ds_read_b128 v[48:51], v225 offset:23568
	s_waitcnt lgkmcnt(11)
	v_pk_fma_f32 v[116:117], v[108:109], v[88:89], v[116:117] op_sel_hi:[1,0,1] neg_lo:[1,0,0] neg_hi:[1,0,0]
	v_pk_fma_f32 v[118:119], v[108:109], v[88:89], v[118:119] op_sel:[0,1,0] neg_lo:[1,0,0] neg_hi:[1,0,0]
	v_pk_fma_f32 v[120:121], v[108:109], v[90:91], v[120:121] op_sel_hi:[1,0,1] neg_lo:[1,0,0] neg_hi:[1,0,0]
	v_pk_fma_f32 v[122:123], v[108:109], v[90:91], v[122:123] op_sel:[0,1,0] neg_lo:[1,0,0] neg_hi:[1,0,0]
	v_pk_fma_f32 v[124:125], v[108:109], v[92:93], v[124:125] op_sel_hi:[1,0,1] neg_lo:[1,0,0] neg_hi:[1,0,0]
	v_pk_fma_f32 v[126:127], v[108:109], v[92:93], v[126:127] op_sel:[0,1,0] neg_lo:[1,0,0] neg_hi:[1,0,0]
	v_pk_fma_f32 v[128:129], v[108:109], v[94:95], v[128:129] op_sel_hi:[1,0,1] neg_lo:[1,0,0] neg_hi:[1,0,0]
	v_pk_fma_f32 v[130:131], v[108:109], v[94:95], v[130:131] op_sel:[0,1,0] neg_lo:[1,0,0] neg_hi:[1,0,0]
	ds_read_b128 v[52:55], v225 offset:15360
	v_pk_fma_f32 v[132:133], v[108:109], v[106:107], v[112:113] op_sel_hi:[1,0,1] neg_lo:[1,0,0] neg_hi:[1,0,0]
	ds_read_b128 v[56:59], v225 offset:15376
	v_pk_fma_f32 v[2:3], v[2:3], v[96:97], v[116:117] op_sel_hi:[1,0,1]
	v_pk_fma_f32 v[4:5], v[4:5], v[96:97], v[118:119] op_sel:[0,1,0]
	v_pk_fma_f32 v[6:7], v[6:7], v[98:99], v[120:121] op_sel_hi:[1,0,1]
	v_pk_fma_f32 v[8:9], v[8:9], v[98:99], v[122:123] op_sel:[0,1,0]
	v_pk_fma_f32 v[132:133], v[104:105], v[106:107], v[132:133] op_sel:[0,1,0]
	v_pk_fma_f32 v[10:11], v[10:11], v[100:101], v[124:125] op_sel_hi:[1,0,1]
	v_pk_fma_f32 v[12:13], v[12:13], v[100:101], v[126:127] op_sel:[0,1,0]
	v_pk_fma_f32 v[14:15], v[14:15], v[102:103], v[128:129] op_sel_hi:[1,0,1]
	v_pk_fma_f32 v[16:17], v[16:17], v[102:103], v[130:131] op_sel:[0,1,0]
	ds_write_b64 v135, v[132:133] offset:56064
	s_waitcnt lgkmcnt(9)
	v_pk_mul_f32 v[108:109], v[2:3], v[20:21] op_sel_hi:[1,0]
	v_pk_mul_f32 v[112:113], v[2:3], v[28:29] op_sel_hi:[1,0]
	v_pk_fma_f32 v[108:109], v[4:5], v[20:21], v[108:109] op_sel:[0,1,0]
	v_pk_fma_f32 v[112:113], v[4:5], v[28:29], v[112:113] op_sel:[0,1,0]
	ds_read_b128 v[64:67], v225 offset:7424
	v_pk_fma_f32 v[108:109], v[6:7], v[22:23], v[108:109] op_sel_hi:[1,0,1]
	v_pk_fma_f32 v[112:113], v[6:7], v[30:31], v[112:113] op_sel_hi:[1,0,1]
	v_pk_fma_f32 v[108:109], v[8:9], v[22:23], v[108:109] op_sel:[0,1,0]
	v_pk_fma_f32 v[112:113], v[8:9], v[30:31], v[112:113] op_sel:[0,1,0]
	ds_read_b128 v[68:71], v225 offset:7440
	v_pk_fma_f32 v[108:109], v[10:11], v[24:25], v[108:109] op_sel_hi:[1,0,1]
	v_pk_fma_f32 v[112:113], v[10:11], v[32:33], v[112:113] op_sel_hi:[1,0,1]
	v_pk_fma_f32 v[108:109], v[12:13], v[24:25], v[108:109] op_sel:[0,1,0]
	v_pk_fma_f32 v[112:113], v[12:13], v[32:33], v[112:113] op_sel:[0,1,0]
	ds_read_b128 v[72:75], v225 offset:40192
	v_pk_fma_f32 v[108:109], v[14:15], v[26:27], v[108:109] op_sel_hi:[1,0,1]
	v_pk_fma_f32 v[112:113], v[14:15], v[34:35], v[112:113] op_sel_hi:[1,0,1]
	v_pk_fma_f32 v[108:109], v[16:17], v[26:27], v[108:109] op_sel:[0,1,0]
	v_pk_fma_f32 v[112:113], v[16:17], v[34:35], v[112:113] op_sel:[0,1,0]
	ds_read_b128 v[76:79], v225 offset:40208
	s_waitcnt lgkmcnt(10)
	v_pk_mul_f32 v[116:117], v[60:61], v[36:37] op_sel_hi:[1,0]
	v_pk_mul_f32 v[118:119], v[60:61], v[36:37] op_sel:[0,1]
	v_pk_mul_f32 v[120:121], v[60:61], v[38:39] op_sel_hi:[1,0]
	v_pk_mul_f32 v[122:123], v[60:61], v[38:39] op_sel:[0,1]
	ds_read_b64 v[104:105], v224 offset:48384
	ds_read_b128 v[80:83], v225 offset:32000
	v_add_f32_dpp v108, v108, v108 quad_perm:[1,0,3,2] row_mask:0xf bank_mask:0xf bound_ctrl:1
	v_add_f32_dpp v109, v109, v109 quad_perm:[1,0,3,2] row_mask:0xf bank_mask:0xf bound_ctrl:1
	v_add_f32_dpp v112, v112, v112 quad_perm:[1,0,3,2] row_mask:0xf bank_mask:0xf bound_ctrl:1
	v_add_f32_dpp v113, v113, v113 quad_perm:[1,0,3,2] row_mask:0xf bank_mask:0xf bound_ctrl:1
	v_pk_mul_f32 v[124:125], v[60:61], v[40:41] op_sel_hi:[1,0]
	v_pk_mul_f32 v[126:127], v[60:61], v[40:41] op_sel:[0,1]
	v_pk_mul_f32 v[128:129], v[60:61], v[42:43] op_sel_hi:[1,0]
	v_pk_mul_f32 v[130:131], v[60:61], v[42:43] op_sel:[0,1]
	ds_read_b128 v[84:87], v225 offset:32016
	ds_read_b64 v[106:107], v134 offset:57576
	v_add_f32_dpp v108, v108, v108 quad_perm:[2,3,0,1] row_mask:0xf bank_mask:0xf bound_ctrl:1
	v_add_f32_dpp v109, v109, v109 quad_perm:[2,3,0,1] row_mask:0xf bank_mask:0xf bound_ctrl:1
	v_add_f32_dpp v112, v112, v112 quad_perm:[2,3,0,1] row_mask:0xf bank_mask:0xf bound_ctrl:1
	v_add_f32_dpp v113, v113, v113 quad_perm:[2,3,0,1] row_mask:0xf bank_mask:0xf bound_ctrl:1
	ds_read_b128 v[88:91], v225 offset:23808
	v_add_f32_dpp v108, v108, v108 row_half_mirror row_mask:0xf bank_mask:0xf bound_ctrl:1
	v_add_f32_dpp v109, v109, v109 row_half_mirror row_mask:0xf bank_mask:0xf bound_ctrl:1
	v_add_f32_dpp v112, v112, v112 row_half_mirror row_mask:0xf bank_mask:0xf bound_ctrl:1
	v_add_f32_dpp v113, v113, v113 row_half_mirror row_mask:0xf bank_mask:0xf bound_ctrl:1
	ds_read_b128 v[92:95], v225 offset:23824
	s_waitcnt lgkmcnt(11)
	v_pk_fma_f32 v[116:117], v[108:109], v[44:45], v[116:117] op_sel_hi:[1,0,1] neg_lo:[1,0,0] neg_hi:[1,0,0]
	v_pk_fma_f32 v[118:119], v[108:109], v[44:45], v[118:119] op_sel:[0,1,0] neg_lo:[1,0,0] neg_hi:[1,0,0]
	v_pk_fma_f32 v[120:121], v[108:109], v[46:47], v[120:121] op_sel_hi:[1,0,1] neg_lo:[1,0,0] neg_hi:[1,0,0]
	v_pk_fma_f32 v[122:123], v[108:109], v[46:47], v[122:123] op_sel:[0,1,0] neg_lo:[1,0,0] neg_hi:[1,0,0]
	v_pk_fma_f32 v[124:125], v[108:109], v[48:49], v[124:125] op_sel_hi:[1,0,1] neg_lo:[1,0,0] neg_hi:[1,0,0]
	v_pk_fma_f32 v[126:127], v[108:109], v[48:49], v[126:127] op_sel:[0,1,0] neg_lo:[1,0,0] neg_hi:[1,0,0]
	v_pk_fma_f32 v[128:129], v[108:109], v[50:51], v[128:129] op_sel_hi:[1,0,1] neg_lo:[1,0,0] neg_hi:[1,0,0]
	v_pk_fma_f32 v[130:131], v[108:109], v[50:51], v[130:131] op_sel:[0,1,0] neg_lo:[1,0,0] neg_hi:[1,0,0]
	ds_read_b128 v[96:99], v225 offset:15616
	v_pk_fma_f32 v[132:133], v[108:109], v[62:63], v[112:113] op_sel_hi:[1,0,1] neg_lo:[1,0,0] neg_hi:[1,0,0]
	ds_read_b128 v[100:103], v225 offset:15632
	v_pk_fma_f32 v[2:3], v[2:3], v[52:53], v[116:117] op_sel_hi:[1,0,1]
	v_pk_fma_f32 v[4:5], v[4:5], v[52:53], v[118:119] op_sel:[0,1,0]
	v_pk_fma_f32 v[6:7], v[6:7], v[54:55], v[120:121] op_sel_hi:[1,0,1]
	v_pk_fma_f32 v[8:9], v[8:9], v[54:55], v[122:123] op_sel:[0,1,0]
	v_pk_fma_f32 v[132:133], v[60:61], v[62:63], v[132:133] op_sel:[0,1,0]
	v_pk_fma_f32 v[10:11], v[10:11], v[56:57], v[124:125] op_sel_hi:[1,0,1]
	v_pk_fma_f32 v[12:13], v[12:13], v[56:57], v[126:127] op_sel:[0,1,0]
	v_pk_fma_f32 v[14:15], v[14:15], v[58:59], v[128:129] op_sel_hi:[1,0,1]
	v_pk_fma_f32 v[16:17], v[16:17], v[58:59], v[130:131] op_sel:[0,1,0]
	ds_write_b64 v135, v[132:133] offset:56320
	s_waitcnt lgkmcnt(9)
	v_pk_mul_f32 v[108:109], v[2:3], v[64:65] op_sel_hi:[1,0]
	v_pk_mul_f32 v[112:113], v[2:3], v[72:73] op_sel_hi:[1,0]
	v_pk_fma_f32 v[108:109], v[4:5], v[64:65], v[108:109] op_sel:[0,1,0]
	v_pk_fma_f32 v[112:113], v[4:5], v[72:73], v[112:113] op_sel:[0,1,0]
	ds_read_b128 v[20:23], v225 offset:7680
	v_pk_fma_f32 v[108:109], v[6:7], v[66:67], v[108:109] op_sel_hi:[1,0,1]
	v_pk_fma_f32 v[112:113], v[6:7], v[74:75], v[112:113] op_sel_hi:[1,0,1]
	v_pk_fma_f32 v[108:109], v[8:9], v[66:67], v[108:109] op_sel:[0,1,0]
	v_pk_fma_f32 v[112:113], v[8:9], v[74:75], v[112:113] op_sel:[0,1,0]
	ds_read_b128 v[24:27], v225 offset:7696
	v_pk_fma_f32 v[108:109], v[10:11], v[68:69], v[108:109] op_sel_hi:[1,0,1]
	v_pk_fma_f32 v[112:113], v[10:11], v[76:77], v[112:113] op_sel_hi:[1,0,1]
	v_pk_fma_f32 v[108:109], v[12:13], v[68:69], v[108:109] op_sel:[0,1,0]
	v_pk_fma_f32 v[112:113], v[12:13], v[76:77], v[112:113] op_sel:[0,1,0]
	ds_read_b128 v[28:31], v225 offset:40448
	v_pk_fma_f32 v[108:109], v[14:15], v[70:71], v[108:109] op_sel_hi:[1,0,1]
	v_pk_fma_f32 v[112:113], v[14:15], v[78:79], v[112:113] op_sel_hi:[1,0,1]
	v_pk_fma_f32 v[108:109], v[16:17], v[70:71], v[108:109] op_sel:[0,1,0]
	v_pk_fma_f32 v[112:113], v[16:17], v[78:79], v[112:113] op_sel:[0,1,0]
	ds_read_b128 v[32:35], v225 offset:40464
	s_waitcnt lgkmcnt(10)
	v_pk_mul_f32 v[116:117], v[104:105], v[80:81] op_sel_hi:[1,0]
	v_pk_mul_f32 v[118:119], v[104:105], v[80:81] op_sel:[0,1]
	v_pk_mul_f32 v[120:121], v[104:105], v[82:83] op_sel_hi:[1,0]
	v_pk_mul_f32 v[122:123], v[104:105], v[82:83] op_sel:[0,1]
	ds_read_b64 v[60:61], v224 offset:48640
	ds_read_b128 v[36:39], v225 offset:32256
	v_add_f32_dpp v108, v108, v108 quad_perm:[1,0,3,2] row_mask:0xf bank_mask:0xf bound_ctrl:1
	v_add_f32_dpp v109, v109, v109 quad_perm:[1,0,3,2] row_mask:0xf bank_mask:0xf bound_ctrl:1
	v_add_f32_dpp v112, v112, v112 quad_perm:[1,0,3,2] row_mask:0xf bank_mask:0xf bound_ctrl:1
	v_add_f32_dpp v113, v113, v113 quad_perm:[1,0,3,2] row_mask:0xf bank_mask:0xf bound_ctrl:1
	v_pk_mul_f32 v[124:125], v[104:105], v[84:85] op_sel_hi:[1,0]
	v_pk_mul_f32 v[126:127], v[104:105], v[84:85] op_sel:[0,1]
	v_pk_mul_f32 v[128:129], v[104:105], v[86:87] op_sel_hi:[1,0]
	v_pk_mul_f32 v[130:131], v[104:105], v[86:87] op_sel:[0,1]
	ds_read_b128 v[40:43], v225 offset:32272
	ds_read_b64 v[62:63], v134 offset:57584
	v_add_f32_dpp v108, v108, v108 quad_perm:[2,3,0,1] row_mask:0xf bank_mask:0xf bound_ctrl:1
	v_add_f32_dpp v109, v109, v109 quad_perm:[2,3,0,1] row_mask:0xf bank_mask:0xf bound_ctrl:1
	v_add_f32_dpp v112, v112, v112 quad_perm:[2,3,0,1] row_mask:0xf bank_mask:0xf bound_ctrl:1
	v_add_f32_dpp v113, v113, v113 quad_perm:[2,3,0,1] row_mask:0xf bank_mask:0xf bound_ctrl:1
	ds_read_b128 v[44:47], v225 offset:24064
	v_add_f32_dpp v108, v108, v108 row_half_mirror row_mask:0xf bank_mask:0xf bound_ctrl:1
	v_add_f32_dpp v109, v109, v109 row_half_mirror row_mask:0xf bank_mask:0xf bound_ctrl:1
	v_add_f32_dpp v112, v112, v112 row_half_mirror row_mask:0xf bank_mask:0xf bound_ctrl:1
	v_add_f32_dpp v113, v113, v113 row_half_mirror row_mask:0xf bank_mask:0xf bound_ctrl:1
	ds_read_b128 v[48:51], v225 offset:24080
	s_waitcnt lgkmcnt(11)
	v_pk_fma_f32 v[116:117], v[108:109], v[88:89], v[116:117] op_sel_hi:[1,0,1] neg_lo:[1,0,0] neg_hi:[1,0,0]
	v_pk_fma_f32 v[118:119], v[108:109], v[88:89], v[118:119] op_sel:[0,1,0] neg_lo:[1,0,0] neg_hi:[1,0,0]
	v_pk_fma_f32 v[120:121], v[108:109], v[90:91], v[120:121] op_sel_hi:[1,0,1] neg_lo:[1,0,0] neg_hi:[1,0,0]
	v_pk_fma_f32 v[122:123], v[108:109], v[90:91], v[122:123] op_sel:[0,1,0] neg_lo:[1,0,0] neg_hi:[1,0,0]
	v_pk_fma_f32 v[124:125], v[108:109], v[92:93], v[124:125] op_sel_hi:[1,0,1] neg_lo:[1,0,0] neg_hi:[1,0,0]
	v_pk_fma_f32 v[126:127], v[108:109], v[92:93], v[126:127] op_sel:[0,1,0] neg_lo:[1,0,0] neg_hi:[1,0,0]
	v_pk_fma_f32 v[128:129], v[108:109], v[94:95], v[128:129] op_sel_hi:[1,0,1] neg_lo:[1,0,0] neg_hi:[1,0,0]
	v_pk_fma_f32 v[130:131], v[108:109], v[94:95], v[130:131] op_sel:[0,1,0] neg_lo:[1,0,0] neg_hi:[1,0,0]
	ds_read_b128 v[52:55], v225 offset:15872
	v_pk_fma_f32 v[132:133], v[108:109], v[106:107], v[112:113] op_sel_hi:[1,0,1] neg_lo:[1,0,0] neg_hi:[1,0,0]
	ds_read_b128 v[56:59], v225 offset:15888
	v_pk_fma_f32 v[2:3], v[2:3], v[96:97], v[116:117] op_sel_hi:[1,0,1]
	v_pk_fma_f32 v[4:5], v[4:5], v[96:97], v[118:119] op_sel:[0,1,0]
	v_pk_fma_f32 v[6:7], v[6:7], v[98:99], v[120:121] op_sel_hi:[1,0,1]
	v_pk_fma_f32 v[8:9], v[8:9], v[98:99], v[122:123] op_sel:[0,1,0]
	v_pk_fma_f32 v[132:133], v[104:105], v[106:107], v[132:133] op_sel:[0,1,0]
	v_pk_fma_f32 v[10:11], v[10:11], v[100:101], v[124:125] op_sel_hi:[1,0,1]
	v_pk_fma_f32 v[12:13], v[12:13], v[100:101], v[126:127] op_sel:[0,1,0]
	v_pk_fma_f32 v[14:15], v[14:15], v[102:103], v[128:129] op_sel_hi:[1,0,1]
	v_pk_fma_f32 v[16:17], v[16:17], v[102:103], v[130:131] op_sel:[0,1,0]
	ds_write_b64 v135, v[132:133] offset:56576
	s_waitcnt lgkmcnt(9)
	v_pk_mul_f32 v[108:109], v[2:3], v[20:21] op_sel_hi:[1,0]
	v_pk_mul_f32 v[112:113], v[2:3], v[28:29] op_sel_hi:[1,0]
	v_pk_fma_f32 v[108:109], v[4:5], v[20:21], v[108:109] op_sel:[0,1,0]
	v_pk_fma_f32 v[112:113], v[4:5], v[28:29], v[112:113] op_sel:[0,1,0]
	ds_read_b128 v[64:67], v225 offset:7936
	v_pk_fma_f32 v[108:109], v[6:7], v[22:23], v[108:109] op_sel_hi:[1,0,1]
	v_pk_fma_f32 v[112:113], v[6:7], v[30:31], v[112:113] op_sel_hi:[1,0,1]
	v_pk_fma_f32 v[108:109], v[8:9], v[22:23], v[108:109] op_sel:[0,1,0]
	v_pk_fma_f32 v[112:113], v[8:9], v[30:31], v[112:113] op_sel:[0,1,0]
	ds_read_b128 v[68:71], v225 offset:7952
	v_pk_fma_f32 v[108:109], v[10:11], v[24:25], v[108:109] op_sel_hi:[1,0,1]
	v_pk_fma_f32 v[112:113], v[10:11], v[32:33], v[112:113] op_sel_hi:[1,0,1]
	v_pk_fma_f32 v[108:109], v[12:13], v[24:25], v[108:109] op_sel:[0,1,0]
	v_pk_fma_f32 v[112:113], v[12:13], v[32:33], v[112:113] op_sel:[0,1,0]
	ds_read_b128 v[72:75], v225 offset:40704
	v_pk_fma_f32 v[108:109], v[14:15], v[26:27], v[108:109] op_sel_hi:[1,0,1]
	v_pk_fma_f32 v[112:113], v[14:15], v[34:35], v[112:113] op_sel_hi:[1,0,1]
	v_pk_fma_f32 v[108:109], v[16:17], v[26:27], v[108:109] op_sel:[0,1,0]
	v_pk_fma_f32 v[112:113], v[16:17], v[34:35], v[112:113] op_sel:[0,1,0]
	ds_read_b128 v[76:79], v225 offset:40720
	s_waitcnt lgkmcnt(10)
	v_pk_mul_f32 v[116:117], v[60:61], v[36:37] op_sel_hi:[1,0]
	v_pk_mul_f32 v[118:119], v[60:61], v[36:37] op_sel:[0,1]
	v_pk_mul_f32 v[120:121], v[60:61], v[38:39] op_sel_hi:[1,0]
	v_pk_mul_f32 v[122:123], v[60:61], v[38:39] op_sel:[0,1]
	ds_read_b64 v[104:105], v224 offset:48896
	ds_read_b128 v[80:83], v225 offset:32512
	v_add_f32_dpp v108, v108, v108 quad_perm:[1,0,3,2] row_mask:0xf bank_mask:0xf bound_ctrl:1
	v_add_f32_dpp v109, v109, v109 quad_perm:[1,0,3,2] row_mask:0xf bank_mask:0xf bound_ctrl:1
	v_add_f32_dpp v112, v112, v112 quad_perm:[1,0,3,2] row_mask:0xf bank_mask:0xf bound_ctrl:1
	v_add_f32_dpp v113, v113, v113 quad_perm:[1,0,3,2] row_mask:0xf bank_mask:0xf bound_ctrl:1
	v_pk_mul_f32 v[124:125], v[60:61], v[40:41] op_sel_hi:[1,0]
	v_pk_mul_f32 v[126:127], v[60:61], v[40:41] op_sel:[0,1]
	v_pk_mul_f32 v[128:129], v[60:61], v[42:43] op_sel_hi:[1,0]
	v_pk_mul_f32 v[130:131], v[60:61], v[42:43] op_sel:[0,1]
	ds_read_b128 v[84:87], v225 offset:32528
	ds_read_b64 v[106:107], v134 offset:57592
	v_add_f32_dpp v108, v108, v108 quad_perm:[2,3,0,1] row_mask:0xf bank_mask:0xf bound_ctrl:1
	v_add_f32_dpp v109, v109, v109 quad_perm:[2,3,0,1] row_mask:0xf bank_mask:0xf bound_ctrl:1
	v_add_f32_dpp v112, v112, v112 quad_perm:[2,3,0,1] row_mask:0xf bank_mask:0xf bound_ctrl:1
	v_add_f32_dpp v113, v113, v113 quad_perm:[2,3,0,1] row_mask:0xf bank_mask:0xf bound_ctrl:1
	ds_read_b128 v[88:91], v225 offset:24320
	v_add_f32_dpp v108, v108, v108 row_half_mirror row_mask:0xf bank_mask:0xf bound_ctrl:1
	v_add_f32_dpp v109, v109, v109 row_half_mirror row_mask:0xf bank_mask:0xf bound_ctrl:1
	v_add_f32_dpp v112, v112, v112 row_half_mirror row_mask:0xf bank_mask:0xf bound_ctrl:1
	v_add_f32_dpp v113, v113, v113 row_half_mirror row_mask:0xf bank_mask:0xf bound_ctrl:1
	ds_read_b128 v[92:95], v225 offset:24336
	s_waitcnt lgkmcnt(11)
	v_pk_fma_f32 v[116:117], v[108:109], v[44:45], v[116:117] op_sel_hi:[1,0,1] neg_lo:[1,0,0] neg_hi:[1,0,0]
	v_pk_fma_f32 v[118:119], v[108:109], v[44:45], v[118:119] op_sel:[0,1,0] neg_lo:[1,0,0] neg_hi:[1,0,0]
	v_pk_fma_f32 v[120:121], v[108:109], v[46:47], v[120:121] op_sel_hi:[1,0,1] neg_lo:[1,0,0] neg_hi:[1,0,0]
	v_pk_fma_f32 v[122:123], v[108:109], v[46:47], v[122:123] op_sel:[0,1,0] neg_lo:[1,0,0] neg_hi:[1,0,0]
	v_pk_fma_f32 v[124:125], v[108:109], v[48:49], v[124:125] op_sel_hi:[1,0,1] neg_lo:[1,0,0] neg_hi:[1,0,0]
	v_pk_fma_f32 v[126:127], v[108:109], v[48:49], v[126:127] op_sel:[0,1,0] neg_lo:[1,0,0] neg_hi:[1,0,0]
	v_pk_fma_f32 v[128:129], v[108:109], v[50:51], v[128:129] op_sel_hi:[1,0,1] neg_lo:[1,0,0] neg_hi:[1,0,0]
	v_pk_fma_f32 v[130:131], v[108:109], v[50:51], v[130:131] op_sel:[0,1,0] neg_lo:[1,0,0] neg_hi:[1,0,0]
	ds_read_b128 v[96:99], v225 offset:16128
	v_pk_fma_f32 v[132:133], v[108:109], v[62:63], v[112:113] op_sel_hi:[1,0,1] neg_lo:[1,0,0] neg_hi:[1,0,0]
	ds_read_b128 v[100:103], v225 offset:16144
	v_pk_fma_f32 v[2:3], v[2:3], v[52:53], v[116:117] op_sel_hi:[1,0,1]
	v_pk_fma_f32 v[4:5], v[4:5], v[52:53], v[118:119] op_sel:[0,1,0]
	v_pk_fma_f32 v[6:7], v[6:7], v[54:55], v[120:121] op_sel_hi:[1,0,1]
	v_pk_fma_f32 v[8:9], v[8:9], v[54:55], v[122:123] op_sel:[0,1,0]
	v_pk_fma_f32 v[132:133], v[60:61], v[62:63], v[132:133] op_sel:[0,1,0]
	v_pk_fma_f32 v[10:11], v[10:11], v[56:57], v[124:125] op_sel_hi:[1,0,1]
	v_pk_fma_f32 v[12:13], v[12:13], v[56:57], v[126:127] op_sel:[0,1,0]
	v_pk_fma_f32 v[14:15], v[14:15], v[58:59], v[128:129] op_sel_hi:[1,0,1]
	v_pk_fma_f32 v[16:17], v[16:17], v[58:59], v[130:131] op_sel:[0,1,0]
	ds_write_b64 v135, v[132:133] offset:56832
	s_waitcnt lgkmcnt(9)
	v_pk_mul_f32 v[108:109], v[2:3], v[64:65] op_sel_hi:[1,0]
	v_pk_mul_f32 v[112:113], v[2:3], v[72:73] op_sel_hi:[1,0]
	v_pk_fma_f32 v[108:109], v[4:5], v[64:65], v[108:109] op_sel:[0,1,0]
	v_pk_fma_f32 v[112:113], v[4:5], v[72:73], v[112:113] op_sel:[0,1,0]
	v_pk_fma_f32 v[108:109], v[6:7], v[66:67], v[108:109] op_sel_hi:[1,0,1]
	v_pk_fma_f32 v[112:113], v[6:7], v[74:75], v[112:113] op_sel_hi:[1,0,1]
	v_pk_fma_f32 v[108:109], v[8:9], v[66:67], v[108:109] op_sel:[0,1,0]
	v_pk_fma_f32 v[112:113], v[8:9], v[74:75], v[112:113] op_sel:[0,1,0]
	v_pk_fma_f32 v[108:109], v[10:11], v[68:69], v[108:109] op_sel_hi:[1,0,1]
	v_pk_fma_f32 v[112:113], v[10:11], v[76:77], v[112:113] op_sel_hi:[1,0,1]
	v_pk_fma_f32 v[108:109], v[12:13], v[68:69], v[108:109] op_sel:[0,1,0]
	v_pk_fma_f32 v[112:113], v[12:13], v[76:77], v[112:113] op_sel:[0,1,0]
	v_pk_fma_f32 v[108:109], v[14:15], v[70:71], v[108:109] op_sel_hi:[1,0,1]
	v_pk_fma_f32 v[112:113], v[14:15], v[78:79], v[112:113] op_sel_hi:[1,0,1]
	v_pk_fma_f32 v[108:109], v[16:17], v[70:71], v[108:109] op_sel:[0,1,0]
	v_pk_fma_f32 v[112:113], v[16:17], v[78:79], v[112:113] op_sel:[0,1,0]
	s_waitcnt lgkmcnt(6)
	v_pk_mul_f32 v[116:117], v[104:105], v[80:81] op_sel_hi:[1,0]
	v_pk_mul_f32 v[118:119], v[104:105], v[80:81] op_sel:[0,1]
	v_pk_mul_f32 v[120:121], v[104:105], v[82:83] op_sel_hi:[1,0]
	v_pk_mul_f32 v[122:123], v[104:105], v[82:83] op_sel:[0,1]
	v_add_f32_dpp v108, v108, v108 quad_perm:[1,0,3,2] row_mask:0xf bank_mask:0xf bound_ctrl:1
	v_add_f32_dpp v109, v109, v109 quad_perm:[1,0,3,2] row_mask:0xf bank_mask:0xf bound_ctrl:1
	v_add_f32_dpp v112, v112, v112 quad_perm:[1,0,3,2] row_mask:0xf bank_mask:0xf bound_ctrl:1
	v_add_f32_dpp v113, v113, v113 quad_perm:[1,0,3,2] row_mask:0xf bank_mask:0xf bound_ctrl:1
	v_pk_mul_f32 v[124:125], v[104:105], v[84:85] op_sel_hi:[1,0]
	v_pk_mul_f32 v[126:127], v[104:105], v[84:85] op_sel:[0,1]
	v_pk_mul_f32 v[128:129], v[104:105], v[86:87] op_sel_hi:[1,0]
	v_pk_mul_f32 v[130:131], v[104:105], v[86:87] op_sel:[0,1]
	v_add_f32_dpp v108, v108, v108 quad_perm:[2,3,0,1] row_mask:0xf bank_mask:0xf bound_ctrl:1
	v_add_f32_dpp v109, v109, v109 quad_perm:[2,3,0,1] row_mask:0xf bank_mask:0xf bound_ctrl:1
	v_add_f32_dpp v112, v112, v112 quad_perm:[2,3,0,1] row_mask:0xf bank_mask:0xf bound_ctrl:1
	v_add_f32_dpp v113, v113, v113 quad_perm:[2,3,0,1] row_mask:0xf bank_mask:0xf bound_ctrl:1
	v_add_f32_dpp v108, v108, v108 row_half_mirror row_mask:0xf bank_mask:0xf bound_ctrl:1
	v_add_f32_dpp v109, v109, v109 row_half_mirror row_mask:0xf bank_mask:0xf bound_ctrl:1
	v_add_f32_dpp v112, v112, v112 row_half_mirror row_mask:0xf bank_mask:0xf bound_ctrl:1
	v_add_f32_dpp v113, v113, v113 row_half_mirror row_mask:0xf bank_mask:0xf bound_ctrl:1
	s_waitcnt lgkmcnt(1)
	v_pk_fma_f32 v[116:117], v[108:109], v[88:89], v[116:117] op_sel_hi:[1,0,1] neg_lo:[1,0,0] neg_hi:[1,0,0]
	v_pk_fma_f32 v[118:119], v[108:109], v[88:89], v[118:119] op_sel:[0,1,0] neg_lo:[1,0,0] neg_hi:[1,0,0]
	v_pk_fma_f32 v[120:121], v[108:109], v[90:91], v[120:121] op_sel_hi:[1,0,1] neg_lo:[1,0,0] neg_hi:[1,0,0]
	v_pk_fma_f32 v[122:123], v[108:109], v[90:91], v[122:123] op_sel:[0,1,0] neg_lo:[1,0,0] neg_hi:[1,0,0]
	v_pk_fma_f32 v[124:125], v[108:109], v[92:93], v[124:125] op_sel_hi:[1,0,1] neg_lo:[1,0,0] neg_hi:[1,0,0]
	v_pk_fma_f32 v[126:127], v[108:109], v[92:93], v[126:127] op_sel:[0,1,0] neg_lo:[1,0,0] neg_hi:[1,0,0]
	v_pk_fma_f32 v[128:129], v[108:109], v[94:95], v[128:129] op_sel_hi:[1,0,1] neg_lo:[1,0,0] neg_hi:[1,0,0]
	v_pk_fma_f32 v[130:131], v[108:109], v[94:95], v[130:131] op_sel:[0,1,0] neg_lo:[1,0,0] neg_hi:[1,0,0]
	v_pk_fma_f32 v[132:133], v[108:109], v[106:107], v[112:113] op_sel_hi:[1,0,1] neg_lo:[1,0,0] neg_hi:[1,0,0]
	v_pk_fma_f32 v[2:3], v[2:3], v[96:97], v[116:117] op_sel_hi:[1,0,1]
	v_pk_fma_f32 v[4:5], v[4:5], v[96:97], v[118:119] op_sel:[0,1,0]
	v_pk_fma_f32 v[6:7], v[6:7], v[98:99], v[120:121] op_sel_hi:[1,0,1]
	v_pk_fma_f32 v[8:9], v[8:9], v[98:99], v[122:123] op_sel:[0,1,0]
	v_pk_fma_f32 v[132:133], v[104:105], v[106:107], v[132:133] op_sel:[0,1,0]
	v_pk_fma_f32 v[10:11], v[10:11], v[100:101], v[124:125] op_sel_hi:[1,0,1]
	v_pk_fma_f32 v[12:13], v[12:13], v[100:101], v[126:127] op_sel:[0,1,0]
	v_pk_fma_f32 v[14:15], v[14:15], v[102:103], v[128:129] op_sel_hi:[1,0,1]
	v_pk_fma_f32 v[16:17], v[16:17], v[102:103], v[130:131] op_sel:[0,1,0]
	ds_write_b64 v135, v[132:133] offset:57088
	s_add_i32 s13, s13, 1
	s_cmpk_eq_i32 s13, 0x80
	s_cbranch_scc0 .Lscan_chunk
